# P1 RoPE epilogues: 32 serialized cos/sin loads per call turned into a 16-deep prefetch ring with counted waits
# speedup vs baseline: 1.0067x; 1.0067x over previous
.LBB0_197:
	s_or_b64 exec, exec, s[48:49]
	v_and_b32_e32 v154, 0x3fc0, v140
	v_lshlrev_b32_e32 v155, 5, v154
	s_and_saveexec_b64 s[6:7], s[58:59]
	s_cbranch_execz .LBB0_205
	v_lshl_add_u32 v144, v213, 7, v155
	v_ashrrev_i32_e32 v145, 31, v144
	v_lshl_add_u64 v[144:145], v[144:145], 3, s[8:9]
	v_lshlrev_b32_e32 v128, 3, v212
	v_lshl_add_u64 v[144:145], v[144:145], 0, v[128:129]
	s_and_saveexec_b64 s[48:49], s[4:5]
	s_xor_b64 s[4:5], exec, s[48:49]
	s_cbranch_execz .LBB0_203
	s_and_b64 s[48:49], s[24:25], exec
	s_cselect_b32 s48, s82, 0xfffff800
	v_add_u32_e32 v128, s48, v142
	v_ashrrev_i32_e32 v128, 6, v128
	v_lshl_add_u32 v146, v210, 2, v128
	v_ashrrev_i32_e32 v147, 31, v146
	s_mov_b64 s[48:49], -1
	s_and_b64 vcc, exec, s[22:23]
	s_cbranch_vccz .LBB0_201
	v_lshlrev_b64 v[148:149], 21, v[146:147]
	v_lshl_add_u64 v[148:149], s[30:31], 0, v[148:149]
	v_lshlrev_b32_e32 v128, 7, v154
	v_mov_b32_e32 v141, v211
	v_lshl_add_u64 v[148:149], v[148:149], 0, v[128:129]
	s_mov_b64 s[48:49], 0
	v_ashrrev_i32_e32 v128, 3, v141
	v_and_b32_e32 v143, -4, v128
	v_lshrrev_b32_e32 v151, 3, v141
	v_lshlrev_b32_e32 v150, 7, v143
	v_bfi_b32 v153, 3, v151, v128
	v_lshl_add_u32 v158, v153, 4, v150
	v_lshlrev_b32_e32 v150, 1, v141
	v_bfe_u32 v152, v141, 3, 2
	v_and_b32_e32 v163, 14, v150
	v_or_b32_e32 v150, 1, v143
	v_lshlrev_b32_e32 v150, 7, v150
	v_bitop3_b32 v153, v143, v152, 1 bitop3:0x36
	v_lshl_add_u32 v160, v153, 4, v150
	v_or_b32_e32 v150, 2, v143
	v_lshlrev_b32_e32 v150, 7, v150
	v_bitop3_b32 v143, v143, v152, 2 bitop3:0x36
	v_lshl_add_u32 v162, v143, 4, v150
	v_or_b32_e32 v143, 3, v128
	v_lshlrev_b32_e32 v143, 7, v143
	v_bitop3_b32 v150, v151, v128, 3 bitop3:0x4e
	v_lshl_add_u32 v166, v150, 4, v143
	s_mov_b32 s101, 0
	s_mov_b32 s100, 0x1000
	v_lshl_add_u64 v[246:247], v[144:145], 0, s[100:101]
	s_mov_b32 s100, 0x2000
	v_lshl_add_u64 v[250:251], v[144:145], 0, s[100:101]
	s_mov_b32 s100, 0x3000
	v_lshl_add_u64 v[252:253], v[144:145], 0, s[100:101]
	global_load_dwordx2 v[212:213], v[144:145], off
	global_load_dwordx2 v[214:215], v[144:145], off offset:256
	global_load_dwordx2 v[216:217], v[144:145], off offset:512
	global_load_dwordx2 v[218:219], v[144:145], off offset:768
	global_load_dwordx2 v[220:221], v[144:145], off offset:2048
	global_load_dwordx2 v[222:223], v[144:145], off offset:2304
	global_load_dwordx2 v[224:225], v[144:145], off offset:2560
	global_load_dwordx2 v[226:227], v[144:145], off offset:2816
	global_load_dwordx2 v[228:229], v[246:247], off
	global_load_dwordx2 v[230:231], v[246:247], off offset:256
	global_load_dwordx2 v[232:233], v[246:247], off offset:512
	global_load_dwordx2 v[234:235], v[246:247], off offset:768
	global_load_dwordx2 v[236:237], v[246:247], off offset:2048
	global_load_dwordx2 v[238:239], v[246:247], off offset:2304
	global_load_dwordx2 v[240:241], v[246:247], off offset:2560
	global_load_dwordx2 v[244:245], v[246:247], off offset:2816
	v_lshlrev_b32_e32 v128, 6, v128
	s_waitcnt vmcnt(15)
	v_mov_b64_e32 v[150:151], v[212:213]
	global_load_dwordx2 v[212:213], v[250:251], off
	v_pk_mul_f32 v[152:153], v[96:97], v[150:151] op_sel:[0,1] op_sel_hi:[0,0]
	v_pk_fma_f32 v[156:157], v[112:113], v[150:151], v[152:153] neg_lo:[0,0,1] neg_hi:[0,0,1]
	v_pk_fma_f32 v[150:151], v[112:113], v[150:151], v[152:153] op_sel_hi:[0,1,1]
	v_cvt_pk_bf16_f32 v150, v156, v151
	v_or_b32_e32 v151, v158, v163
	v_add_u32_e32 v143, v192, v151
	v_xad_u32 v156, v151, 64, v192
	ds_write_b16 v143, v150
	ds_write_b16_d16_hi v156, v150
	s_waitcnt vmcnt(15)
	v_mov_b64_e32 v[150:151], v[214:215]
	global_load_dwordx2 v[214:215], v[250:251], off offset:256
	v_pk_mul_f32 v[152:153], v[96:97], v[150:151] op_sel:[1,1] op_sel_hi:[1,0]
	s_nop 0
	v_pk_fma_f32 v[158:159], v[112:113], v[150:151], v[152:153] op_sel:[1,0,0] neg_lo:[0,0,1] neg_hi:[0,0,1]
	v_pk_fma_f32 v[150:151], v[112:113], v[150:151], v[152:153] op_sel:[1,0,0]
	s_nop 0
	v_cvt_pk_bf16_f32 v150, v158, v151
	v_or_b32_e32 v151, v160, v163
	v_add_u32_e32 v157, v192, v151
	v_xad_u32 v158, v151, 64, v192
	ds_write_b16 v157, v150
	ds_write_b16_d16_hi v158, v150
	s_waitcnt vmcnt(15)
	v_mov_b64_e32 v[150:151], v[216:217]
	global_load_dwordx2 v[216:217], v[250:251], off offset:512
	v_pk_mul_f32 v[152:153], v[98:99], v[150:151] op_sel:[0,1] op_sel_hi:[0,0]
	v_pk_fma_f32 v[160:161], v[114:115], v[150:151], v[152:153] neg_lo:[0,0,1] neg_hi:[0,0,1]
	v_pk_fma_f32 v[150:151], v[114:115], v[150:151], v[152:153] op_sel_hi:[0,1,1]
	v_cvt_pk_bf16_f32 v150, v160, v151
	v_or_b32_e32 v151, v162, v163
	v_add_u32_e32 v159, v192, v151
	v_xad_u32 v160, v151, 64, v192
	ds_write_b16 v159, v150
	ds_write_b16_d16_hi v160, v150
	v_mov_b32_e32 v152, v99
	v_mov_b32_e32 v162, v115
	s_waitcnt vmcnt(15)
	v_mov_b64_e32 v[150:151], v[218:219]
	global_load_dwordx2 v[218:219], v[250:251], off offset:768
	v_pk_mul_f32 v[152:153], v[152:153], v[150:151] op_sel:[0,1] op_sel_hi:[0,0]
	v_pk_fma_f32 v[164:165], v[162:163], v[150:151], v[152:153] op_sel_hi:[0,1,1] neg_lo:[0,0,1] neg_hi:[0,0,1]
	v_pk_fma_f32 v[150:151], v[162:163], v[150:151], v[152:153] op_sel_hi:[0,1,1]
	v_cvt_pk_bf16_f32 v150, v164, v151
	v_or_b32_e32 v151, v166, v163
	v_add_u32_e32 v161, v192, v151
	v_xad_u32 v162, v151, 64, v192
	ds_write_b16 v161, v150
	ds_write_b16_d16_hi v162, v150
	s_waitcnt vmcnt(15)
	v_mov_b64_e32 v[150:151], v[220:221]
	global_load_dwordx2 v[220:221], v[250:251], off offset:2048
	v_pk_mul_f32 v[152:153], v[100:101], v[150:151] op_sel:[0,1] op_sel_hi:[0,0]
	v_pk_fma_f32 v[164:165], v[116:117], v[150:151], v[152:153] neg_lo:[0,0,1] neg_hi:[0,0,1]
	v_pk_fma_f32 v[150:151], v[116:117], v[150:151], v[152:153] op_sel_hi:[0,1,1]
	v_cvt_pk_bf16_f32 v150, v164, v151
	ds_write_b16 v143, v150 offset:1024
	ds_write_b16_d16_hi v156, v150 offset:1024
	v_mov_b32_e32 v152, v101
	v_mov_b32_e32 v164, v117
	s_waitcnt vmcnt(15)
	v_mov_b64_e32 v[150:151], v[222:223]
	global_load_dwordx2 v[222:223], v[250:251], off offset:2304
	v_pk_mul_f32 v[152:153], v[152:153], v[150:151] op_sel:[0,1] op_sel_hi:[0,0]
	v_pk_fma_f32 v[166:167], v[164:165], v[150:151], v[152:153] op_sel_hi:[0,1,1] neg_lo:[0,0,1] neg_hi:[0,0,1]
	v_pk_fma_f32 v[150:151], v[164:165], v[150:151], v[152:153] op_sel_hi:[0,1,1]
	v_cvt_pk_bf16_f32 v150, v166, v151
	ds_write_b16 v157, v150 offset:1024
	ds_write_b16_d16_hi v158, v150 offset:1024
	s_waitcnt vmcnt(15)
	v_mov_b64_e32 v[150:151], v[224:225]
	global_load_dwordx2 v[224:225], v[250:251], off offset:2560
	v_pk_mul_f32 v[152:153], v[102:103], v[150:151] op_sel:[0,1] op_sel_hi:[0,0]
	v_pk_fma_f32 v[164:165], v[118:119], v[150:151], v[152:153] neg_lo:[0,0,1] neg_hi:[0,0,1]
	v_pk_fma_f32 v[150:151], v[118:119], v[150:151], v[152:153] op_sel_hi:[0,1,1]
	v_cvt_pk_bf16_f32 v150, v164, v151
	ds_write_b16 v159, v150 offset:1024
	ds_write_b16_d16_hi v160, v150 offset:1024
	v_mov_b32_e32 v152, v103
	v_mov_b32_e32 v164, v119
	s_waitcnt vmcnt(15)
	v_mov_b64_e32 v[150:151], v[226:227]
	global_load_dwordx2 v[226:227], v[250:251], off offset:2816
	v_pk_mul_f32 v[152:153], v[152:153], v[150:151] op_sel:[0,1] op_sel_hi:[0,0]
	v_pk_fma_f32 v[166:167], v[164:165], v[150:151], v[152:153] op_sel_hi:[0,1,1] neg_lo:[0,0,1] neg_hi:[0,0,1]
	v_pk_fma_f32 v[150:151], v[164:165], v[150:151], v[152:153] op_sel_hi:[0,1,1]
	v_add_co_u32_e32 v152, vcc, s83, v144
	v_cvt_pk_bf16_f32 v150, v166, v151
	s_nop 0
	v_addc_co_u32_e32 v153, vcc, 0, v145, vcc
	ds_write_b16 v161, v150 offset:1024
	ds_write_b16_d16_hi v162, v150 offset:1024
	v_add_co_u32_e32 v150, vcc, s51, v144
	s_nop 1
	v_addc_co_u32_e32 v151, vcc, 0, v145, vcc
	s_waitcnt vmcnt(15)
	v_mov_b64_e32 v[164:165], v[228:229]
	global_load_dwordx2 v[228:229], v[252:253], off
	v_pk_mul_f32 v[166:167], v[104:105], v[164:165] op_sel:[0,1] op_sel_hi:[0,0]
	v_pk_fma_f32 v[168:169], v[120:121], v[164:165], v[166:167] neg_lo:[0,0,1] neg_hi:[0,0,1]
	v_pk_fma_f32 v[164:165], v[120:121], v[164:165], v[166:167] op_sel_hi:[0,1,1]
	v_cvt_pk_bf16_f32 v163, v168, v165
	ds_write_b16 v143, v163 offset:2048
	ds_write_b16_d16_hi v156, v163 offset:2048
	v_mov_b32_e32 v166, v105
	v_mov_b32_e32 v168, v121
	s_waitcnt vmcnt(15)
	v_mov_b64_e32 v[164:165], v[230:231]
	global_load_dwordx2 v[230:231], v[252:253], off offset:256
	v_pk_mul_f32 v[166:167], v[166:167], v[164:165] op_sel:[0,1] op_sel_hi:[0,0]
	v_pk_fma_f32 v[170:171], v[168:169], v[164:165], v[166:167] op_sel_hi:[0,1,1] neg_lo:[0,0,1] neg_hi:[0,0,1]
	v_pk_fma_f32 v[164:165], v[168:169], v[164:165], v[166:167] op_sel_hi:[0,1,1]
	v_cvt_pk_bf16_f32 v163, v170, v165
	ds_write_b16 v157, v163 offset:2048
	ds_write_b16_d16_hi v158, v163 offset:2048
	s_waitcnt vmcnt(15)
	v_mov_b64_e32 v[164:165], v[232:233]
	global_load_dwordx2 v[232:233], v[252:253], off offset:512
	v_pk_mul_f32 v[166:167], v[106:107], v[164:165] op_sel:[0,1] op_sel_hi:[0,0]
	v_pk_fma_f32 v[168:169], v[122:123], v[164:165], v[166:167] neg_lo:[0,0,1] neg_hi:[0,0,1]
	v_pk_fma_f32 v[164:165], v[122:123], v[164:165], v[166:167] op_sel_hi:[0,1,1]
	v_cvt_pk_bf16_f32 v163, v168, v165
	ds_write_b16 v159, v163 offset:2048
	ds_write_b16_d16_hi v160, v163 offset:2048
	v_mov_b32_e32 v166, v107
	v_mov_b32_e32 v168, v123
	s_waitcnt vmcnt(15)
	v_mov_b64_e32 v[164:165], v[234:235]
	global_load_dwordx2 v[234:235], v[252:253], off offset:768
	v_pk_mul_f32 v[166:167], v[166:167], v[164:165] op_sel:[0,1] op_sel_hi:[0,0]
	v_pk_fma_f32 v[170:171], v[168:169], v[164:165], v[166:167] op_sel_hi:[0,1,1] neg_lo:[0,0,1] neg_hi:[0,0,1]
	v_pk_fma_f32 v[164:165], v[168:169], v[164:165], v[166:167] op_sel_hi:[0,1,1]
	v_cvt_pk_bf16_f32 v163, v170, v165
	ds_write_b16 v161, v163 offset:2048
	ds_write_b16_d16_hi v162, v163 offset:2048
	s_waitcnt vmcnt(15)
	v_mov_b64_e32 v[164:165], v[236:237]
	global_load_dwordx2 v[236:237], v[252:253], off offset:2048
	v_pk_mul_f32 v[166:167], v[108:109], v[164:165] op_sel:[0,1] op_sel_hi:[0,0]
	v_pk_fma_f32 v[168:169], v[124:125], v[164:165], v[166:167] neg_lo:[0,0,1] neg_hi:[0,0,1]
	v_pk_fma_f32 v[164:165], v[124:125], v[164:165], v[166:167] op_sel_hi:[0,1,1]
	v_cvt_pk_bf16_f32 v163, v168, v165
	ds_write_b16 v143, v163 offset:3072
	ds_write_b16_d16_hi v156, v163 offset:3072
	v_mov_b32_e32 v166, v109
	v_mov_b32_e32 v168, v125
	s_waitcnt vmcnt(15)
	v_mov_b64_e32 v[164:165], v[238:239]
	global_load_dwordx2 v[238:239], v[252:253], off offset:2304
	v_pk_mul_f32 v[166:167], v[166:167], v[164:165] op_sel:[0,1] op_sel_hi:[0,0]
	v_pk_fma_f32 v[170:171], v[168:169], v[164:165], v[166:167] op_sel_hi:[0,1,1] neg_lo:[0,0,1] neg_hi:[0,0,1]
	v_pk_fma_f32 v[164:165], v[168:169], v[164:165], v[166:167] op_sel_hi:[0,1,1]
	v_cvt_pk_bf16_f32 v163, v170, v165
	ds_write_b16 v157, v163 offset:3072
	ds_write_b16_d16_hi v158, v163 offset:3072
	s_waitcnt vmcnt(15)
	v_mov_b64_e32 v[164:165], v[240:241]
	global_load_dwordx2 v[240:241], v[252:253], off offset:2560
	v_pk_mul_f32 v[166:167], v[110:111], v[164:165] op_sel:[0,1] op_sel_hi:[0,0]
	v_pk_fma_f32 v[168:169], v[126:127], v[164:165], v[166:167] neg_lo:[0,0,1] neg_hi:[0,0,1]
	v_pk_fma_f32 v[164:165], v[126:127], v[164:165], v[166:167] op_sel_hi:[0,1,1]
	v_cvt_pk_bf16_f32 v163, v168, v165
	ds_write_b16 v159, v163 offset:3072
	ds_write_b16_d16_hi v160, v163 offset:3072
	v_mov_b32_e32 v164, v111
	v_mov_b32_e32 v166, v127
	s_waitcnt vmcnt(15)
	v_mov_b64_e32 v[152:153], v[244:245]
	global_load_dwordx2 v[244:245], v[252:253], off offset:2816
	v_pk_mul_f32 v[164:165], v[164:165], v[152:153] op_sel:[0,1] op_sel_hi:[0,0]
	v_pk_fma_f32 v[168:169], v[166:167], v[152:153], v[164:165] op_sel_hi:[0,1,1] neg_lo:[0,0,1] neg_hi:[0,0,1]
	v_pk_fma_f32 v[152:153], v[166:167], v[152:153], v[164:165] op_sel_hi:[0,1,1]
	v_cvt_pk_bf16_f32 v152, v168, v153
	ds_write_b16 v161, v152 offset:3072
	ds_write_b16_d16_hi v162, v152 offset:3072
	s_waitcnt vmcnt(15)
	v_mov_b64_e32 v[152:153], v[212:213]
	v_pk_mul_f32 v[164:165], v[64:65], v[152:153] op_sel:[0,1] op_sel_hi:[0,0]
	v_pk_fma_f32 v[166:167], v[80:81], v[152:153], v[164:165] neg_lo:[0,0,1] neg_hi:[0,0,1]
	v_pk_fma_f32 v[152:153], v[80:81], v[152:153], v[164:165] op_sel_hi:[0,1,1]
	v_cvt_pk_bf16_f32 v152, v166, v153
	ds_write_b16 v143, v152 offset:4096
	ds_write_b16_d16_hi v156, v152 offset:4096
	s_waitcnt vmcnt(14)
	v_mov_b64_e32 v[152:153], v[214:215]
	v_pk_mul_f32 v[164:165], v[64:65], v[152:153] op_sel:[1,1] op_sel_hi:[1,0]
	s_nop 0
	v_pk_fma_f32 v[166:167], v[80:81], v[152:153], v[164:165] op_sel:[1,0,0] neg_lo:[0,0,1] neg_hi:[0,0,1]
	v_pk_fma_f32 v[152:153], v[80:81], v[152:153], v[164:165] op_sel:[1,0,0]
	s_nop 0
	v_cvt_pk_bf16_f32 v152, v166, v153
	ds_write_b16 v157, v152 offset:4096
	ds_write_b16_d16_hi v158, v152 offset:4096
	s_waitcnt vmcnt(13)
	v_mov_b64_e32 v[152:153], v[216:217]
	v_pk_mul_f32 v[164:165], v[66:67], v[152:153] op_sel:[0,1] op_sel_hi:[0,0]
	v_pk_fma_f32 v[166:167], v[82:83], v[152:153], v[164:165] neg_lo:[0,0,1] neg_hi:[0,0,1]
	v_pk_fma_f32 v[152:153], v[82:83], v[152:153], v[164:165] op_sel_hi:[0,1,1]
	v_cvt_pk_bf16_f32 v152, v166, v153
	ds_write_b16 v159, v152 offset:4096
	ds_write_b16_d16_hi v160, v152 offset:4096
	v_mov_b32_e32 v164, v67
	v_mov_b32_e32 v166, v83
	s_waitcnt vmcnt(12)
	v_mov_b64_e32 v[152:153], v[218:219]
	v_pk_mul_f32 v[164:165], v[164:165], v[152:153] op_sel:[0,1] op_sel_hi:[0,0]
	v_pk_fma_f32 v[168:169], v[166:167], v[152:153], v[164:165] op_sel_hi:[0,1,1] neg_lo:[0,0,1] neg_hi:[0,0,1]
	v_pk_fma_f32 v[152:153], v[166:167], v[152:153], v[164:165] op_sel_hi:[0,1,1]
	v_cvt_pk_bf16_f32 v152, v168, v153
	ds_write_b16 v161, v152 offset:4096
	ds_write_b16_d16_hi v162, v152 offset:4096
	s_waitcnt vmcnt(11)
	v_mov_b64_e32 v[152:153], v[220:221]
	v_pk_mul_f32 v[164:165], v[68:69], v[152:153] op_sel:[0,1] op_sel_hi:[0,0]
	v_pk_fma_f32 v[166:167], v[84:85], v[152:153], v[164:165] neg_lo:[0,0,1] neg_hi:[0,0,1]
	v_pk_fma_f32 v[152:153], v[84:85], v[152:153], v[164:165] op_sel_hi:[0,1,1]
	v_cvt_pk_bf16_f32 v152, v166, v153
	ds_write_b16 v143, v152 offset:5120
	ds_write_b16_d16_hi v156, v152 offset:5120
	v_mov_b32_e32 v164, v69
	v_mov_b32_e32 v166, v85
	s_waitcnt vmcnt(10)
	v_mov_b64_e32 v[152:153], v[222:223]
	v_pk_mul_f32 v[164:165], v[164:165], v[152:153] op_sel:[0,1] op_sel_hi:[0,0]
	v_pk_fma_f32 v[168:169], v[166:167], v[152:153], v[164:165] op_sel_hi:[0,1,1] neg_lo:[0,0,1] neg_hi:[0,0,1]
	v_pk_fma_f32 v[152:153], v[166:167], v[152:153], v[164:165] op_sel_hi:[0,1,1]
	v_cvt_pk_bf16_f32 v152, v168, v153
	ds_write_b16 v157, v152 offset:5120
	ds_write_b16_d16_hi v158, v152 offset:5120
	s_waitcnt vmcnt(9)
	v_mov_b64_e32 v[152:153], v[224:225]
	v_pk_mul_f32 v[164:165], v[70:71], v[152:153] op_sel:[0,1] op_sel_hi:[0,0]
	v_pk_fma_f32 v[166:167], v[86:87], v[152:153], v[164:165] neg_lo:[0,0,1] neg_hi:[0,0,1]
	v_pk_fma_f32 v[152:153], v[86:87], v[152:153], v[164:165] op_sel_hi:[0,1,1]
	v_cvt_pk_bf16_f32 v152, v166, v153
	ds_write_b16 v159, v152 offset:5120
	ds_write_b16_d16_hi v160, v152 offset:5120
	v_mov_b32_e32 v152, v71
	v_mov_b32_e32 v164, v87
	s_waitcnt vmcnt(8)
	v_mov_b64_e32 v[150:151], v[226:227]
	v_pk_mul_f32 v[152:153], v[152:153], v[150:151] op_sel:[0,1] op_sel_hi:[0,0]
	v_pk_fma_f32 v[166:167], v[164:165], v[150:151], v[152:153] op_sel_hi:[0,1,1] neg_lo:[0,0,1] neg_hi:[0,0,1]
	v_pk_fma_f32 v[150:151], v[164:165], v[150:151], v[152:153] op_sel_hi:[0,1,1]
	v_cvt_pk_bf16_f32 v150, v166, v151
	ds_write_b16 v161, v150 offset:5120
	ds_write_b16_d16_hi v162, v150 offset:5120
	v_add_co_u32_e32 v150, vcc, s90, v144
	s_nop 1
	v_addc_co_u32_e32 v151, vcc, 0, v145, vcc
	s_waitcnt vmcnt(7)
	v_mov_b64_e32 v[152:153], v[228:229]
	v_pk_mul_f32 v[164:165], v[72:73], v[152:153] op_sel:[0,1] op_sel_hi:[0,0]
	v_pk_fma_f32 v[166:167], v[88:89], v[152:153], v[164:165] neg_lo:[0,0,1] neg_hi:[0,0,1]
	v_pk_fma_f32 v[152:153], v[88:89], v[152:153], v[164:165] op_sel_hi:[0,1,1]
	v_cvt_pk_bf16_f32 v152, v166, v153
	ds_write_b16 v143, v152 offset:6144
	ds_write_b16_d16_hi v156, v152 offset:6144
	v_mov_b32_e32 v164, v73
	v_mov_b32_e32 v166, v89
	s_waitcnt vmcnt(6)
	v_mov_b64_e32 v[152:153], v[230:231]
	v_pk_mul_f32 v[164:165], v[164:165], v[152:153] op_sel:[0,1] op_sel_hi:[0,0]
	v_pk_fma_f32 v[168:169], v[166:167], v[152:153], v[164:165] op_sel_hi:[0,1,1] neg_lo:[0,0,1] neg_hi:[0,0,1]
	v_pk_fma_f32 v[152:153], v[166:167], v[152:153], v[164:165] op_sel_hi:[0,1,1]
	v_cvt_pk_bf16_f32 v152, v168, v153
	ds_write_b16 v157, v152 offset:6144
	ds_write_b16_d16_hi v158, v152 offset:6144
	s_waitcnt vmcnt(5)
	v_mov_b64_e32 v[152:153], v[232:233]
	v_pk_mul_f32 v[164:165], v[74:75], v[152:153] op_sel:[0,1] op_sel_hi:[0,0]
	v_pk_fma_f32 v[166:167], v[90:91], v[152:153], v[164:165] neg_lo:[0,0,1] neg_hi:[0,0,1]
	v_pk_fma_f32 v[152:153], v[90:91], v[152:153], v[164:165] op_sel_hi:[0,1,1]
	v_cvt_pk_bf16_f32 v152, v166, v153
	ds_write_b16 v159, v152 offset:6144
	ds_write_b16_d16_hi v160, v152 offset:6144
	v_mov_b32_e32 v164, v75
	v_mov_b32_e32 v166, v91
	s_waitcnt vmcnt(4)
	v_mov_b64_e32 v[152:153], v[234:235]
	v_pk_mul_f32 v[164:165], v[164:165], v[152:153] op_sel:[0,1] op_sel_hi:[0,0]
	v_pk_fma_f32 v[168:169], v[166:167], v[152:153], v[164:165] op_sel_hi:[0,1,1] neg_lo:[0,0,1] neg_hi:[0,0,1]
	v_pk_fma_f32 v[152:153], v[166:167], v[152:153], v[164:165] op_sel_hi:[0,1,1]
	v_cvt_pk_bf16_f32 v152, v168, v153
	ds_write_b16 v161, v152 offset:6144
	ds_write_b16_d16_hi v162, v152 offset:6144
	s_waitcnt vmcnt(3)
	v_mov_b64_e32 v[152:153], v[236:237]
	v_pk_mul_f32 v[164:165], v[76:77], v[152:153] op_sel:[0,1] op_sel_hi:[0,0]
	v_pk_fma_f32 v[166:167], v[92:93], v[152:153], v[164:165] neg_lo:[0,0,1] neg_hi:[0,0,1]
	v_pk_fma_f32 v[152:153], v[92:93], v[152:153], v[164:165] op_sel_hi:[0,1,1]
	v_cvt_pk_bf16_f32 v152, v166, v153
	ds_write_b16 v143, v152 offset:7168
	ds_write_b16_d16_hi v156, v152 offset:7168
	v_mov_b32_e32 v156, v77
	s_waitcnt vmcnt(2)
	v_mov_b64_e32 v[152:153], v[238:239]
	v_pk_mul_f32 v[164:165], v[156:157], v[152:153] op_sel:[0,1] op_sel_hi:[0,0]
	v_mov_b32_e32 v156, v93
	v_pk_fma_f32 v[166:167], v[156:157], v[152:153], v[164:165] op_sel_hi:[0,1,1] neg_lo:[0,0,1] neg_hi:[0,0,1]
	v_pk_fma_f32 v[152:153], v[156:157], v[152:153], v[164:165] op_sel_hi:[0,1,1]
	v_cvt_pk_bf16_f32 v143, v166, v153
	ds_write_b16 v157, v143 offset:7168
	ds_write_b16_d16_hi v158, v143 offset:7168
	s_waitcnt vmcnt(1)
	v_mov_b64_e32 v[152:153], v[240:241]
	v_pk_mul_f32 v[156:157], v[78:79], v[152:153] op_sel:[0,1] op_sel_hi:[0,0]
	v_pk_fma_f32 v[164:165], v[94:95], v[152:153], v[156:157] neg_lo:[0,0,1] neg_hi:[0,0,1]
	v_pk_fma_f32 v[152:153], v[94:95], v[152:153], v[156:157] op_sel_hi:[0,1,1]
	v_cvt_pk_bf16_f32 v143, v164, v153
	ds_write_b16 v159, v143 offset:7168
	ds_write_b16_d16_hi v160, v143 offset:7168
	v_mov_b32_e32 v152, v79
	v_mov_b32_e32 v156, v95
	s_waitcnt vmcnt(0)
	v_mov_b64_e32 v[150:151], v[244:245]
	v_pk_mul_f32 v[152:153], v[152:153], v[150:151] op_sel:[0,1] op_sel_hi:[0,0]
	v_pk_fma_f32 v[158:159], v[156:157], v[150:151], v[152:153] op_sel_hi:[0,1,1] neg_lo:[0,0,1] neg_hi:[0,0,1]
	v_pk_fma_f32 v[150:151], v[156:157], v[150:151], v[152:153] op_sel_hi:[0,1,1]
	v_cvt_pk_bf16_f32 v143, v158, v151
	ds_write_b16 v161, v143 offset:7168
	ds_write_b16_d16_hi v162, v143 offset:7168
	v_lshl_add_u32 v143, v141, 7, v192
	v_and_b32_e32 v158, 15, v141
	v_lshlrev_b32_e32 v141, 4, v141
	v_and_b32_e32 v141, 0x70, v141
	v_add_u32_e32 v150, v143, v141
	ds_read_b128 v[150:153], v150
	v_and_or_b32 v156, v128, s91, v158
	v_lshlrev_b32_e32 v156, 3, v156
	v_ashrrev_i32_e32 v157, 31, v156
	v_lshl_add_u64 v[156:157], v[156:157], 1, v[148:149]
	s_waitcnt lgkmcnt(0)
	global_store_dwordx4 v[156:157], v[150:153], off
	v_or_b32_e32 v128, v128, v158
	v_lshlrev_b32_e32 v128, 3, v128
	v_xad_u32 v150, v141, 16, v143
	ds_read_b128 v[150:153], v150
	s_waitcnt lgkmcnt(0)
	global_store_dwordx4 v[156:157], v[150:153], off offset:256
	s_nop 1
	v_xad_u32 v150, v141, 32, v143
	ds_read_b128 v[150:153], v150
	s_waitcnt lgkmcnt(0)
	global_store_dwordx4 v[156:157], v[150:153], off offset:512
	s_nop 1
	v_xad_u32 v150, v141, 48, v143
	ds_read_b128 v[150:153], v150
	s_waitcnt lgkmcnt(0)
	global_store_dwordx4 v[156:157], v[150:153], off offset:768
	s_nop 1
	v_xad_u32 v150, v141, 64, v143
	ds_read_b128 v[150:153], v150
	v_or_b32_e32 v156, 0x200, v128
	v_ashrrev_i32_e32 v157, 31, v156
	v_lshl_add_u64 v[156:157], v[156:157], 1, v[148:149]
	s_waitcnt lgkmcnt(0)
	global_store_dwordx4 v[156:157], v[150:153], off
	v_or_b32_e32 v156, 0x280, v128
	s_nop 0
	v_xad_u32 v150, v141, s76, v143
	ds_read_b128 v[150:153], v150
	v_ashrrev_i32_e32 v157, 31, v156
	v_lshl_add_u64 v[156:157], v[156:157], 1, v[148:149]
	s_waitcnt lgkmcnt(0)
	global_store_dwordx4 v[156:157], v[150:153], off
	s_nop 1
	v_xad_u32 v150, v141, s77, v143
	ds_read_b128 v[150:153], v150
	v_or_b32_e32 v156, 0x300, v128
	v_ashrrev_i32_e32 v157, 31, v156
	v_lshl_add_u64 v[156:157], v[156:157], 1, v[148:149]
	v_xad_u32 v141, v141, s21, v143
	s_waitcnt lgkmcnt(0)
	global_store_dwordx4 v[156:157], v[150:153], off
	ds_read_b128 v[150:153], v141
	v_or_b32_e32 v156, 0x380, v128
	v_ashrrev_i32_e32 v157, 31, v156
	v_lshl_add_u64 v[148:149], v[156:157], 1, v[148:149]
	s_waitcnt lgkmcnt(0)
	global_store_dwordx4 v[148:149], v[150:153], off
.LBB0_201:
	s_andn2_b64 vcc, exec, s[48:49]
	s_cbranch_vccnz .LBB0_203
	v_lshlrev_b64 v[146:147], 20, v[146:147]
	v_lshlrev_b32_e32 v128, 6, v154
	v_lshl_add_u64 v[146:147], s[46:47], 0, v[146:147]
	v_lshl_add_u64 v[146:147], v[146:147], 0, v[128:129]
	s_nop 0
	v_ashrrev_i32_e32 v128, 3, v211
	v_and_b32_e32 v141, -4, v128
	v_lshrrev_b32_e32 v148, 3, v211
	v_lshlrev_b32_e32 v143, 7, v141
	v_bfi_b32 v150, 3, v148, v128
	v_lshl_add_u32 v143, v150, 4, v143
	v_lshlrev_b32_e32 v150, 1, v211
	v_bfe_u32 v149, v211, 3, 2
	v_and_b32_e32 v156, 14, v150
	v_or_b32_e32 v150, 1, v141
	v_lshlrev_b32_e32 v150, 7, v150
	v_bitop3_b32 v151, v141, v149, 1 bitop3:0x36
	v_lshl_add_u32 v157, v151, 4, v150
	v_or_b32_e32 v150, 2, v141
	v_lshlrev_b32_e32 v150, 7, v150
	v_bitop3_b32 v141, v141, v149, 2 bitop3:0x36
	v_lshl_add_u32 v158, v141, 4, v150
	v_or_b32_e32 v141, 3, v128
	v_bitop3_b32 v128, v148, v128, 3 bitop3:0x4e
	s_mov_b32 s101, 0
	s_mov_b32 s100, 0x1000
	v_lshl_add_u64 v[246:247], v[144:145], 0, s[100:101]
	s_mov_b32 s100, 0x2000
	v_lshl_add_u64 v[250:251], v[144:145], 0, s[100:101]
	s_mov_b32 s100, 0x3000
	v_lshl_add_u64 v[252:253], v[144:145], 0, s[100:101]
	global_load_dwordx2 v[212:213], v[144:145], off
	global_load_dwordx2 v[214:215], v[144:145], off offset:256
	global_load_dwordx2 v[216:217], v[144:145], off offset:512
	global_load_dwordx2 v[218:219], v[144:145], off offset:768
	global_load_dwordx2 v[220:221], v[144:145], off offset:2048
	global_load_dwordx2 v[222:223], v[144:145], off offset:2304
	global_load_dwordx2 v[224:225], v[144:145], off offset:2560
	global_load_dwordx2 v[226:227], v[144:145], off offset:2816
	global_load_dwordx2 v[228:229], v[246:247], off
	global_load_dwordx2 v[230:231], v[246:247], off offset:256
	global_load_dwordx2 v[232:233], v[246:247], off offset:512
	global_load_dwordx2 v[234:235], v[246:247], off offset:768
	global_load_dwordx2 v[236:237], v[246:247], off offset:2048
	global_load_dwordx2 v[238:239], v[246:247], off offset:2304
	global_load_dwordx2 v[240:241], v[246:247], off offset:2560
	global_load_dwordx2 v[244:245], v[246:247], off offset:2816
	v_lshlrev_b32_e32 v141, 7, v141
	v_lshl_add_u32 v159, v128, 4, v141
	v_or_b32_e32 v141, v143, v156
	v_add_u32_e32 v128, v192, v141
	v_xad_u32 v141, v141, 64, v192
	s_waitcnt vmcnt(15)
	v_mov_b64_e32 v[148:149], v[212:213]
	global_load_dwordx2 v[212:213], v[250:251], off
	v_pk_mul_f32 v[150:151], v[96:97], v[148:149] op_sel:[0,1] op_sel_hi:[0,0]
	v_pk_fma_f32 v[152:153], v[112:113], v[148:149], v[150:151] neg_lo:[0,0,1] neg_hi:[0,0,1]
	v_pk_fma_f32 v[148:149], v[112:113], v[148:149], v[150:151] op_sel_hi:[0,1,1]
	v_cvt_pk_bf16_f32 v148, v152, v149
	ds_write_b16 v128, v148
	ds_write_b16_d16_hi v141, v148
	s_waitcnt vmcnt(15)
	v_mov_b64_e32 v[148:149], v[214:215]
	global_load_dwordx2 v[214:215], v[250:251], off offset:256
	v_pk_mul_f32 v[96:97], v[96:97], v[148:149] op_sel:[1,1] op_sel_hi:[1,0]
	s_nop 0
	v_pk_fma_f32 v[150:151], v[112:113], v[148:149], v[96:97] op_sel:[1,0,0] neg_lo:[0,0,1] neg_hi:[0,0,1]
	v_pk_fma_f32 v[96:97], v[112:113], v[148:149], v[96:97] op_sel:[1,0,0]
	s_nop 0
	v_cvt_pk_bf16_f32 v96, v150, v97
	v_or_b32_e32 v97, v157, v156
	v_add_u32_e32 v112, v192, v97
	v_xad_u32 v113, v97, 64, v192
	ds_write_b16 v112, v96
	ds_write_b16_d16_hi v113, v96
	s_waitcnt vmcnt(15)
	v_mov_b64_e32 v[96:97], v[216:217]
	global_load_dwordx2 v[216:217], v[250:251], off offset:512
	v_pk_mul_f32 v[148:149], v[98:99], v[96:97] op_sel:[0,1] op_sel_hi:[0,0]
	v_pk_fma_f32 v[150:151], v[114:115], v[96:97], v[148:149] neg_lo:[0,0,1] neg_hi:[0,0,1]
	v_pk_fma_f32 v[96:97], v[114:115], v[96:97], v[148:149] op_sel_hi:[0,1,1]
	v_cvt_pk_bf16_f32 v96, v150, v97
	v_or_b32_e32 v97, v158, v156
	v_add_u32_e32 v114, v192, v97
	v_xad_u32 v143, v97, 64, v192
	ds_write_b16 v114, v96
	ds_write_b16_d16_hi v143, v96
	v_mov_b32_e32 v98, v99
	v_mov_b32_e32 v148, v115
	s_waitcnt vmcnt(15)
	v_mov_b64_e32 v[96:97], v[218:219]
	global_load_dwordx2 v[218:219], v[250:251], off offset:768
	v_pk_mul_f32 v[98:99], v[98:99], v[96:97] op_sel:[0,1] op_sel_hi:[0,0]
	v_pk_fma_f32 v[150:151], v[148:149], v[96:97], v[98:99] op_sel_hi:[0,1,1] neg_lo:[0,0,1] neg_hi:[0,0,1]
	v_pk_fma_f32 v[96:97], v[148:149], v[96:97], v[98:99] op_sel_hi:[0,1,1]
	v_cvt_pk_bf16_f32 v96, v150, v97
	v_or_b32_e32 v97, v159, v156
	v_add_u32_e32 v115, v192, v97
	v_xad_u32 v148, v97, 64, v192
	ds_write_b16 v115, v96
	ds_write_b16_d16_hi v148, v96
	s_waitcnt vmcnt(15)
	v_mov_b64_e32 v[96:97], v[220:221]
	global_load_dwordx2 v[220:221], v[250:251], off offset:2048
	v_pk_mul_f32 v[98:99], v[100:101], v[96:97] op_sel:[0,1] op_sel_hi:[0,0]
	v_pk_fma_f32 v[150:151], v[116:117], v[96:97], v[98:99] neg_lo:[0,0,1] neg_hi:[0,0,1]
	v_pk_fma_f32 v[96:97], v[116:117], v[96:97], v[98:99] op_sel_hi:[0,1,1]
	v_cvt_pk_bf16_f32 v96, v150, v97
	ds_write_b16 v128, v96 offset:1024
	ds_write_b16_d16_hi v141, v96 offset:1024
	v_mov_b32_e32 v98, v101
	v_mov_b32_e32 v100, v117
	s_waitcnt vmcnt(15)
	v_mov_b64_e32 v[96:97], v[222:223]
	global_load_dwordx2 v[222:223], v[250:251], off offset:2304
	v_pk_mul_f32 v[98:99], v[98:99], v[96:97] op_sel:[0,1] op_sel_hi:[0,0]
	v_pk_fma_f32 v[116:117], v[100:101], v[96:97], v[98:99] op_sel_hi:[0,1,1] neg_lo:[0,0,1] neg_hi:[0,0,1]
	v_pk_fma_f32 v[96:97], v[100:101], v[96:97], v[98:99] op_sel_hi:[0,1,1]
	v_cvt_pk_bf16_f32 v96, v116, v97
	ds_write_b16 v112, v96 offset:1024
	ds_write_b16_d16_hi v113, v96 offset:1024
	s_waitcnt vmcnt(15)
	v_mov_b64_e32 v[96:97], v[224:225]
	global_load_dwordx2 v[224:225], v[250:251], off offset:2560
	v_pk_mul_f32 v[98:99], v[102:103], v[96:97] op_sel:[0,1] op_sel_hi:[0,0]
	v_pk_fma_f32 v[100:101], v[118:119], v[96:97], v[98:99] neg_lo:[0,0,1] neg_hi:[0,0,1]
	v_pk_fma_f32 v[96:97], v[118:119], v[96:97], v[98:99] op_sel_hi:[0,1,1]
	v_cvt_pk_bf16_f32 v96, v100, v97
	ds_write_b16 v114, v96 offset:1024
	ds_write_b16_d16_hi v143, v96 offset:1024
	v_mov_b32_e32 v98, v103
	v_mov_b32_e32 v100, v119
	s_waitcnt vmcnt(15)
	v_mov_b64_e32 v[96:97], v[226:227]
	global_load_dwordx2 v[226:227], v[250:251], off offset:2816
	v_pk_mul_f32 v[98:99], v[98:99], v[96:97] op_sel:[0,1] op_sel_hi:[0,0]
	v_pk_fma_f32 v[102:103], v[100:101], v[96:97], v[98:99] op_sel_hi:[0,1,1] neg_lo:[0,0,1] neg_hi:[0,0,1]
	v_pk_fma_f32 v[96:97], v[100:101], v[96:97], v[98:99] op_sel_hi:[0,1,1]
	v_add_co_u32_e32 v98, vcc, s83, v144
	v_cvt_pk_bf16_f32 v96, v102, v97
	s_nop 0
	v_addc_co_u32_e32 v99, vcc, 0, v145, vcc
	ds_write_b16 v115, v96 offset:1024
	ds_write_b16_d16_hi v148, v96 offset:1024
	v_add_co_u32_e32 v96, vcc, s51, v144
	s_nop 1
	v_addc_co_u32_e32 v97, vcc, 0, v145, vcc
	s_waitcnt vmcnt(15)
	v_mov_b64_e32 v[100:101], v[228:229]
	global_load_dwordx2 v[228:229], v[252:253], off
	v_pk_mul_f32 v[102:103], v[104:105], v[100:101] op_sel:[0,1] op_sel_hi:[0,0]
	v_pk_fma_f32 v[116:117], v[120:121], v[100:101], v[102:103] neg_lo:[0,0,1] neg_hi:[0,0,1]
	v_pk_fma_f32 v[100:101], v[120:121], v[100:101], v[102:103] op_sel_hi:[0,1,1]
	v_cvt_pk_bf16_f32 v100, v116, v101
	ds_write_b16 v128, v100 offset:2048
	ds_write_b16_d16_hi v141, v100 offset:2048
	v_mov_b32_e32 v102, v105
	v_mov_b32_e32 v104, v121
	s_waitcnt vmcnt(15)
	v_mov_b64_e32 v[100:101], v[230:231]
	global_load_dwordx2 v[230:231], v[252:253], off offset:256
	v_pk_mul_f32 v[102:103], v[102:103], v[100:101] op_sel:[0,1] op_sel_hi:[0,0]
	v_pk_fma_f32 v[116:117], v[104:105], v[100:101], v[102:103] op_sel_hi:[0,1,1] neg_lo:[0,0,1] neg_hi:[0,0,1]
	v_pk_fma_f32 v[100:101], v[104:105], v[100:101], v[102:103] op_sel_hi:[0,1,1]
	v_cvt_pk_bf16_f32 v100, v116, v101
	ds_write_b16 v112, v100 offset:2048
	ds_write_b16_d16_hi v113, v100 offset:2048
	s_waitcnt vmcnt(15)
	v_mov_b64_e32 v[100:101], v[232:233]
	global_load_dwordx2 v[232:233], v[252:253], off offset:512
	v_pk_mul_f32 v[102:103], v[106:107], v[100:101] op_sel:[0,1] op_sel_hi:[0,0]
	v_pk_fma_f32 v[104:105], v[122:123], v[100:101], v[102:103] neg_lo:[0,0,1] neg_hi:[0,0,1]
	v_pk_fma_f32 v[100:101], v[122:123], v[100:101], v[102:103] op_sel_hi:[0,1,1]
	v_cvt_pk_bf16_f32 v100, v104, v101
	ds_write_b16 v114, v100 offset:2048
	ds_write_b16_d16_hi v143, v100 offset:2048
	v_mov_b32_e32 v102, v107
	v_mov_b32_e32 v104, v123
	s_waitcnt vmcnt(15)
	v_mov_b64_e32 v[100:101], v[234:235]
	global_load_dwordx2 v[234:235], v[252:253], off offset:768
	v_pk_mul_f32 v[102:103], v[102:103], v[100:101] op_sel:[0,1] op_sel_hi:[0,0]
	v_pk_fma_f32 v[106:107], v[104:105], v[100:101], v[102:103] op_sel_hi:[0,1,1] neg_lo:[0,0,1] neg_hi:[0,0,1]
	v_pk_fma_f32 v[100:101], v[104:105], v[100:101], v[102:103] op_sel_hi:[0,1,1]
	v_cvt_pk_bf16_f32 v100, v106, v101
	ds_write_b16 v115, v100 offset:2048
	ds_write_b16_d16_hi v148, v100 offset:2048
	s_waitcnt vmcnt(15)
	v_mov_b64_e32 v[100:101], v[236:237]
	global_load_dwordx2 v[236:237], v[252:253], off offset:2048
	v_pk_mul_f32 v[102:103], v[108:109], v[100:101] op_sel:[0,1] op_sel_hi:[0,0]
	v_pk_fma_f32 v[104:105], v[124:125], v[100:101], v[102:103] neg_lo:[0,0,1] neg_hi:[0,0,1]
	v_pk_fma_f32 v[100:101], v[124:125], v[100:101], v[102:103] op_sel_hi:[0,1,1]
	v_cvt_pk_bf16_f32 v100, v104, v101
	ds_write_b16 v128, v100 offset:3072
	ds_write_b16_d16_hi v141, v100 offset:3072
	v_mov_b32_e32 v102, v109
	v_mov_b32_e32 v104, v125
	s_waitcnt vmcnt(15)
	v_mov_b64_e32 v[100:101], v[238:239]
	global_load_dwordx2 v[238:239], v[252:253], off offset:2304
	v_pk_mul_f32 v[102:103], v[102:103], v[100:101] op_sel:[0,1] op_sel_hi:[0,0]
	v_pk_fma_f32 v[106:107], v[104:105], v[100:101], v[102:103] op_sel_hi:[0,1,1] neg_lo:[0,0,1] neg_hi:[0,0,1]
	v_pk_fma_f32 v[100:101], v[104:105], v[100:101], v[102:103] op_sel_hi:[0,1,1]
	v_cvt_pk_bf16_f32 v100, v106, v101
	ds_write_b16 v112, v100 offset:3072
	ds_write_b16_d16_hi v113, v100 offset:3072
	s_waitcnt vmcnt(15)
	v_mov_b64_e32 v[100:101], v[240:241]
	global_load_dwordx2 v[240:241], v[252:253], off offset:2560
	v_pk_mul_f32 v[102:103], v[110:111], v[100:101] op_sel:[0,1] op_sel_hi:[0,0]
	v_pk_fma_f32 v[104:105], v[126:127], v[100:101], v[102:103] neg_lo:[0,0,1] neg_hi:[0,0,1]
	v_pk_fma_f32 v[100:101], v[126:127], v[100:101], v[102:103] op_sel_hi:[0,1,1]
	v_cvt_pk_bf16_f32 v100, v104, v101
	ds_write_b16 v114, v100 offset:3072
	ds_write_b16_d16_hi v143, v100 offset:3072
	v_mov_b32_e32 v100, v111
	v_mov_b32_e32 v102, v127
	s_waitcnt vmcnt(15)
	v_mov_b64_e32 v[98:99], v[244:245]
	global_load_dwordx2 v[244:245], v[252:253], off offset:2816
	v_pk_mul_f32 v[100:101], v[100:101], v[98:99] op_sel:[0,1] op_sel_hi:[0,0]
	v_pk_fma_f32 v[104:105], v[102:103], v[98:99], v[100:101] op_sel_hi:[0,1,1] neg_lo:[0,0,1] neg_hi:[0,0,1]
	v_pk_fma_f32 v[98:99], v[102:103], v[98:99], v[100:101] op_sel_hi:[0,1,1]
	v_cvt_pk_bf16_f32 v98, v104, v99
	ds_write_b16 v115, v98 offset:3072
	ds_write_b16_d16_hi v148, v98 offset:3072
	s_waitcnt vmcnt(15)
	v_mov_b64_e32 v[98:99], v[212:213]
	v_pk_mul_f32 v[100:101], v[64:65], v[98:99] op_sel:[0,1] op_sel_hi:[0,0]
	v_pk_fma_f32 v[102:103], v[80:81], v[98:99], v[100:101] neg_lo:[0,0,1] neg_hi:[0,0,1]
	v_pk_fma_f32 v[98:99], v[80:81], v[98:99], v[100:101] op_sel_hi:[0,1,1]
	v_cvt_pk_bf16_f32 v98, v102, v99
	ds_write_b16 v128, v98 offset:4096
	ds_write_b16_d16_hi v141, v98 offset:4096
	s_waitcnt vmcnt(14)
	v_mov_b64_e32 v[98:99], v[214:215]
	v_pk_mul_f32 v[64:65], v[64:65], v[98:99] op_sel:[1,1] op_sel_hi:[1,0]
	s_nop 0
	v_pk_fma_f32 v[100:101], v[80:81], v[98:99], v[64:65] op_sel:[1,0,0] neg_lo:[0,0,1] neg_hi:[0,0,1]
	v_pk_fma_f32 v[64:65], v[80:81], v[98:99], v[64:65] op_sel:[1,0,0]
	s_nop 0
	v_cvt_pk_bf16_f32 v64, v100, v65
	ds_write_b16 v112, v64 offset:4096
	ds_write_b16_d16_hi v113, v64 offset:4096
	s_waitcnt vmcnt(13)
	v_mov_b64_e32 v[64:65], v[216:217]
	v_pk_mul_f32 v[80:81], v[66:67], v[64:65] op_sel:[0,1] op_sel_hi:[0,0]
	v_pk_fma_f32 v[98:99], v[82:83], v[64:65], v[80:81] neg_lo:[0,0,1] neg_hi:[0,0,1]
	v_pk_fma_f32 v[64:65], v[82:83], v[64:65], v[80:81] op_sel_hi:[0,1,1]
	v_cvt_pk_bf16_f32 v64, v98, v65
	ds_write_b16 v114, v64 offset:4096
	ds_write_b16_d16_hi v143, v64 offset:4096
	v_mov_b32_e32 v66, v67
	v_mov_b32_e32 v80, v83
	s_waitcnt vmcnt(12)
	v_mov_b64_e32 v[64:65], v[218:219]
	v_pk_mul_f32 v[66:67], v[66:67], v[64:65] op_sel:[0,1] op_sel_hi:[0,0]
	v_pk_fma_f32 v[82:83], v[80:81], v[64:65], v[66:67] op_sel_hi:[0,1,1] neg_lo:[0,0,1] neg_hi:[0,0,1]
	v_pk_fma_f32 v[64:65], v[80:81], v[64:65], v[66:67] op_sel_hi:[0,1,1]
	v_cvt_pk_bf16_f32 v64, v82, v65
	ds_write_b16 v115, v64 offset:4096
	ds_write_b16_d16_hi v148, v64 offset:4096
	s_waitcnt vmcnt(11)
	v_mov_b64_e32 v[64:65], v[220:221]
	v_pk_mul_f32 v[66:67], v[68:69], v[64:65] op_sel:[0,1] op_sel_hi:[0,0]
	v_pk_fma_f32 v[80:81], v[84:85], v[64:65], v[66:67] neg_lo:[0,0,1] neg_hi:[0,0,1]
	v_pk_fma_f32 v[64:65], v[84:85], v[64:65], v[66:67] op_sel_hi:[0,1,1]
	v_cvt_pk_bf16_f32 v64, v80, v65
	ds_write_b16 v128, v64 offset:5120
	ds_write_b16_d16_hi v141, v64 offset:5120
	v_mov_b32_e32 v66, v69
	v_mov_b32_e32 v68, v85
	s_waitcnt vmcnt(10)
	v_mov_b64_e32 v[64:65], v[222:223]
	v_pk_mul_f32 v[66:67], v[66:67], v[64:65] op_sel:[0,1] op_sel_hi:[0,0]
	v_pk_fma_f32 v[80:81], v[68:69], v[64:65], v[66:67] op_sel_hi:[0,1,1] neg_lo:[0,0,1] neg_hi:[0,0,1]
	v_pk_fma_f32 v[64:65], v[68:69], v[64:65], v[66:67] op_sel_hi:[0,1,1]
	v_cvt_pk_bf16_f32 v64, v80, v65
	ds_write_b16 v112, v64 offset:5120
	ds_write_b16_d16_hi v113, v64 offset:5120
	s_waitcnt vmcnt(9)
	v_mov_b64_e32 v[64:65], v[224:225]
	v_pk_mul_f32 v[66:67], v[70:71], v[64:65] op_sel:[0,1] op_sel_hi:[0,0]
	v_pk_fma_f32 v[68:69], v[86:87], v[64:65], v[66:67] neg_lo:[0,0,1] neg_hi:[0,0,1]
	v_pk_fma_f32 v[64:65], v[86:87], v[64:65], v[66:67] op_sel_hi:[0,1,1]
	v_cvt_pk_bf16_f32 v64, v68, v65
	ds_write_b16 v114, v64 offset:5120
	ds_write_b16_d16_hi v143, v64 offset:5120
	v_mov_b32_e32 v66, v71
	v_mov_b32_e32 v68, v87
	s_waitcnt vmcnt(8)
	v_mov_b64_e32 v[64:65], v[226:227]
	v_pk_mul_f32 v[66:67], v[66:67], v[64:65] op_sel:[0,1] op_sel_hi:[0,0]
	v_pk_fma_f32 v[70:71], v[68:69], v[64:65], v[66:67] op_sel_hi:[0,1,1] neg_lo:[0,0,1] neg_hi:[0,0,1]
	v_pk_fma_f32 v[64:65], v[68:69], v[64:65], v[66:67] op_sel_hi:[0,1,1]
	v_cvt_pk_bf16_f32 v64, v70, v65
	ds_write_b16 v115, v64 offset:5120
	ds_write_b16_d16_hi v148, v64 offset:5120
	v_add_co_u32_e32 v64, vcc, s90, v144
	s_nop 1
	v_addc_co_u32_e32 v65, vcc, 0, v145, vcc
	s_waitcnt vmcnt(7)
	v_mov_b64_e32 v[66:67], v[228:229]
	v_pk_mul_f32 v[68:69], v[72:73], v[66:67] op_sel:[0,1] op_sel_hi:[0,0]
	v_pk_fma_f32 v[70:71], v[88:89], v[66:67], v[68:69] neg_lo:[0,0,1] neg_hi:[0,0,1]
	v_pk_fma_f32 v[66:67], v[88:89], v[66:67], v[68:69] op_sel_hi:[0,1,1]
	v_cvt_pk_bf16_f32 v66, v70, v67
	ds_write_b16 v128, v66 offset:6144
	ds_write_b16_d16_hi v141, v66 offset:6144
	v_mov_b32_e32 v68, v73
	v_mov_b32_e32 v70, v89
	s_waitcnt vmcnt(6)
	v_mov_b64_e32 v[66:67], v[230:231]
	v_pk_mul_f32 v[68:69], v[68:69], v[66:67] op_sel:[0,1] op_sel_hi:[0,0]
	v_pk_fma_f32 v[72:73], v[70:71], v[66:67], v[68:69] op_sel_hi:[0,1,1] neg_lo:[0,0,1] neg_hi:[0,0,1]
	v_pk_fma_f32 v[66:67], v[70:71], v[66:67], v[68:69] op_sel_hi:[0,1,1]
	v_cvt_pk_bf16_f32 v66, v72, v67
	ds_write_b16 v112, v66 offset:6144
	ds_write_b16_d16_hi v113, v66 offset:6144
	s_waitcnt vmcnt(5)
	v_mov_b64_e32 v[66:67], v[232:233]
	v_pk_mul_f32 v[68:69], v[74:75], v[66:67] op_sel:[0,1] op_sel_hi:[0,0]
	v_pk_fma_f32 v[70:71], v[90:91], v[66:67], v[68:69] neg_lo:[0,0,1] neg_hi:[0,0,1]
	v_pk_fma_f32 v[66:67], v[90:91], v[66:67], v[68:69] op_sel_hi:[0,1,1]
	v_cvt_pk_bf16_f32 v66, v70, v67
	ds_write_b16 v114, v66 offset:6144
	ds_write_b16_d16_hi v143, v66 offset:6144
	v_mov_b32_e32 v68, v75
	v_mov_b32_e32 v70, v91
	v_mov_b32_e32 v74, v129
	s_waitcnt vmcnt(4)
	v_mov_b64_e32 v[66:67], v[234:235]
	v_pk_mul_f32 v[68:69], v[68:69], v[66:67] op_sel:[0,1] op_sel_hi:[0,0]
	v_pk_fma_f32 v[72:73], v[70:71], v[66:67], v[68:69] op_sel_hi:[0,1,1] neg_lo:[0,0,1] neg_hi:[0,0,1]
	v_pk_fma_f32 v[66:67], v[70:71], v[66:67], v[68:69] op_sel_hi:[0,1,1]
	v_cvt_pk_bf16_f32 v66, v72, v67
	ds_write_b16 v115, v66 offset:6144
	ds_write_b16_d16_hi v148, v66 offset:6144
	s_waitcnt vmcnt(3)
	v_mov_b64_e32 v[66:67], v[236:237]
	v_pk_mul_f32 v[68:69], v[76:77], v[66:67] op_sel:[0,1] op_sel_hi:[0,0]
	v_pk_fma_f32 v[70:71], v[92:93], v[66:67], v[68:69] neg_lo:[0,0,1] neg_hi:[0,0,1]
	v_pk_fma_f32 v[66:67], v[92:93], v[66:67], v[68:69] op_sel_hi:[0,1,1]
	v_cvt_pk_bf16_f32 v66, v70, v67
	ds_write_b16 v128, v66 offset:7168
	ds_write_b16_d16_hi v141, v66 offset:7168
	v_mov_b32_e32 v68, v77
	v_mov_b32_e32 v70, v93
	v_mov_b32_e32 v77, v129
	s_waitcnt vmcnt(2)
	v_mov_b64_e32 v[66:67], v[238:239]
	v_pk_mul_f32 v[68:69], v[68:69], v[66:67] op_sel:[0,1] op_sel_hi:[0,0]
	v_pk_fma_f32 v[72:73], v[70:71], v[66:67], v[68:69] op_sel_hi:[0,1,1] neg_lo:[0,0,1] neg_hi:[0,0,1]
	v_pk_fma_f32 v[66:67], v[70:71], v[66:67], v[68:69] op_sel_hi:[0,1,1]
	v_cvt_pk_bf16_f32 v66, v72, v67
	ds_write_b16 v112, v66 offset:7168
	ds_write_b16_d16_hi v113, v66 offset:7168
	s_waitcnt vmcnt(1)
	v_mov_b64_e32 v[66:67], v[240:241]
	v_pk_mul_f32 v[68:69], v[78:79], v[66:67] op_sel:[0,1] op_sel_hi:[0,0]
	v_pk_fma_f32 v[70:71], v[94:95], v[66:67], v[68:69] neg_lo:[0,0,1] neg_hi:[0,0,1]
	v_pk_fma_f32 v[66:67], v[94:95], v[66:67], v[68:69] op_sel_hi:[0,1,1]
	v_cvt_pk_bf16_f32 v66, v70, v67
	ds_write_b16 v114, v66 offset:7168
	ds_write_b16_d16_hi v143, v66 offset:7168
	v_mov_b32_e32 v66, v79
	v_mov_b32_e32 v68, v95
	s_waitcnt vmcnt(0)
	v_mov_b64_e32 v[64:65], v[244:245]
	v_pk_mul_f32 v[66:67], v[66:67], v[64:65] op_sel:[0,1] op_sel_hi:[0,0]
	v_pk_fma_f32 v[70:71], v[68:69], v[64:65], v[66:67] op_sel_hi:[0,1,1] neg_lo:[0,0,1] neg_hi:[0,0,1]
	v_pk_fma_f32 v[64:65], v[68:69], v[64:65], v[66:67] op_sel_hi:[0,1,1]
	v_cvt_pk_bf16_f32 v64, v70, v65
	v_lshlrev_b32_e32 v65, 2, v211
	v_and_b32_e32 v66, 15, v211
	v_and_or_b32 v78, v65, s78, v66
	v_lshlrev_b32_e32 v65, 4, v211
	ds_write_b16 v115, v64 offset:7168
	ds_write_b16_d16_hi v148, v64 offset:7168
	v_lshl_add_u32 v64, v211, 7, v192
	v_and_b32_e32 v65, 0x70, v65
	v_add_u32_e32 v66, v64, v65
	ds_read_b128 v[66:69], v66
	v_xad_u32 v70, v65, 64, v64
	ds_read_b128 v[70:73], v70
	s_waitcnt lgkmcnt(1)
	v_lshlrev_b32_e32 v75, 16, v66
	v_and_b32_e32 v66, 0xffff0000, v66
	v_cvt_pk_fp8_f32 v74, v75, v66
	v_lshlrev_b32_e32 v76, 16, v67
	v_and_b32_e32 v67, 0xffff0000, v67
	v_lshlrev_b32_e32 v66, 16, v68
	v_cvt_pk_fp8_f32 v74, v76, v67 op_sel:[0,0,1]
	v_and_b32_e32 v67, 0xffff0000, v68
	v_mov_b32_e32 v75, v129
	v_cvt_pk_fp8_f32 v75, v66, v67
	s_waitcnt lgkmcnt(0)
	v_lshlrev_b32_e32 v66, 16, v70
	v_and_b32_e32 v67, 0xffff0000, v70
	v_mov_b32_e32 v76, v129
	v_cvt_pk_fp8_f32 v76, v66, v67
	v_lshlrev_b32_e32 v66, 16, v72
	v_and_b32_e32 v67, 0xffff0000, v72
	v_cvt_pk_fp8_f32 v77, v66, v67
	v_lshlrev_b32_e32 v68, 16, v69
	v_and_b32_e32 v69, 0xffff0000, v69
	v_cvt_pk_fp8_f32 v75, v68, v69 op_sel:[0,0,1]
	v_lshlrev_b32_e32 v68, 16, v71
	v_and_b32_e32 v69, 0xffff0000, v71
	v_lshlrev_b32_e32 v66, 4, v78
	v_cvt_pk_fp8_f32 v76, v68, v69 op_sel:[0,0,1]
	v_lshlrev_b32_e32 v68, 16, v73
	v_and_b32_e32 v69, 0xffff0000, v73
	v_ashrrev_i32_e32 v67, 31, v66
	v_cvt_pk_fp8_f32 v77, v68, v69 op_sel:[0,0,1]
	v_lshl_add_u64 v[68:69], v[146:147], 0, v[66:67]
	v_xad_u32 v66, v65, 16, v64
	ds_read_b128 v[70:73], v66
	v_xad_u32 v66, v65, s76, v64
	global_store_dwordx4 v[68:69], v[74:77], off
	ds_read_b128 v[74:77], v66
	s_waitcnt lgkmcnt(1)
	v_lshlrev_b32_e32 v66, 16, v70
	v_and_b32_e32 v67, 0xffff0000, v70
	v_mov_b32_e32 v70, v129
	v_cvt_pk_fp8_f32 v70, v66, v67
	v_lshlrev_b32_e32 v78, 16, v71
	v_and_b32_e32 v71, 0xffff0000, v71
	v_lshlrev_b32_e32 v66, 16, v72
	v_cvt_pk_fp8_f32 v70, v78, v71 op_sel:[0,0,1]
	v_and_b32_e32 v67, 0xffff0000, v72
	v_mov_b32_e32 v71, v129
	v_cvt_pk_fp8_f32 v71, v66, v67
	v_lshlrev_b32_e32 v72, 16, v73
	v_and_b32_e32 v73, 0xffff0000, v73
	s_waitcnt lgkmcnt(0)
	v_lshlrev_b32_e32 v66, 16, v74
	v_cvt_pk_fp8_f32 v71, v72, v73 op_sel:[0,0,1]
	v_and_b32_e32 v67, 0xffff0000, v74
	v_mov_b32_e32 v72, v129
	v_cvt_pk_fp8_f32 v72, v66, v67
	v_lshlrev_b32_e32 v73, 16, v75
	v_and_b32_e32 v74, 0xffff0000, v75
	v_lshlrev_b32_e32 v66, 16, v76
	v_cvt_pk_fp8_f32 v72, v73, v74 op_sel:[0,0,1]
	v_and_b32_e32 v67, 0xffff0000, v76
	v_mov_b32_e32 v73, v129
	v_cvt_pk_fp8_f32 v73, v66, v67
	v_lshlrev_b32_e32 v74, 16, v77
	v_and_b32_e32 v75, 0xffff0000, v77
	v_xad_u32 v66, v65, 32, v64
	v_cvt_pk_fp8_f32 v73, v74, v75 op_sel:[0,0,1]
	global_store_dwordx4 v[68:69], v[70:73], off offset:256
	ds_read_b128 v[70:73], v66
	v_xad_u32 v66, v65, s77, v64
	ds_read_b128 v[74:77], v66
	s_waitcnt lgkmcnt(1)
	v_lshlrev_b32_e32 v66, 16, v70
	v_and_b32_e32 v67, 0xffff0000, v70
	v_mov_b32_e32 v70, v129
	v_cvt_pk_fp8_f32 v70, v66, v67
	v_lshlrev_b32_e32 v78, 16, v71
	v_and_b32_e32 v71, 0xffff0000, v71
	v_lshlrev_b32_e32 v66, 16, v72
	v_cvt_pk_fp8_f32 v70, v78, v71 op_sel:[0,0,1]
	v_and_b32_e32 v67, 0xffff0000, v72
	v_mov_b32_e32 v71, v129
	v_cvt_pk_fp8_f32 v71, v66, v67
	v_lshlrev_b32_e32 v72, 16, v73
	v_and_b32_e32 v73, 0xffff0000, v73
	s_waitcnt lgkmcnt(0)
	v_lshlrev_b32_e32 v66, 16, v74
	v_cvt_pk_fp8_f32 v71, v72, v73 op_sel:[0,0,1]
	v_and_b32_e32 v67, 0xffff0000, v74
	v_mov_b32_e32 v72, v129
	v_cvt_pk_fp8_f32 v72, v66, v67
	v_lshlrev_b32_e32 v73, 16, v75
	v_and_b32_e32 v74, 0xffff0000, v75
	v_lshlrev_b32_e32 v66, 16, v76
	v_cvt_pk_fp8_f32 v72, v73, v74 op_sel:[0,0,1]
	v_and_b32_e32 v67, 0xffff0000, v76
	v_mov_b32_e32 v73, v129
	v_cvt_pk_fp8_f32 v73, v66, v67
	v_lshlrev_b32_e32 v74, 16, v77
	v_and_b32_e32 v75, 0xffff0000, v77
	v_xad_u32 v66, v65, 48, v64
	v_cvt_pk_fp8_f32 v73, v74, v75 op_sel:[0,0,1]
	v_xad_u32 v64, v65, s21, v64
	ds_read_b128 v[74:77], v64
	v_mov_b32_e32 v64, v129
	global_store_dwordx4 v[68:69], v[70:73], off offset:512
	ds_read_b128 v[70:73], v66
	s_waitcnt lgkmcnt(0)
	v_lshlrev_b32_e32 v65, 16, v70
	v_and_b32_e32 v66, 0xffff0000, v70
	v_cvt_pk_fp8_f32 v64, v65, v66
	v_lshlrev_b32_e32 v67, 16, v71
	v_and_b32_e32 v70, 0xffff0000, v71
	v_lshlrev_b32_e32 v66, 16, v72
	v_cvt_pk_fp8_f32 v64, v67, v70 op_sel:[0,0,1]
	v_and_b32_e32 v67, 0xffff0000, v72
	v_mov_b32_e32 v65, v129
	v_cvt_pk_fp8_f32 v65, v66, v67
	v_lshlrev_b32_e32 v70, 16, v73
	v_and_b32_e32 v71, 0xffff0000, v73
	v_lshlrev_b32_e32 v67, 16, v74
	v_cvt_pk_fp8_f32 v65, v70, v71 op_sel:[0,0,1]
	v_and_b32_e32 v70, 0xffff0000, v74
	v_mov_b32_e32 v66, v129
	v_cvt_pk_fp8_f32 v66, v67, v70
	v_lshlrev_b32_e32 v71, 16, v75
	v_and_b32_e32 v72, 0xffff0000, v75
	v_and_b32_e32 v73, 0xffff0000, v76
	v_cvt_pk_fp8_f32 v66, v71, v72 op_sel:[0,0,1]
	v_lshlrev_b32_e32 v72, 16, v76
	v_mov_b32_e32 v67, v129
	v_cvt_pk_fp8_f32 v67, v72, v73
	v_lshlrev_b32_e32 v70, 16, v77
	v_and_b32_e32 v71, 0xffff0000, v77
	v_cvt_pk_fp8_f32 v67, v70, v71 op_sel:[0,0,1]
	global_store_dwordx4 v[68:69], v[64:67], off offset:768
.LBB0_203:
	s_andn2_saveexec_b64 s[4:5], s[4:5]
	s_cbranch_execz .LBB0_205
	s_mov_b32 s101, 0
	s_mov_b32 s100, 0x1000
	v_lshl_add_u64 v[246:247], v[144:145], 0, s[100:101]
	s_mov_b32 s100, 0x2000
	v_lshl_add_u64 v[250:251], v[144:145], 0, s[100:101]
	s_mov_b32 s100, 0x3000
	v_lshl_add_u64 v[252:253], v[144:145], 0, s[100:101]
	global_load_dwordx2 v[212:213], v[144:145], off
	global_load_dwordx2 v[214:215], v[144:145], off offset:256
	global_load_dwordx2 v[216:217], v[144:145], off offset:512
	global_load_dwordx2 v[218:219], v[144:145], off offset:768
	global_load_dwordx2 v[220:221], v[144:145], off offset:2048
	global_load_dwordx2 v[222:223], v[144:145], off offset:2304
	global_load_dwordx2 v[224:225], v[144:145], off offset:2560
	global_load_dwordx2 v[226:227], v[144:145], off offset:2816
	global_load_dwordx2 v[228:229], v[246:247], off
	global_load_dwordx2 v[230:231], v[246:247], off offset:256
	global_load_dwordx2 v[232:233], v[246:247], off offset:512
	global_load_dwordx2 v[234:235], v[246:247], off offset:768
	global_load_dwordx2 v[236:237], v[246:247], off offset:2048
	global_load_dwordx2 v[238:239], v[246:247], off offset:2304
	global_load_dwordx2 v[240:241], v[246:247], off offset:2560
	global_load_dwordx2 v[244:245], v[246:247], off offset:2816
	v_ashrrev_i32_e32 v146, 3, v211
	v_lshrrev_b32_e32 v158, 3, v211
	v_lshlrev_b32_e32 v128, 1, v211
	v_and_b32_e32 v160, -4, v146
	v_bfe_u32 v159, v211, 3, 2
	v_bfi_b32 v141, 3, v158, v146
	v_and_b32_e32 v161, 14, v128
	v_lshlrev_b32_e32 v128, 7, v160
	v_or_b32_e32 v143, 1, v160
	v_bitop3_b32 v147, v160, v159, 1 bitop3:0x36
	v_lshl_add_u32 v128, v141, 4, v128
	v_lshlrev_b32_e32 v141, 7, v143
	v_lshl_add_u32 v143, v147, 4, v141
	v_or_b32_e32 v141, v128, v161
	v_add_u32_e32 v128, v192, v141
	v_or_b32_e32 v147, v143, v161
	v_xad_u32 v141, v141, 64, v192
	v_add_u32_e32 v143, v192, v147
	v_xad_u32 v147, v147, 64, v192
	s_waitcnt vmcnt(14)
	v_mov_b64_e32 v[148:149], v[212:213]
	v_mov_b64_e32 v[150:151], v[214:215]
	global_load_dwordx2 v[212:213], v[250:251], off
	global_load_dwordx2 v[214:215], v[250:251], off offset:256
	v_pk_mul_f32 v[152:153], v[96:97], v[148:149] op_sel:[0,1] op_sel_hi:[0,0]
	v_pk_mul_f32 v[96:97], v[96:97], v[150:151] op_sel:[1,1] op_sel_hi:[1,0]
	v_pk_fma_f32 v[156:157], v[112:113], v[148:149], v[152:153] neg_lo:[0,0,1] neg_hi:[0,0,1]
	v_pk_fma_f32 v[148:149], v[112:113], v[148:149], v[152:153] op_sel_hi:[0,1,1]
	v_pk_fma_f32 v[152:153], v[112:113], v[150:151], v[96:97] op_sel:[1,0,0] neg_lo:[0,0,1] neg_hi:[0,0,1]
	v_pk_fma_f32 v[96:97], v[112:113], v[150:151], v[96:97] op_sel:[1,0,0]
	v_mov_b32_e32 v157, v149
	v_mov_b32_e32 v153, v97
	v_pk_mul_f32 v[96:97], v[156:157], s[20:21] op_sel_hi:[1,0]
	v_pk_mul_f32 v[112:113], v[152:153], s[20:21] op_sel_hi:[1,0]
	v_cvt_pk_bf16_f32 v96, v96, v97
	v_cvt_pk_bf16_f32 v97, v112, v113
	ds_write_b16 v128, v96
	ds_write_b16_d16_hi v141, v96
	ds_write_b16 v143, v97
	ds_write_b16_d16_hi v147, v97
	v_mov_b32_e32 v152, v99
	v_or_b32_e32 v112, 3, v146
	v_or_b32_e32 v148, 2, v160
	v_mov_b32_e32 v156, v115
	v_bitop3_b32 v113, v158, v146, 3 bitop3:0x4e
	v_bitop3_b32 v149, v160, v159, 2 bitop3:0x36
	v_lshlrev_b32_e32 v112, 7, v112
	v_lshlrev_b32_e32 v148, 7, v148
	v_lshl_add_u32 v112, v113, 4, v112
	v_lshl_add_u32 v113, v149, 4, v148
	v_or_b32_e32 v148, v112, v161
	v_or_b32_e32 v149, v113, v161
	v_add_u32_e32 v112, v192, v148
	v_xad_u32 v113, v148, 64, v192
	v_add_u32_e32 v148, v192, v149
	v_xad_u32 v149, v149, 64, v192
	s_waitcnt vmcnt(15)
	v_mov_b64_e32 v[96:97], v[216:217]
	global_load_dwordx2 v[216:217], v[250:251], off offset:512
	v_pk_mul_f32 v[98:99], v[98:99], v[96:97] op_sel:[0,1] op_sel_hi:[0,0]
	s_waitcnt vmcnt(15)
	v_mov_b64_e32 v[150:151], v[218:219]
	global_load_dwordx2 v[218:219], v[250:251], off offset:768
	v_pk_mul_f32 v[152:153], v[152:153], v[150:151] op_sel:[0,1] op_sel_hi:[0,0]
	v_pk_fma_f32 v[158:159], v[114:115], v[96:97], v[98:99] neg_lo:[0,0,1] neg_hi:[0,0,1]
	v_pk_fma_f32 v[96:97], v[114:115], v[96:97], v[98:99] op_sel_hi:[0,1,1]
	v_pk_fma_f32 v[98:99], v[156:157], v[150:151], v[152:153] op_sel_hi:[0,1,1] neg_lo:[0,0,1] neg_hi:[0,0,1]
	v_pk_fma_f32 v[114:115], v[156:157], v[150:151], v[152:153] op_sel_hi:[0,1,1]
	v_mov_b32_e32 v159, v97
	v_mov_b32_e32 v99, v115
	v_pk_mul_f32 v[96:97], v[158:159], s[20:21] op_sel_hi:[1,0]
	v_pk_mul_f32 v[98:99], v[98:99], s[20:21] op_sel_hi:[1,0]
	v_cvt_pk_bf16_f32 v96, v96, v97
	v_cvt_pk_bf16_f32 v97, v98, v99
	ds_write_b16 v148, v96
	ds_write_b16_d16_hi v149, v96
	ds_write_b16 v112, v97
	ds_write_b16_d16_hi v113, v97
	v_mov_b32_e32 v114, v101
	v_mov_b32_e32 v150, v117
	s_waitcnt vmcnt(15)
	v_mov_b64_e32 v[96:97], v[220:221]
	global_load_dwordx2 v[220:221], v[250:251], off offset:2048
	v_pk_mul_f32 v[100:101], v[100:101], v[96:97] op_sel:[0,1] op_sel_hi:[0,0]
	s_waitcnt vmcnt(15)
	v_mov_b64_e32 v[98:99], v[222:223]
	global_load_dwordx2 v[222:223], v[250:251], off offset:2304
	v_pk_mul_f32 v[114:115], v[114:115], v[98:99] op_sel:[0,1] op_sel_hi:[0,0]
	v_pk_fma_f32 v[152:153], v[116:117], v[96:97], v[100:101] neg_lo:[0,0,1] neg_hi:[0,0,1]
	v_pk_fma_f32 v[96:97], v[116:117], v[96:97], v[100:101] op_sel_hi:[0,1,1]
	v_pk_fma_f32 v[100:101], v[150:151], v[98:99], v[114:115] op_sel_hi:[0,1,1] neg_lo:[0,0,1] neg_hi:[0,0,1]
	v_pk_fma_f32 v[98:99], v[150:151], v[98:99], v[114:115] op_sel_hi:[0,1,1]
	v_mov_b32_e32 v153, v97
	v_mov_b32_e32 v101, v99
	v_pk_mul_f32 v[96:97], v[152:153], s[20:21] op_sel_hi:[1,0]
	v_pk_mul_f32 v[98:99], v[100:101], s[20:21] op_sel_hi:[1,0]
	v_cvt_pk_bf16_f32 v96, v96, v97
	v_cvt_pk_bf16_f32 v97, v98, v99
	ds_write_b16 v128, v96 offset:1024
	ds_write_b16_d16_hi v141, v96 offset:1024
	ds_write_b16 v143, v97 offset:1024
	ds_write_b16_d16_hi v147, v97 offset:1024
	v_mov_b32_e32 v116, v103
	v_mov_b32_e32 v150, v119
	v_add_co_u32_e32 v98, vcc, s83, v144
	s_waitcnt vmcnt(15)
	v_mov_b64_e32 v[100:101], v[224:225]
	global_load_dwordx2 v[224:225], v[250:251], off offset:2560
	v_pk_mul_f32 v[102:103], v[102:103], v[100:101] op_sel:[0,1] op_sel_hi:[0,0]
	s_waitcnt vmcnt(15)
	v_mov_b64_e32 v[114:115], v[226:227]
	global_load_dwordx2 v[226:227], v[250:251], off offset:2816
	v_pk_mul_f32 v[116:117], v[116:117], v[114:115] op_sel:[0,1] op_sel_hi:[0,0]
	v_pk_fma_f32 v[152:153], v[118:119], v[100:101], v[102:103] neg_lo:[0,0,1] neg_hi:[0,0,1]
	v_pk_fma_f32 v[100:101], v[118:119], v[100:101], v[102:103] op_sel_hi:[0,1,1]
	v_pk_fma_f32 v[102:103], v[150:151], v[114:115], v[116:117] op_sel_hi:[0,1,1] neg_lo:[0,0,1] neg_hi:[0,0,1]
	v_pk_fma_f32 v[114:115], v[150:151], v[114:115], v[116:117] op_sel_hi:[0,1,1]
	v_mov_b32_e32 v153, v101
	v_mov_b32_e32 v103, v115
	v_pk_mul_f32 v[100:101], v[152:153], s[20:21] op_sel_hi:[1,0]
	v_addc_co_u32_e32 v99, vcc, 0, v145, vcc
	v_pk_mul_f32 v[102:103], v[102:103], s[20:21] op_sel_hi:[1,0]
	v_cvt_pk_bf16_f32 v100, v100, v101
	v_add_co_u32_e32 v96, vcc, s51, v144
	v_cvt_pk_bf16_f32 v101, v102, v103
	ds_write_b16 v148, v100 offset:1024
	ds_write_b16_d16_hi v149, v100 offset:1024
	ds_write_b16 v112, v101 offset:1024
	ds_write_b16_d16_hi v113, v101 offset:1024
	v_addc_co_u32_e32 v97, vcc, 0, v145, vcc
	v_mov_b32_e32 v114, v105
	v_mov_b32_e32 v116, v121
	s_waitcnt vmcnt(15)
	v_mov_b64_e32 v[100:101], v[228:229]
	global_load_dwordx2 v[228:229], v[252:253], off
	v_pk_mul_f32 v[104:105], v[104:105], v[100:101] op_sel:[0,1] op_sel_hi:[0,0]
	s_waitcnt vmcnt(15)
	v_mov_b64_e32 v[102:103], v[230:231]
	global_load_dwordx2 v[230:231], v[252:253], off offset:256
	v_pk_mul_f32 v[114:115], v[114:115], v[102:103] op_sel:[0,1] op_sel_hi:[0,0]
	v_pk_fma_f32 v[118:119], v[120:121], v[100:101], v[104:105] neg_lo:[0,0,1] neg_hi:[0,0,1]
	v_pk_fma_f32 v[100:101], v[120:121], v[100:101], v[104:105] op_sel_hi:[0,1,1]
	v_pk_fma_f32 v[104:105], v[116:117], v[102:103], v[114:115] op_sel_hi:[0,1,1] neg_lo:[0,0,1] neg_hi:[0,0,1]
	v_pk_fma_f32 v[102:103], v[116:117], v[102:103], v[114:115] op_sel_hi:[0,1,1]
	v_mov_b32_e32 v119, v101
	v_mov_b32_e32 v105, v103
	v_pk_mul_f32 v[100:101], v[118:119], s[20:21] op_sel_hi:[1,0]
	v_pk_mul_f32 v[102:103], v[104:105], s[20:21] op_sel_hi:[1,0]
	v_cvt_pk_bf16_f32 v100, v100, v101
	v_cvt_pk_bf16_f32 v101, v102, v103
	ds_write_b16 v128, v100 offset:2048
	ds_write_b16_d16_hi v141, v100 offset:2048
	ds_write_b16 v143, v101 offset:2048
	ds_write_b16_d16_hi v147, v101 offset:2048
	v_mov_b32_e32 v104, v107
	v_mov_b32_e32 v114, v123
	s_waitcnt vmcnt(15)
	v_mov_b64_e32 v[100:101], v[232:233]
	global_load_dwordx2 v[232:233], v[252:253], off offset:512
	v_pk_mul_f32 v[106:107], v[106:107], v[100:101] op_sel:[0,1] op_sel_hi:[0,0]
	s_waitcnt vmcnt(15)
	v_mov_b64_e32 v[102:103], v[234:235]
	global_load_dwordx2 v[234:235], v[252:253], off offset:768
	v_pk_mul_f32 v[104:105], v[104:105], v[102:103] op_sel:[0,1] op_sel_hi:[0,0]
	v_pk_fma_f32 v[116:117], v[122:123], v[100:101], v[106:107] neg_lo:[0,0,1] neg_hi:[0,0,1]
	v_pk_fma_f32 v[100:101], v[122:123], v[100:101], v[106:107] op_sel_hi:[0,1,1]
	v_pk_fma_f32 v[106:107], v[114:115], v[102:103], v[104:105] op_sel_hi:[0,1,1] neg_lo:[0,0,1] neg_hi:[0,0,1]
	v_pk_fma_f32 v[102:103], v[114:115], v[102:103], v[104:105] op_sel_hi:[0,1,1]
	v_mov_b32_e32 v117, v101
	v_mov_b32_e32 v107, v103
	v_pk_mul_f32 v[100:101], v[116:117], s[20:21] op_sel_hi:[1,0]
	v_pk_mul_f32 v[102:103], v[106:107], s[20:21] op_sel_hi:[1,0]
	v_cvt_pk_bf16_f32 v100, v100, v101
	v_cvt_pk_bf16_f32 v101, v102, v103
	ds_write_b16 v148, v100 offset:2048
	ds_write_b16_d16_hi v149, v100 offset:2048
	ds_write_b16 v112, v101 offset:2048
	ds_write_b16_d16_hi v113, v101 offset:2048
	v_mov_b32_e32 v104, v109
	v_mov_b32_e32 v106, v125
	s_waitcnt vmcnt(15)
	v_mov_b64_e32 v[100:101], v[236:237]
	global_load_dwordx2 v[236:237], v[252:253], off offset:2048
	v_pk_mul_f32 v[108:109], v[108:109], v[100:101] op_sel:[0,1] op_sel_hi:[0,0]
	s_waitcnt vmcnt(15)
	v_mov_b64_e32 v[102:103], v[238:239]
	global_load_dwordx2 v[238:239], v[252:253], off offset:2304
	v_pk_mul_f32 v[104:105], v[104:105], v[102:103] op_sel:[0,1] op_sel_hi:[0,0]
	v_pk_fma_f32 v[114:115], v[124:125], v[100:101], v[108:109] neg_lo:[0,0,1] neg_hi:[0,0,1]
	v_pk_fma_f32 v[100:101], v[124:125], v[100:101], v[108:109] op_sel_hi:[0,1,1]
	v_pk_fma_f32 v[108:109], v[106:107], v[102:103], v[104:105] op_sel_hi:[0,1,1] neg_lo:[0,0,1] neg_hi:[0,0,1]
	v_pk_fma_f32 v[102:103], v[106:107], v[102:103], v[104:105] op_sel_hi:[0,1,1]
	v_mov_b32_e32 v115, v101
	v_mov_b32_e32 v109, v103
	v_pk_mul_f32 v[100:101], v[114:115], s[20:21] op_sel_hi:[1,0]
	v_pk_mul_f32 v[102:103], v[108:109], s[20:21] op_sel_hi:[1,0]
	v_cvt_pk_bf16_f32 v100, v100, v101
	v_cvt_pk_bf16_f32 v101, v102, v103
	ds_write_b16 v128, v100 offset:3072
	ds_write_b16_d16_hi v141, v100 offset:3072
	ds_write_b16 v143, v101 offset:3072
	ds_write_b16_d16_hi v147, v101 offset:3072
	s_nop 0
	v_mov_b32_e32 v102, v111
	v_mov_b32_e32 v104, v127
	s_waitcnt vmcnt(15)
	v_mov_b64_e32 v[100:101], v[240:241]
	global_load_dwordx2 v[240:241], v[252:253], off offset:2560
	v_pk_mul_f32 v[106:107], v[110:111], v[100:101] op_sel:[0,1] op_sel_hi:[0,0]
	s_waitcnt vmcnt(15)
	v_mov_b64_e32 v[98:99], v[244:245]
	global_load_dwordx2 v[244:245], v[252:253], off offset:2816
	v_pk_mul_f32 v[102:103], v[102:103], v[98:99] op_sel:[0,1] op_sel_hi:[0,0]
	v_pk_fma_f32 v[108:109], v[126:127], v[100:101], v[106:107] neg_lo:[0,0,1] neg_hi:[0,0,1]
	v_pk_fma_f32 v[100:101], v[126:127], v[100:101], v[106:107] op_sel_hi:[0,1,1]
	v_pk_fma_f32 v[106:107], v[104:105], v[98:99], v[102:103] op_sel_hi:[0,1,1] neg_lo:[0,0,1] neg_hi:[0,0,1]
	v_pk_fma_f32 v[98:99], v[104:105], v[98:99], v[102:103] op_sel_hi:[0,1,1]
	v_mov_b32_e32 v109, v101
	v_mov_b32_e32 v107, v99
	v_pk_mul_f32 v[98:99], v[108:109], s[20:21] op_sel_hi:[1,0]
	v_pk_mul_f32 v[100:101], v[106:107], s[20:21] op_sel_hi:[1,0]
	v_cvt_pk_bf16_f32 v98, v98, v99
	v_cvt_pk_bf16_f32 v99, v100, v101
	ds_write_b16 v148, v98 offset:3072
	ds_write_b16_d16_hi v149, v98 offset:3072
	ds_write_b16 v112, v99 offset:3072
	ds_write_b16_d16_hi v113, v99 offset:3072
	s_waitcnt vmcnt(15)
	v_mov_b64_e32 v[98:99], v[212:213]
	v_pk_mul_f32 v[102:103], v[64:65], v[98:99] op_sel:[0,1] op_sel_hi:[0,0]
	s_waitcnt vmcnt(14)
	v_mov_b64_e32 v[100:101], v[214:215]
	v_pk_mul_f32 v[64:65], v[64:65], v[100:101] op_sel:[1,1] op_sel_hi:[1,0]
	v_pk_fma_f32 v[104:105], v[80:81], v[98:99], v[102:103] neg_lo:[0,0,1] neg_hi:[0,0,1]
	v_pk_fma_f32 v[98:99], v[80:81], v[98:99], v[102:103] op_sel_hi:[0,1,1]
	v_pk_fma_f32 v[102:103], v[80:81], v[100:101], v[64:65] op_sel:[1,0,0] neg_lo:[0,0,1] neg_hi:[0,0,1]
	v_pk_fma_f32 v[64:65], v[80:81], v[100:101], v[64:65] op_sel:[1,0,0]
	v_mov_b32_e32 v105, v99
	v_mov_b32_e32 v103, v65
	v_pk_mul_f32 v[64:65], v[104:105], s[20:21] op_sel_hi:[1,0]
	v_pk_mul_f32 v[80:81], v[102:103], s[20:21] op_sel_hi:[1,0]
	v_cvt_pk_bf16_f32 v64, v64, v65
	v_cvt_pk_bf16_f32 v65, v80, v81
	ds_write_b16 v128, v64 offset:4096
	ds_write_b16_d16_hi v141, v64 offset:4096
	ds_write_b16 v143, v65 offset:4096
	ds_write_b16_d16_hi v147, v65 offset:4096
	v_mov_b32_e32 v98, v67
	v_mov_b32_e32 v100, v83
	s_waitcnt vmcnt(13)
	v_mov_b64_e32 v[64:65], v[216:217]
	v_pk_mul_f32 v[66:67], v[66:67], v[64:65] op_sel:[0,1] op_sel_hi:[0,0]
	s_waitcnt vmcnt(12)
	v_mov_b64_e32 v[80:81], v[218:219]
	v_pk_mul_f32 v[98:99], v[98:99], v[80:81] op_sel:[0,1] op_sel_hi:[0,0]
	v_pk_fma_f32 v[102:103], v[82:83], v[64:65], v[66:67] neg_lo:[0,0,1] neg_hi:[0,0,1]
	v_pk_fma_f32 v[64:65], v[82:83], v[64:65], v[66:67] op_sel_hi:[0,1,1]
	v_pk_fma_f32 v[66:67], v[100:101], v[80:81], v[98:99] op_sel_hi:[0,1,1] neg_lo:[0,0,1] neg_hi:[0,0,1]
	v_pk_fma_f32 v[80:81], v[100:101], v[80:81], v[98:99] op_sel_hi:[0,1,1]
	v_mov_b32_e32 v103, v65
	v_mov_b32_e32 v67, v81
	v_pk_mul_f32 v[64:65], v[102:103], s[20:21] op_sel_hi:[1,0]
	v_pk_mul_f32 v[66:67], v[66:67], s[20:21] op_sel_hi:[1,0]
	v_cvt_pk_bf16_f32 v64, v64, v65
	v_cvt_pk_bf16_f32 v65, v66, v67
	ds_write_b16 v148, v64 offset:4096
	ds_write_b16_d16_hi v149, v64 offset:4096
	ds_write_b16 v112, v65 offset:4096
	ds_write_b16_d16_hi v113, v65 offset:4096
	v_mov_b32_e32 v80, v69
	v_mov_b32_e32 v82, v85
	s_waitcnt vmcnt(11)
	v_mov_b64_e32 v[64:65], v[220:221]
	v_pk_mul_f32 v[68:69], v[68:69], v[64:65] op_sel:[0,1] op_sel_hi:[0,0]
	s_waitcnt vmcnt(10)
	v_mov_b64_e32 v[66:67], v[222:223]
	v_pk_mul_f32 v[80:81], v[80:81], v[66:67] op_sel:[0,1] op_sel_hi:[0,0]
	v_pk_fma_f32 v[98:99], v[84:85], v[64:65], v[68:69] neg_lo:[0,0,1] neg_hi:[0,0,1]
	v_pk_fma_f32 v[64:65], v[84:85], v[64:65], v[68:69] op_sel_hi:[0,1,1]
	v_pk_fma_f32 v[68:69], v[82:83], v[66:67], v[80:81] op_sel_hi:[0,1,1] neg_lo:[0,0,1] neg_hi:[0,0,1]
	v_pk_fma_f32 v[66:67], v[82:83], v[66:67], v[80:81] op_sel_hi:[0,1,1]
	v_mov_b32_e32 v99, v65
	v_mov_b32_e32 v69, v67
	v_pk_mul_f32 v[64:65], v[98:99], s[20:21] op_sel_hi:[1,0]
	v_pk_mul_f32 v[66:67], v[68:69], s[20:21] op_sel_hi:[1,0]
	v_cvt_pk_bf16_f32 v64, v64, v65
	v_cvt_pk_bf16_f32 v65, v66, v67
	ds_write_b16 v128, v64 offset:5120
	ds_write_b16_d16_hi v141, v64 offset:5120
	ds_write_b16 v143, v65 offset:5120
	ds_write_b16_d16_hi v147, v65 offset:5120
	v_mov_b32_e32 v80, v71
	v_mov_b32_e32 v82, v87
	v_add_co_u32_e32 v66, vcc, s90, v144
	s_waitcnt vmcnt(9)
	v_mov_b64_e32 v[64:65], v[224:225]
	v_pk_mul_f32 v[70:71], v[70:71], v[64:65] op_sel:[0,1] op_sel_hi:[0,0]
	s_waitcnt vmcnt(8)
	v_mov_b64_e32 v[68:69], v[226:227]
	v_pk_mul_f32 v[80:81], v[80:81], v[68:69] op_sel:[0,1] op_sel_hi:[0,0]
	v_pk_fma_f32 v[84:85], v[86:87], v[64:65], v[70:71] neg_lo:[0,0,1] neg_hi:[0,0,1]
	v_pk_fma_f32 v[64:65], v[86:87], v[64:65], v[70:71] op_sel_hi:[0,1,1]
	v_pk_fma_f32 v[70:71], v[82:83], v[68:69], v[80:81] op_sel_hi:[0,1,1] neg_lo:[0,0,1] neg_hi:[0,0,1]
	v_pk_fma_f32 v[68:69], v[82:83], v[68:69], v[80:81] op_sel_hi:[0,1,1]
	v_mov_b32_e32 v85, v65
	v_mov_b32_e32 v71, v69
	v_pk_mul_f32 v[64:65], v[84:85], s[20:21] op_sel_hi:[1,0]
	v_pk_mul_f32 v[68:69], v[70:71], s[20:21] op_sel_hi:[1,0]
	v_cvt_pk_bf16_f32 v64, v64, v65
	v_cvt_pk_bf16_f32 v65, v68, v69
	ds_write_b16 v148, v64 offset:5120
	ds_write_b16_d16_hi v149, v64 offset:5120
	ds_write_b16 v112, v65 offset:5120
	ds_write_b16_d16_hi v113, v65 offset:5120
	v_addc_co_u32_e32 v67, vcc, 0, v145, vcc
	v_mov_b32_e32 v70, v73
	v_mov_b32_e32 v80, v89
	v_add_u32_e32 v84, 40, v146
	v_add_u32_e32 v86, 48, v146
	v_ashrrev_i32_e32 v85, 31, v84
	v_ashrrev_i32_e32 v87, 31, v86
	v_lshlrev_b64 v[102:103], 11, v[84:85]
	v_lshlrev_b64 v[104:105], 11, v[86:87]
	s_waitcnt vmcnt(7)
	v_mov_b64_e32 v[64:65], v[228:229]
	v_pk_mul_f32 v[72:73], v[72:73], v[64:65] op_sel:[0,1] op_sel_hi:[0,0]
	s_waitcnt vmcnt(6)
	v_mov_b64_e32 v[68:69], v[230:231]
	v_pk_mul_f32 v[70:71], v[70:71], v[68:69] op_sel:[0,1] op_sel_hi:[0,0]
	v_pk_fma_f32 v[82:83], v[88:89], v[64:65], v[72:73] neg_lo:[0,0,1] neg_hi:[0,0,1]
	v_pk_fma_f32 v[64:65], v[88:89], v[64:65], v[72:73] op_sel_hi:[0,1,1]
	v_pk_fma_f32 v[72:73], v[80:81], v[68:69], v[70:71] op_sel_hi:[0,1,1] neg_lo:[0,0,1] neg_hi:[0,0,1]
	v_pk_fma_f32 v[68:69], v[80:81], v[68:69], v[70:71] op_sel_hi:[0,1,1]
	v_mov_b32_e32 v83, v65
	v_mov_b32_e32 v73, v69
	v_pk_mul_f32 v[64:65], v[82:83], s[20:21] op_sel_hi:[1,0]
	v_pk_mul_f32 v[68:69], v[72:73], s[20:21] op_sel_hi:[1,0]
	v_cvt_pk_bf16_f32 v64, v64, v65
	v_cvt_pk_bf16_f32 v65, v68, v69
	ds_write_b16 v128, v64 offset:6144
	ds_write_b16_d16_hi v141, v64 offset:6144
	ds_write_b16 v143, v65 offset:6144
	ds_write_b16_d16_hi v147, v65 offset:6144
	v_mov_b32_e32 v70, v75
	v_mov_b32_e32 v72, v91
	v_add_u32_e32 v82, 32, v146
	v_add_u32_e32 v88, 56, v146
	v_ashrrev_i32_e32 v83, 31, v82
	v_ashrrev_i32_e32 v89, 31, v88
	v_lshlrev_b64 v[100:101], 11, v[82:83]
	v_lshlrev_b64 v[106:107], 11, v[88:89]
	s_waitcnt vmcnt(5)
	v_mov_b64_e32 v[64:65], v[232:233]
	v_pk_mul_f32 v[74:75], v[74:75], v[64:65] op_sel:[0,1] op_sel_hi:[0,0]
	s_waitcnt vmcnt(4)
	v_mov_b64_e32 v[68:69], v[234:235]
	v_pk_mul_f32 v[70:71], v[70:71], v[68:69] op_sel:[0,1] op_sel_hi:[0,0]
	v_pk_fma_f32 v[80:81], v[90:91], v[64:65], v[74:75] neg_lo:[0,0,1] neg_hi:[0,0,1]
	v_pk_fma_f32 v[64:65], v[90:91], v[64:65], v[74:75] op_sel_hi:[0,1,1]
	v_pk_fma_f32 v[74:75], v[72:73], v[68:69], v[70:71] op_sel_hi:[0,1,1] neg_lo:[0,0,1] neg_hi:[0,0,1]
	v_pk_fma_f32 v[68:69], v[72:73], v[68:69], v[70:71] op_sel_hi:[0,1,1]
	v_mov_b32_e32 v81, v65
	v_mov_b32_e32 v75, v69
	v_pk_mul_f32 v[64:65], v[80:81], s[20:21] op_sel_hi:[1,0]
	v_pk_mul_f32 v[68:69], v[74:75], s[20:21] op_sel_hi:[1,0]
	v_cvt_pk_bf16_f32 v64, v64, v65
	v_cvt_pk_bf16_f32 v65, v68, v69
	ds_write_b16 v148, v64 offset:6144
	ds_write_b16_d16_hi v149, v64 offset:6144
	ds_write_b16 v112, v65 offset:6144
	ds_write_b16_d16_hi v113, v65 offset:6144
	v_mov_b32_e32 v70, v77
	v_mov_b32_e32 v72, v93
	v_add_u32_e32 v80, 24, v146
	v_ashrrev_i32_e32 v81, 31, v80
	v_lshlrev_b64 v[98:99], 11, v[80:81]
	s_waitcnt vmcnt(3)
	v_mov_b64_e32 v[64:65], v[236:237]
	v_pk_mul_f32 v[74:75], v[76:77], v[64:65] op_sel:[0,1] op_sel_hi:[0,0]
	s_waitcnt vmcnt(2)
	v_mov_b64_e32 v[68:69], v[238:239]
	v_pk_mul_f32 v[70:71], v[70:71], v[68:69] op_sel:[0,1] op_sel_hi:[0,0]
	v_pk_fma_f32 v[76:77], v[92:93], v[64:65], v[74:75] neg_lo:[0,0,1] neg_hi:[0,0,1]
	v_pk_fma_f32 v[64:65], v[92:93], v[64:65], v[74:75] op_sel_hi:[0,1,1]
	v_pk_fma_f32 v[74:75], v[72:73], v[68:69], v[70:71] op_sel_hi:[0,1,1] neg_lo:[0,0,1] neg_hi:[0,0,1]
	v_pk_fma_f32 v[68:69], v[72:73], v[68:69], v[70:71] op_sel_hi:[0,1,1]
	v_mov_b32_e32 v77, v65
	v_mov_b32_e32 v75, v69
	v_pk_mul_f32 v[64:65], v[76:77], s[20:21] op_sel_hi:[1,0]
	v_pk_mul_f32 v[68:69], v[74:75], s[20:21] op_sel_hi:[1,0]
	v_cvt_pk_bf16_f32 v64, v64, v65
	v_cvt_pk_bf16_f32 v65, v68, v69
	ds_write_b16 v128, v64 offset:7168
	ds_write_b16_d16_hi v141, v64 offset:7168
	ds_write_b16 v143, v65 offset:7168
	ds_write_b16_d16_hi v147, v65 offset:7168
	s_nop 0
	v_ashrrev_i32_e32 v141, 31, v140
	v_lshlrev_b64 v[72:73], 11, v[140:141]
	v_lshlrev_b32_e32 v69, 4, v211
	v_xor_b32_e32 v71, v146, v211
	v_ashrrev_i32_e32 v143, 31, v142
	v_lshl_add_u64 v[72:73], s[10:11], 0, v[72:73]
	v_and_b32_e32 v128, 0x70, v69
	v_lshlrev_b32_e32 v69, 4, v71
	v_lshl_add_u64 v[74:75], v[142:143], 1, v[72:73]
	v_ashrrev_i32_e32 v147, 31, v146
	v_add_u32_e32 v72, 8, v146
	v_add_u32_e32 v76, 16, v146
	v_and_b32_e32 v69, 0x70, v69
	v_lshl_add_u64 v[74:75], v[74:75], 0, v[128:129]
	v_lshlrev_b64 v[90:91], 11, v[146:147]
	v_ashrrev_i32_e32 v73, 31, v72
	v_ashrrev_i32_e32 v77, 31, v76
	v_add_u32_e32 v69, v192, v69
	v_mov_b32_e32 v68, v79
	v_lshl_add_u64 v[96:97], v[74:75], 0, v[90:91]
	v_lshlrev_b64 v[90:91], 11, v[72:73]
	v_lshlrev_b64 v[92:93], 11, v[76:77]
	v_lshl_add_u32 v77, v72, 7, v69
	v_mov_b32_e32 v70, v95
	v_lshl_add_u64 v[108:109], v[74:75], 0, v[90:91]
	v_lshl_add_u64 v[110:111], v[74:75], 0, v[92:93]
	v_lshl_add_u64 v[98:99], v[74:75], 0, v[98:99]
	v_lshl_add_u64 v[100:101], v[74:75], 0, v[100:101]
	v_lshl_add_u64 v[102:103], v[74:75], 0, v[102:103]
	v_lshl_add_u64 v[104:105], v[74:75], 0, v[104:105]
	v_lshl_add_u64 v[106:107], v[74:75], 0, v[106:107]
	v_lshl_add_u32 v71, v146, 7, v69
	v_lshl_add_u32 v76, v76, 7, v69
	v_lshl_add_u32 v80, v80, 7, v69
	v_lshl_add_u32 v81, v82, 7, v69
	v_lshl_add_u32 v84, v84, 7, v69
	v_lshl_add_u32 v89, v86, 7, v69
	v_lshl_add_u32 v92, v88, 7, v69
	s_waitcnt vmcnt(1)
	v_mov_b64_e32 v[64:65], v[240:241]
	v_pk_mul_f32 v[72:73], v[78:79], v[64:65] op_sel:[0,1] op_sel_hi:[0,0]
	s_waitcnt vmcnt(0)
	v_mov_b64_e32 v[66:67], v[244:245]
	v_pk_mul_f32 v[68:69], v[68:69], v[66:67] op_sel:[0,1] op_sel_hi:[0,0]
	v_pk_fma_f32 v[74:75], v[94:95], v[64:65], v[72:73] neg_lo:[0,0,1] neg_hi:[0,0,1]
	v_pk_fma_f32 v[64:65], v[94:95], v[64:65], v[72:73] op_sel_hi:[0,1,1]
	v_pk_fma_f32 v[72:73], v[70:71], v[66:67], v[68:69] op_sel_hi:[0,1,1] neg_lo:[0,0,1] neg_hi:[0,0,1]
	v_pk_fma_f32 v[66:67], v[70:71], v[66:67], v[68:69] op_sel_hi:[0,1,1]
	v_mov_b32_e32 v75, v65
	v_mov_b32_e32 v73, v67
	v_pk_mul_f32 v[64:65], v[74:75], s[20:21] op_sel_hi:[1,0]
	v_pk_mul_f32 v[66:67], v[72:73], s[20:21] op_sel_hi:[1,0]
	v_cvt_pk_bf16_f32 v64, v64, v65
	v_cvt_pk_bf16_f32 v65, v66, v67
	ds_write_b16 v148, v64 offset:7168
	ds_write_b16_d16_hi v149, v64 offset:7168
	ds_write_b16 v112, v65 offset:7168
	ds_write_b16_d16_hi v113, v65 offset:7168
	ds_read_b128 v[64:67], v71
	ds_read_b128 v[68:71], v77
	ds_read_b128 v[72:75], v76
	ds_read_b128 v[76:79], v80
	ds_read_b128 v[80:83], v81
	ds_read_b128 v[84:87], v84
	ds_read_b128 v[88:91], v89
	ds_read_b128 v[92:95], v92
	s_waitcnt lgkmcnt(7)
	global_store_dwordx4 v[96:97], v[64:67], off
	s_waitcnt lgkmcnt(6)
	global_store_dwordx4 v[108:109], v[68:71], off
	s_waitcnt lgkmcnt(5)
	global_store_dwordx4 v[110:111], v[72:75], off
	s_waitcnt lgkmcnt(4)
	global_store_dwordx4 v[98:99], v[76:79], off
	s_waitcnt lgkmcnt(3)
	global_store_dwordx4 v[100:101], v[80:83], off
	s_waitcnt lgkmcnt(2)
	global_store_dwordx4 v[102:103], v[84:87], off
	s_waitcnt lgkmcnt(1)
	global_store_dwordx4 v[104:105], v[88:91], off
	s_waitcnt lgkmcnt(0)
	global_store_dwordx4 v[106:107], v[92:95], off

.LBB0_240:
	s_or_b64 exec, exec, s[48:49]
	s_and_saveexec_b64 s[6:7], s[58:59]
	s_cbranch_execz .LBB0_159
	v_lshl_add_u32 v64, v101, 7, v155
	v_ashrrev_i32_e32 v65, 31, v64
	v_lshl_add_u64 v[64:65], v[64:65], 3, s[8:9]
	v_lshlrev_b32_e32 v128, 3, v100
	v_lshl_add_u64 v[64:65], v[64:65], 0, v[128:129]
	s_and_saveexec_b64 s[48:49], s[4:5]
	s_xor_b64 s[4:5], exec, s[48:49]
	s_cbranch_execz .LBB0_246
	s_and_b64 s[24:25], s[24:25], exec
	s_cselect_b32 s24, s82, 0xfffff800
	v_add_u32_e32 v66, s24, v99
	v_ashrrev_i32_e32 v66, 6, v66
	v_lshl_add_u32 v66, v210, 2, v66
	v_ashrrev_i32_e32 v67, 31, v66
	s_mov_b64 s[24:25], -1
	s_and_b64 vcc, exec, s[22:23]
	s_cbranch_vccz .LBB0_244
	v_mov_b32_e32 v68, v98
	s_mov_b32 s101, 0
	s_mov_b32 s100, 0x1000
	v_lshl_add_u64 v[246:247], v[64:65], 0, s[100:101]
	s_mov_b32 s100, 0x2000
	v_lshl_add_u64 v[250:251], v[64:65], 0, s[100:101]
	s_mov_b32 s100, 0x3000
	v_lshl_add_u64 v[252:253], v[64:65], 0, s[100:101]
	global_load_dwordx2 v[212:213], v[64:65], off
	global_load_dwordx2 v[214:215], v[64:65], off offset:256
	global_load_dwordx2 v[216:217], v[64:65], off offset:512
	global_load_dwordx2 v[218:219], v[64:65], off offset:768
	global_load_dwordx2 v[220:221], v[64:65], off offset:2048
	global_load_dwordx2 v[222:223], v[64:65], off offset:2304
	global_load_dwordx2 v[224:225], v[64:65], off offset:2560
	global_load_dwordx2 v[226:227], v[64:65], off offset:2816
	global_load_dwordx2 v[228:229], v[246:247], off
	global_load_dwordx2 v[230:231], v[246:247], off offset:256
	global_load_dwordx2 v[232:233], v[246:247], off offset:512
	global_load_dwordx2 v[234:235], v[246:247], off offset:768
	global_load_dwordx2 v[236:237], v[246:247], off offset:2048
	global_load_dwordx2 v[238:239], v[246:247], off offset:2304
	global_load_dwordx2 v[240:241], v[246:247], off offset:2560
	global_load_dwordx2 v[244:245], v[246:247], off offset:2816
	v_ashrrev_i32_e32 v73, 3, v68
	v_lshrrev_b32_e32 v69, 3, v68
	v_lshlrev_b32_e32 v76, 1, v68
	v_and_b32_e32 v82, -4, v73
	v_bfe_u32 v72, v68, 3, 2
	v_bfi_b32 v77, 3, v69, v73
	v_and_b32_e32 v83, 14, v76
	v_lshlrev_b32_e32 v76, 7, v82
	v_or_b32_e32 v78, 1, v82
	v_bitop3_b32 v79, v82, v72, 1 bitop3:0x36
	v_lshl_add_u32 v76, v77, 4, v76
	v_lshlrev_b32_e32 v77, 7, v78
	v_lshl_add_u32 v77, v79, 4, v77
	v_or_b32_e32 v76, v76, v83
	v_add_u32_e32 v90, v192, v76
	v_xad_u32 v91, v76, 64, v192
	v_or_b32_e32 v76, v77, v83
	v_add_u32_e32 v92, v192, v76
	v_xad_u32 v93, v76, 64, v192
	v_bitop3_b32 v69, v69, v73, 3 bitop3:0x4e
	v_bitop3_b32 v72, v82, v72, 2 bitop3:0x36
	v_lshlrev_b32_e32 v128, 7, v154
	s_mov_b64 s[24:25], 0
	s_waitcnt vmcnt(14)
	v_mov_b64_e32 v[70:71], v[212:213]
	v_mov_b64_e32 v[74:75], v[214:215]
	global_load_dwordx2 v[212:213], v[250:251], off
	global_load_dwordx2 v[214:215], v[250:251], off offset:256
	v_pk_mul_f32 v[76:77], v[32:33], v[70:71] op_sel:[0,1] op_sel_hi:[0,0]
	v_pk_mul_f32 v[78:79], v[32:33], v[74:75] op_sel:[1,1] op_sel_hi:[1,0]
	v_pk_fma_f32 v[80:81], v[48:49], v[70:71], v[76:77] neg_lo:[0,0,1] neg_hi:[0,0,1]
	v_pk_fma_f32 v[70:71], v[48:49], v[70:71], v[76:77] op_sel_hi:[0,1,1]
	v_pk_fma_f32 v[76:77], v[48:49], v[74:75], v[78:79] op_sel:[1,0,0] neg_lo:[0,0,1] neg_hi:[0,0,1]
	v_pk_fma_f32 v[74:75], v[48:49], v[74:75], v[78:79] op_sel:[1,0,0]
	v_cvt_pk_bf16_f32 v70, v80, v71
	v_cvt_pk_bf16_f32 v71, v76, v75
	ds_write_b16 v90, v70
	ds_write_b16_d16_hi v91, v70
	ds_write_b16 v92, v71
	ds_write_b16_d16_hi v93, v71
	v_or_b32_e32 v70, 3, v73
	v_or_b32_e32 v71, 2, v82
	v_lshlrev_b32_e32 v70, 7, v70
	v_lshlrev_b32_e32 v71, 7, v71
	v_lshl_add_u32 v69, v69, 4, v70
	v_lshl_add_u32 v70, v72, 4, v71
	v_mov_b32_e32 v78, v35
	v_or_b32_e32 v71, v69, v83
	v_or_b32_e32 v72, v70, v83
	v_mov_b32_e32 v80, v51
	v_add_u32_e32 v69, v192, v71
	v_xad_u32 v70, v71, 64, v192
	v_add_u32_e32 v71, v192, v72
	v_xad_u32 v72, v72, 64, v192
	v_lshlrev_b32_e32 v73, 6, v73
	s_waitcnt vmcnt(15)
	v_mov_b64_e32 v[74:75], v[216:217]
	global_load_dwordx2 v[216:217], v[250:251], off offset:512
	v_pk_mul_f32 v[82:83], v[34:35], v[74:75] op_sel:[0,1] op_sel_hi:[0,0]
	s_waitcnt vmcnt(15)
	v_mov_b64_e32 v[76:77], v[218:219]
	global_load_dwordx2 v[218:219], v[250:251], off offset:768
	v_pk_mul_f32 v[78:79], v[78:79], v[76:77] op_sel:[0,1] op_sel_hi:[0,0]
	v_pk_fma_f32 v[84:85], v[50:51], v[74:75], v[82:83] neg_lo:[0,0,1] neg_hi:[0,0,1]
	v_pk_fma_f32 v[74:75], v[50:51], v[74:75], v[82:83] op_sel_hi:[0,1,1]
	v_pk_fma_f32 v[82:83], v[80:81], v[76:77], v[78:79] op_sel_hi:[0,1,1] neg_lo:[0,0,1] neg_hi:[0,0,1]
	v_pk_fma_f32 v[76:77], v[80:81], v[76:77], v[78:79] op_sel_hi:[0,1,1]
	v_cvt_pk_bf16_f32 v74, v84, v75
	v_cvt_pk_bf16_f32 v75, v82, v77
	ds_write_b16 v71, v74
	ds_write_b16_d16_hi v72, v74
	ds_write_b16 v69, v75
	ds_write_b16_d16_hi v70, v75
	v_mov_b32_e32 v78, v37
	v_mov_b32_e32 v80, v53
	s_waitcnt vmcnt(15)
	v_mov_b64_e32 v[74:75], v[220:221]
	global_load_dwordx2 v[220:221], v[250:251], off offset:2048
	v_pk_mul_f32 v[82:83], v[36:37], v[74:75] op_sel:[0,1] op_sel_hi:[0,0]
	s_waitcnt vmcnt(15)
	v_mov_b64_e32 v[76:77], v[222:223]
	global_load_dwordx2 v[222:223], v[250:251], off offset:2304
	v_pk_mul_f32 v[78:79], v[78:79], v[76:77] op_sel:[0,1] op_sel_hi:[0,0]
	v_pk_fma_f32 v[84:85], v[52:53], v[74:75], v[82:83] neg_lo:[0,0,1] neg_hi:[0,0,1]
	v_pk_fma_f32 v[74:75], v[52:53], v[74:75], v[82:83] op_sel_hi:[0,1,1]
	v_pk_fma_f32 v[82:83], v[80:81], v[76:77], v[78:79] op_sel_hi:[0,1,1] neg_lo:[0,0,1] neg_hi:[0,0,1]
	v_pk_fma_f32 v[76:77], v[80:81], v[76:77], v[78:79] op_sel_hi:[0,1,1]
	v_cvt_pk_bf16_f32 v74, v84, v75
	v_cvt_pk_bf16_f32 v75, v82, v77
	ds_write_b16 v90, v74 offset:1024
	ds_write_b16_d16_hi v91, v74 offset:1024
	ds_write_b16 v92, v75 offset:1024
	ds_write_b16_d16_hi v93, v75 offset:1024
	v_mov_b32_e32 v78, v39
	v_mov_b32_e32 v80, v55
	v_add_co_u32_e32 v82, vcc, s83, v64
	s_waitcnt vmcnt(15)
	v_mov_b64_e32 v[74:75], v[224:225]
	global_load_dwordx2 v[224:225], v[250:251], off offset:2560
	v_pk_mul_f32 v[86:87], v[38:39], v[74:75] op_sel:[0,1] op_sel_hi:[0,0]
	s_waitcnt vmcnt(15)
	v_mov_b64_e32 v[76:77], v[226:227]
	global_load_dwordx2 v[226:227], v[250:251], off offset:2816
	v_pk_mul_f32 v[78:79], v[78:79], v[76:77] op_sel:[0,1] op_sel_hi:[0,0]
	v_pk_fma_f32 v[88:89], v[54:55], v[74:75], v[86:87] neg_lo:[0,0,1] neg_hi:[0,0,1]
	v_pk_fma_f32 v[74:75], v[54:55], v[74:75], v[86:87] op_sel_hi:[0,1,1]
	v_addc_co_u32_e32 v83, vcc, 0, v65, vcc
	v_pk_fma_f32 v[86:87], v[80:81], v[76:77], v[78:79] op_sel_hi:[0,1,1] neg_lo:[0,0,1] neg_hi:[0,0,1]
	v_pk_fma_f32 v[76:77], v[80:81], v[76:77], v[78:79] op_sel_hi:[0,1,1]
	v_cvt_pk_bf16_f32 v74, v88, v75
	v_add_co_u32_e32 v84, vcc, s51, v64
	v_cvt_pk_bf16_f32 v75, v86, v77
	ds_write_b16 v71, v74 offset:1024
	ds_write_b16_d16_hi v72, v74 offset:1024
	ds_write_b16 v69, v75 offset:1024
	ds_write_b16_d16_hi v70, v75 offset:1024
	v_addc_co_u32_e32 v85, vcc, 0, v65, vcc
	v_mov_b32_e32 v78, v41
	v_mov_b32_e32 v80, v57
	s_waitcnt vmcnt(15)
	v_mov_b64_e32 v[74:75], v[228:229]
	global_load_dwordx2 v[228:229], v[252:253], off
	v_pk_mul_f32 v[86:87], v[40:41], v[74:75] op_sel:[0,1] op_sel_hi:[0,0]
	s_waitcnt vmcnt(15)
	v_mov_b64_e32 v[76:77], v[230:231]
	global_load_dwordx2 v[230:231], v[252:253], off offset:256
	v_pk_mul_f32 v[78:79], v[78:79], v[76:77] op_sel:[0,1] op_sel_hi:[0,0]
	v_pk_fma_f32 v[88:89], v[56:57], v[74:75], v[86:87] neg_lo:[0,0,1] neg_hi:[0,0,1]
	v_pk_fma_f32 v[74:75], v[56:57], v[74:75], v[86:87] op_sel_hi:[0,1,1]
	v_pk_fma_f32 v[86:87], v[80:81], v[76:77], v[78:79] op_sel_hi:[0,1,1] neg_lo:[0,0,1] neg_hi:[0,0,1]
	v_pk_fma_f32 v[76:77], v[80:81], v[76:77], v[78:79] op_sel_hi:[0,1,1]
	v_cvt_pk_bf16_f32 v74, v88, v75
	v_cvt_pk_bf16_f32 v75, v86, v77
	ds_write_b16 v90, v74 offset:2048
	ds_write_b16_d16_hi v91, v74 offset:2048
	ds_write_b16 v92, v75 offset:2048
	ds_write_b16_d16_hi v93, v75 offset:2048
	v_mov_b32_e32 v78, v43
	v_mov_b32_e32 v80, v59
	s_waitcnt vmcnt(15)
	v_mov_b64_e32 v[74:75], v[232:233]
	global_load_dwordx2 v[232:233], v[252:253], off offset:512
	v_pk_mul_f32 v[86:87], v[42:43], v[74:75] op_sel:[0,1] op_sel_hi:[0,0]
	s_waitcnt vmcnt(15)
	v_mov_b64_e32 v[76:77], v[234:235]
	global_load_dwordx2 v[234:235], v[252:253], off offset:768
	v_pk_mul_f32 v[78:79], v[78:79], v[76:77] op_sel:[0,1] op_sel_hi:[0,0]
	v_pk_fma_f32 v[88:89], v[58:59], v[74:75], v[86:87] neg_lo:[0,0,1] neg_hi:[0,0,1]
	v_pk_fma_f32 v[74:75], v[58:59], v[74:75], v[86:87] op_sel_hi:[0,1,1]
	v_pk_fma_f32 v[86:87], v[80:81], v[76:77], v[78:79] op_sel_hi:[0,1,1] neg_lo:[0,0,1] neg_hi:[0,0,1]
	v_pk_fma_f32 v[76:77], v[80:81], v[76:77], v[78:79] op_sel_hi:[0,1,1]
	v_cvt_pk_bf16_f32 v74, v88, v75
	v_cvt_pk_bf16_f32 v75, v86, v77
	ds_write_b16 v71, v74 offset:2048
	ds_write_b16_d16_hi v72, v74 offset:2048
	ds_write_b16 v69, v75 offset:2048
	ds_write_b16_d16_hi v70, v75 offset:2048
	v_mov_b32_e32 v78, v45
	v_mov_b32_e32 v80, v61
	s_waitcnt vmcnt(15)
	v_mov_b64_e32 v[74:75], v[236:237]
	global_load_dwordx2 v[236:237], v[252:253], off offset:2048
	v_pk_mul_f32 v[86:87], v[44:45], v[74:75] op_sel:[0,1] op_sel_hi:[0,0]
	s_waitcnt vmcnt(15)
	v_mov_b64_e32 v[76:77], v[238:239]
	global_load_dwordx2 v[238:239], v[252:253], off offset:2304
	v_pk_mul_f32 v[78:79], v[78:79], v[76:77] op_sel:[0,1] op_sel_hi:[0,0]
	v_pk_fma_f32 v[88:89], v[60:61], v[74:75], v[86:87] neg_lo:[0,0,1] neg_hi:[0,0,1]
	v_pk_fma_f32 v[74:75], v[60:61], v[74:75], v[86:87] op_sel_hi:[0,1,1]
	v_pk_fma_f32 v[86:87], v[80:81], v[76:77], v[78:79] op_sel_hi:[0,1,1] neg_lo:[0,0,1] neg_hi:[0,0,1]
	v_pk_fma_f32 v[76:77], v[80:81], v[76:77], v[78:79] op_sel_hi:[0,1,1]
	v_cvt_pk_bf16_f32 v74, v88, v75
	v_cvt_pk_bf16_f32 v75, v86, v77
	ds_write_b16 v90, v74 offset:3072
	ds_write_b16_d16_hi v91, v74 offset:3072
	ds_write_b16 v92, v75 offset:3072
	ds_write_b16_d16_hi v93, v75 offset:3072
	v_mov_b32_e32 v78, v47
	v_mov_b32_e32 v80, v63
	s_waitcnt vmcnt(15)
	v_mov_b64_e32 v[74:75], v[240:241]
	global_load_dwordx2 v[240:241], v[252:253], off offset:2560
	v_pk_mul_f32 v[82:83], v[46:47], v[74:75] op_sel:[0,1] op_sel_hi:[0,0]
	s_waitcnt vmcnt(15)
	v_mov_b64_e32 v[76:77], v[244:245]
	global_load_dwordx2 v[244:245], v[252:253], off offset:2816
	v_pk_mul_f32 v[78:79], v[78:79], v[76:77] op_sel:[0,1] op_sel_hi:[0,0]
	v_pk_fma_f32 v[86:87], v[62:63], v[74:75], v[82:83] neg_lo:[0,0,1] neg_hi:[0,0,1]
	v_pk_fma_f32 v[74:75], v[62:63], v[74:75], v[82:83] op_sel_hi:[0,1,1]
	v_pk_fma_f32 v[82:83], v[80:81], v[76:77], v[78:79] op_sel_hi:[0,1,1] neg_lo:[0,0,1] neg_hi:[0,0,1]
	v_pk_fma_f32 v[76:77], v[80:81], v[76:77], v[78:79] op_sel_hi:[0,1,1]
	v_cvt_pk_bf16_f32 v74, v86, v75
	v_cvt_pk_bf16_f32 v75, v82, v77
	ds_write_b16 v71, v74 offset:3072
	ds_write_b16_d16_hi v72, v74 offset:3072
	ds_write_b16 v69, v75 offset:3072
	ds_write_b16_d16_hi v70, v75 offset:3072
	s_waitcnt vmcnt(15)
	v_mov_b64_e32 v[74:75], v[212:213]
	v_pk_mul_f32 v[78:79], v[0:1], v[74:75] op_sel:[0,1] op_sel_hi:[0,0]
	s_waitcnt vmcnt(14)
	v_mov_b64_e32 v[76:77], v[214:215]
	v_pk_mul_f32 v[80:81], v[0:1], v[76:77] op_sel:[1,1] op_sel_hi:[1,0]
	v_pk_fma_f32 v[82:83], v[16:17], v[74:75], v[78:79] neg_lo:[0,0,1] neg_hi:[0,0,1]
	v_pk_fma_f32 v[74:75], v[16:17], v[74:75], v[78:79] op_sel_hi:[0,1,1]
	v_pk_fma_f32 v[78:79], v[16:17], v[76:77], v[80:81] op_sel:[1,0,0] neg_lo:[0,0,1] neg_hi:[0,0,1]
	v_pk_fma_f32 v[76:77], v[16:17], v[76:77], v[80:81] op_sel:[1,0,0]
	v_cvt_pk_bf16_f32 v74, v82, v75
	v_cvt_pk_bf16_f32 v75, v78, v77
	ds_write_b16 v90, v74 offset:4096
	ds_write_b16_d16_hi v91, v74 offset:4096
	ds_write_b16 v92, v75 offset:4096
	ds_write_b16_d16_hi v93, v75 offset:4096
	v_mov_b32_e32 v78, v3
	v_mov_b32_e32 v80, v19
	s_waitcnt vmcnt(13)
	v_mov_b64_e32 v[74:75], v[216:217]
	v_pk_mul_f32 v[82:83], v[2:3], v[74:75] op_sel:[0,1] op_sel_hi:[0,0]
	s_waitcnt vmcnt(12)
	v_mov_b64_e32 v[76:77], v[218:219]
	v_pk_mul_f32 v[78:79], v[78:79], v[76:77] op_sel:[0,1] op_sel_hi:[0,0]
	v_pk_fma_f32 v[86:87], v[18:19], v[74:75], v[82:83] neg_lo:[0,0,1] neg_hi:[0,0,1]
	v_pk_fma_f32 v[74:75], v[18:19], v[74:75], v[82:83] op_sel_hi:[0,1,1]
	v_pk_fma_f32 v[82:83], v[80:81], v[76:77], v[78:79] op_sel_hi:[0,1,1] neg_lo:[0,0,1] neg_hi:[0,0,1]
	v_pk_fma_f32 v[76:77], v[80:81], v[76:77], v[78:79] op_sel_hi:[0,1,1]
	v_cvt_pk_bf16_f32 v74, v86, v75
	v_cvt_pk_bf16_f32 v75, v82, v77
	ds_write_b16 v71, v74 offset:4096
	ds_write_b16_d16_hi v72, v74 offset:4096
	ds_write_b16 v69, v75 offset:4096
	ds_write_b16_d16_hi v70, v75 offset:4096
	v_mov_b32_e32 v78, v5
	v_mov_b32_e32 v80, v21
	s_waitcnt vmcnt(11)
	v_mov_b64_e32 v[74:75], v[220:221]
	v_pk_mul_f32 v[82:83], v[4:5], v[74:75] op_sel:[0,1] op_sel_hi:[0,0]
	s_waitcnt vmcnt(10)
	v_mov_b64_e32 v[76:77], v[222:223]
	v_pk_mul_f32 v[78:79], v[78:79], v[76:77] op_sel:[0,1] op_sel_hi:[0,0]
	v_pk_fma_f32 v[86:87], v[20:21], v[74:75], v[82:83] neg_lo:[0,0,1] neg_hi:[0,0,1]
	v_pk_fma_f32 v[74:75], v[20:21], v[74:75], v[82:83] op_sel_hi:[0,1,1]
	v_pk_fma_f32 v[82:83], v[80:81], v[76:77], v[78:79] op_sel_hi:[0,1,1] neg_lo:[0,0,1] neg_hi:[0,0,1]
	v_pk_fma_f32 v[76:77], v[80:81], v[76:77], v[78:79] op_sel_hi:[0,1,1]
	v_cvt_pk_bf16_f32 v74, v86, v75
	v_cvt_pk_bf16_f32 v75, v82, v77
	ds_write_b16 v90, v74 offset:5120
	ds_write_b16_d16_hi v91, v74 offset:5120
	ds_write_b16 v92, v75 offset:5120
	ds_write_b16_d16_hi v93, v75 offset:5120
	v_mov_b32_e32 v78, v7
	v_mov_b32_e32 v80, v23
	v_add_co_u32_e32 v82, vcc, s90, v64
	s_waitcnt vmcnt(9)
	v_mov_b64_e32 v[74:75], v[224:225]
	v_pk_mul_f32 v[84:85], v[6:7], v[74:75] op_sel:[0,1] op_sel_hi:[0,0]
	s_waitcnt vmcnt(8)
	v_mov_b64_e32 v[76:77], v[226:227]
	v_pk_mul_f32 v[78:79], v[78:79], v[76:77] op_sel:[0,1] op_sel_hi:[0,0]
	v_pk_fma_f32 v[86:87], v[22:23], v[74:75], v[84:85] neg_lo:[0,0,1] neg_hi:[0,0,1]
	v_pk_fma_f32 v[74:75], v[22:23], v[74:75], v[84:85] op_sel_hi:[0,1,1]
	v_pk_fma_f32 v[84:85], v[80:81], v[76:77], v[78:79] op_sel_hi:[0,1,1] neg_lo:[0,0,1] neg_hi:[0,0,1]
	v_pk_fma_f32 v[76:77], v[80:81], v[76:77], v[78:79] op_sel_hi:[0,1,1]
	v_cvt_pk_bf16_f32 v74, v86, v75
	v_cvt_pk_bf16_f32 v75, v84, v77
	ds_write_b16 v71, v74 offset:5120
	ds_write_b16_d16_hi v72, v74 offset:5120
	ds_write_b16 v69, v75 offset:5120
	ds_write_b16_d16_hi v70, v75 offset:5120
	v_addc_co_u32_e32 v83, vcc, 0, v65, vcc
	v_mov_b32_e32 v78, v9
	v_mov_b32_e32 v80, v25
	s_waitcnt vmcnt(7)
	v_mov_b64_e32 v[74:75], v[228:229]
	v_pk_mul_f32 v[84:85], v[8:9], v[74:75] op_sel:[0,1] op_sel_hi:[0,0]
	s_waitcnt vmcnt(6)
	v_mov_b64_e32 v[76:77], v[230:231]
	v_pk_mul_f32 v[78:79], v[78:79], v[76:77] op_sel:[0,1] op_sel_hi:[0,0]
	v_pk_fma_f32 v[86:87], v[24:25], v[74:75], v[84:85] neg_lo:[0,0,1] neg_hi:[0,0,1]
	v_pk_fma_f32 v[74:75], v[24:25], v[74:75], v[84:85] op_sel_hi:[0,1,1]
	v_pk_fma_f32 v[84:85], v[80:81], v[76:77], v[78:79] op_sel_hi:[0,1,1] neg_lo:[0,0,1] neg_hi:[0,0,1]
	v_pk_fma_f32 v[76:77], v[80:81], v[76:77], v[78:79] op_sel_hi:[0,1,1]
	v_cvt_pk_bf16_f32 v74, v86, v75
	v_cvt_pk_bf16_f32 v75, v84, v77
	ds_write_b16 v90, v74 offset:6144
	ds_write_b16_d16_hi v91, v74 offset:6144
	ds_write_b16 v92, v75 offset:6144
	ds_write_b16_d16_hi v93, v75 offset:6144
	v_mov_b32_e32 v78, v11
	v_mov_b32_e32 v80, v27
	s_waitcnt vmcnt(5)
	v_mov_b64_e32 v[74:75], v[232:233]
	v_pk_mul_f32 v[84:85], v[10:11], v[74:75] op_sel:[0,1] op_sel_hi:[0,0]
	s_waitcnt vmcnt(4)
	v_mov_b64_e32 v[76:77], v[234:235]
	v_pk_mul_f32 v[78:79], v[78:79], v[76:77] op_sel:[0,1] op_sel_hi:[0,0]
	v_pk_fma_f32 v[86:87], v[26:27], v[74:75], v[84:85] neg_lo:[0,0,1] neg_hi:[0,0,1]
	v_pk_fma_f32 v[74:75], v[26:27], v[74:75], v[84:85] op_sel_hi:[0,1,1]
	v_pk_fma_f32 v[84:85], v[80:81], v[76:77], v[78:79] op_sel_hi:[0,1,1] neg_lo:[0,0,1] neg_hi:[0,0,1]
	v_pk_fma_f32 v[76:77], v[80:81], v[76:77], v[78:79] op_sel_hi:[0,1,1]
	v_cvt_pk_bf16_f32 v74, v86, v75
	v_cvt_pk_bf16_f32 v75, v84, v77
	ds_write_b16 v71, v74 offset:6144
	ds_write_b16_d16_hi v72, v74 offset:6144
	ds_write_b16 v69, v75 offset:6144
	ds_write_b16_d16_hi v70, v75 offset:6144
	v_mov_b32_e32 v78, v13
	v_mov_b32_e32 v80, v29
	s_waitcnt vmcnt(3)
	v_mov_b64_e32 v[74:75], v[236:237]
	v_pk_mul_f32 v[84:85], v[12:13], v[74:75] op_sel:[0,1] op_sel_hi:[0,0]
	s_waitcnt vmcnt(2)
	v_mov_b64_e32 v[76:77], v[238:239]
	v_pk_mul_f32 v[78:79], v[78:79], v[76:77] op_sel:[0,1] op_sel_hi:[0,0]
	v_pk_fma_f32 v[86:87], v[28:29], v[74:75], v[84:85] neg_lo:[0,0,1] neg_hi:[0,0,1]
	v_pk_fma_f32 v[74:75], v[28:29], v[74:75], v[84:85] op_sel_hi:[0,1,1]
	v_pk_fma_f32 v[84:85], v[80:81], v[76:77], v[78:79] op_sel_hi:[0,1,1] neg_lo:[0,0,1] neg_hi:[0,0,1]
	v_pk_fma_f32 v[76:77], v[80:81], v[76:77], v[78:79] op_sel_hi:[0,1,1]
	v_cvt_pk_bf16_f32 v74, v86, v75
	v_cvt_pk_bf16_f32 v75, v84, v77
	ds_write_b16 v90, v74 offset:7168
	ds_write_b16_d16_hi v91, v74 offset:7168
	ds_write_b16 v92, v75 offset:7168
	ds_write_b16_d16_hi v93, v75 offset:7168
	v_lshl_add_u32 v81, v68, 7, v192
	v_and_b32_e32 v83, 15, v68
	v_lshlrev_b32_e32 v68, 4, v68
	v_and_b32_e32 v68, 0x70, v68
	v_and_or_b32 v84, v73, s91, v83
	v_or_b32_e32 v73, v73, v83
	v_lshlrev_b64 v[78:79], 21, v[66:67]
	v_add_u32_e32 v94, v81, v68
	v_xad_u32 v95, v68, 16, v81
	v_xad_u32 v99, v68, 32, v81
	v_xad_u32 v100, v68, 48, v81
	v_xad_u32 v101, v68, 64, v81
	v_xad_u32 v102, v68, s76, v81
	v_xad_u32 v103, v68, s77, v81
	v_xad_u32 v112, v68, s21, v81
	v_lshlrev_b32_e32 v68, 3, v73
	v_lshl_add_u64 v[78:79], s[30:31], 0, v[78:79]
	v_lshlrev_b32_e32 v84, 3, v84
	v_or_b32_e32 v86, 0x200, v68
	v_or_b32_e32 v88, 0x280, v68
	v_or_b32_e32 v90, 0x300, v68
	v_or_b32_e32 v92, 0x380, v68
	v_lshl_add_u64 v[78:79], v[78:79], 0, v[128:129]
	v_ashrrev_i32_e32 v85, 31, v84
	v_ashrrev_i32_e32 v87, 31, v86
	v_ashrrev_i32_e32 v89, 31, v88
	v_ashrrev_i32_e32 v91, 31, v90
	v_ashrrev_i32_e32 v93, 31, v92
	v_mov_b32_e32 v80, v15
	v_lshl_add_u64 v[96:97], v[84:85], 1, v[78:79]
	v_lshl_add_u64 v[104:105], v[86:87], 1, v[78:79]
	v_lshl_add_u64 v[106:107], v[88:89], 1, v[78:79]
	v_lshl_add_u64 v[108:109], v[90:91], 1, v[78:79]
	v_lshl_add_u64 v[110:111], v[92:93], 1, v[78:79]
	v_mov_b32_e32 v82, v31
	s_waitcnt vmcnt(1)
	v_mov_b64_e32 v[74:75], v[240:241]
	v_pk_mul_f32 v[78:79], v[14:15], v[74:75] op_sel:[0,1] op_sel_hi:[0,0]
	s_waitcnt vmcnt(0)
	v_mov_b64_e32 v[76:77], v[244:245]
	v_pk_mul_f32 v[80:81], v[80:81], v[76:77] op_sel:[0,1] op_sel_hi:[0,0]
	v_pk_fma_f32 v[84:85], v[30:31], v[74:75], v[78:79] neg_lo:[0,0,1] neg_hi:[0,0,1]
	v_pk_fma_f32 v[74:75], v[30:31], v[74:75], v[78:79] op_sel_hi:[0,1,1]
	v_pk_fma_f32 v[78:79], v[82:83], v[76:77], v[80:81] op_sel_hi:[0,1,1] neg_lo:[0,0,1] neg_hi:[0,0,1]
	v_pk_fma_f32 v[76:77], v[82:83], v[76:77], v[80:81] op_sel_hi:[0,1,1]
	v_cvt_pk_bf16_f32 v68, v84, v75
	v_cvt_pk_bf16_f32 v73, v78, v77
	ds_write_b16 v71, v68 offset:7168
	ds_write_b16_d16_hi v72, v68 offset:7168
	ds_write_b16 v69, v73 offset:7168
	ds_write_b16_d16_hi v70, v73 offset:7168
	ds_read_b128 v[68:71], v94
	ds_read_b128 v[72:75], v95
	ds_read_b128 v[76:79], v99
	ds_read_b128 v[80:83], v100
	ds_read_b128 v[84:87], v101
	ds_read_b128 v[88:91], v102
	ds_read_b128 v[92:95], v103
	ds_read_b128 v[100:103], v112
	s_waitcnt lgkmcnt(7)
	global_store_dwordx4 v[96:97], v[68:71], off
	s_waitcnt lgkmcnt(6)
	global_store_dwordx4 v[96:97], v[72:75], off offset:256
	s_waitcnt lgkmcnt(5)
	global_store_dwordx4 v[96:97], v[76:79], off offset:512
	s_waitcnt lgkmcnt(4)
	global_store_dwordx4 v[96:97], v[80:83], off offset:768
	s_waitcnt lgkmcnt(3)
	global_store_dwordx4 v[104:105], v[84:87], off
	s_waitcnt lgkmcnt(2)
	global_store_dwordx4 v[106:107], v[88:91], off
	s_waitcnt lgkmcnt(1)
	global_store_dwordx4 v[108:109], v[92:95], off
	s_waitcnt lgkmcnt(0)
	global_store_dwordx4 v[110:111], v[100:103], off
.LBB0_244:
	s_andn2_b64 vcc, exec, s[24:25]
	s_cbranch_vccnz .LBB0_246
	s_mov_b32 s101, 0
	s_mov_b32 s100, 0x1000
	v_lshl_add_u64 v[246:247], v[64:65], 0, s[100:101]
	s_mov_b32 s100, 0x2000
	v_lshl_add_u64 v[250:251], v[64:65], 0, s[100:101]
	s_mov_b32 s100, 0x3000
	v_lshl_add_u64 v[252:253], v[64:65], 0, s[100:101]
	global_load_dwordx2 v[212:213], v[64:65], off
	global_load_dwordx2 v[214:215], v[64:65], off offset:256
	global_load_dwordx2 v[216:217], v[64:65], off offset:512
	global_load_dwordx2 v[218:219], v[64:65], off offset:768
	global_load_dwordx2 v[220:221], v[64:65], off offset:2048
	global_load_dwordx2 v[222:223], v[64:65], off offset:2304
	global_load_dwordx2 v[224:225], v[64:65], off offset:2560
	global_load_dwordx2 v[226:227], v[64:65], off offset:2816
	global_load_dwordx2 v[228:229], v[246:247], off
	global_load_dwordx2 v[230:231], v[246:247], off offset:256
	global_load_dwordx2 v[232:233], v[246:247], off offset:512
	global_load_dwordx2 v[234:235], v[246:247], off offset:768
	global_load_dwordx2 v[236:237], v[246:247], off offset:2048
	global_load_dwordx2 v[238:239], v[246:247], off offset:2304
	global_load_dwordx2 v[240:241], v[246:247], off offset:2560
	global_load_dwordx2 v[244:245], v[246:247], off offset:2816
	v_ashrrev_i32_e32 v76, 3, v98
	v_lshrrev_b32_e32 v77, 3, v98
	v_lshlrev_b32_e32 v72, 1, v98
	v_and_b32_e32 v79, -4, v76
	v_bfe_u32 v78, v98, 3, 2
	v_bfi_b32 v73, 3, v77, v76
	v_and_b32_e32 v80, 14, v72
	v_lshlrev_b32_e32 v72, 7, v79
	v_or_b32_e32 v74, 1, v79
	v_bitop3_b32 v75, v79, v78, 1 bitop3:0x36
	v_lshl_add_u32 v72, v73, 4, v72
	v_lshlrev_b32_e32 v73, 7, v74
	v_lshl_add_u32 v73, v75, 4, v73
	v_or_b32_e32 v72, v72, v80
	v_add_u32_e32 v81, v192, v72
	v_xad_u32 v82, v72, 64, v192
	v_or_b32_e32 v72, v73, v80
	v_add_u32_e32 v83, v192, v72
	v_xad_u32 v84, v72, 64, v192
	v_lshlrev_b32_e32 v128, 6, v154
	s_waitcnt vmcnt(14)
	v_mov_b64_e32 v[68:69], v[212:213]
	v_mov_b64_e32 v[70:71], v[214:215]
	global_load_dwordx2 v[212:213], v[250:251], off
	global_load_dwordx2 v[214:215], v[250:251], off offset:256
	v_pk_mul_f32 v[72:73], v[32:33], v[68:69] op_sel:[0,1] op_sel_hi:[0,0]
	v_pk_mul_f32 v[32:33], v[32:33], v[70:71] op_sel:[1,1] op_sel_hi:[1,0]
	v_pk_fma_f32 v[74:75], v[48:49], v[68:69], v[72:73] neg_lo:[0,0,1] neg_hi:[0,0,1]
	v_pk_fma_f32 v[68:69], v[48:49], v[68:69], v[72:73] op_sel_hi:[0,1,1]
	v_pk_fma_f32 v[72:73], v[48:49], v[70:71], v[32:33] op_sel:[1,0,0] neg_lo:[0,0,1] neg_hi:[0,0,1]
	v_pk_fma_f32 v[32:33], v[48:49], v[70:71], v[32:33] op_sel:[1,0,0]
	v_or_b32_e32 v48, 2, v79
	v_cvt_pk_bf16_f32 v32, v74, v69
	v_cvt_pk_bf16_f32 v33, v72, v33
	ds_write_b16 v81, v32
	ds_write_b16_d16_hi v82, v32
	ds_write_b16 v83, v33
	ds_write_b16_d16_hi v84, v33
	v_or_b32_e32 v32, 3, v76
	v_bitop3_b32 v33, v77, v76, 3 bitop3:0x4e
	v_bitop3_b32 v49, v79, v78, 2 bitop3:0x36
	v_lshlrev_b32_e32 v32, 7, v32
	v_lshlrev_b32_e32 v48, 7, v48
	v_mov_b32_e32 v72, v35
	v_lshl_add_u32 v32, v33, 4, v32
	v_lshl_add_u32 v33, v49, 4, v48
	v_mov_b32_e32 v74, v51
	v_or_b32_e32 v48, v32, v80
	v_or_b32_e32 v49, v33, v80
	v_add_u32_e32 v32, v192, v48
	v_xad_u32 v33, v48, 64, v192
	v_add_u32_e32 v48, v192, v49
	v_xad_u32 v49, v49, 64, v192
	s_waitcnt vmcnt(15)
	v_mov_b64_e32 v[68:69], v[216:217]
	global_load_dwordx2 v[216:217], v[250:251], off offset:512
	v_pk_mul_f32 v[34:35], v[34:35], v[68:69] op_sel:[0,1] op_sel_hi:[0,0]
	s_waitcnt vmcnt(15)
	v_mov_b64_e32 v[70:71], v[218:219]
	global_load_dwordx2 v[218:219], v[250:251], off offset:768
	v_pk_mul_f32 v[72:73], v[72:73], v[70:71] op_sel:[0,1] op_sel_hi:[0,0]
	v_pk_fma_f32 v[76:77], v[50:51], v[68:69], v[34:35] neg_lo:[0,0,1] neg_hi:[0,0,1]
	v_pk_fma_f32 v[34:35], v[50:51], v[68:69], v[34:35] op_sel_hi:[0,1,1]
	v_pk_fma_f32 v[50:51], v[74:75], v[70:71], v[72:73] op_sel_hi:[0,1,1] neg_lo:[0,0,1] neg_hi:[0,0,1]
	v_pk_fma_f32 v[68:69], v[74:75], v[70:71], v[72:73] op_sel_hi:[0,1,1]
	v_cvt_pk_bf16_f32 v34, v76, v35
	v_cvt_pk_bf16_f32 v35, v50, v69
	ds_write_b16 v48, v34
	ds_write_b16_d16_hi v49, v34
	ds_write_b16 v32, v35
	ds_write_b16_d16_hi v33, v35
	v_mov_b32_e32 v68, v37
	v_mov_b32_e32 v70, v53
	s_waitcnt vmcnt(15)
	v_mov_b64_e32 v[34:35], v[220:221]
	global_load_dwordx2 v[220:221], v[250:251], off offset:2048
	v_pk_mul_f32 v[36:37], v[36:37], v[34:35] op_sel:[0,1] op_sel_hi:[0,0]
	s_waitcnt vmcnt(15)
	v_mov_b64_e32 v[50:51], v[222:223]
	global_load_dwordx2 v[222:223], v[250:251], off offset:2304
	v_pk_mul_f32 v[68:69], v[68:69], v[50:51] op_sel:[0,1] op_sel_hi:[0,0]
	v_pk_fma_f32 v[72:73], v[52:53], v[34:35], v[36:37] neg_lo:[0,0,1] neg_hi:[0,0,1]
	v_pk_fma_f32 v[34:35], v[52:53], v[34:35], v[36:37] op_sel_hi:[0,1,1]
	v_pk_fma_f32 v[36:37], v[70:71], v[50:51], v[68:69] op_sel_hi:[0,1,1] neg_lo:[0,0,1] neg_hi:[0,0,1]
	v_pk_fma_f32 v[50:51], v[70:71], v[50:51], v[68:69] op_sel_hi:[0,1,1]
	v_cvt_pk_bf16_f32 v34, v72, v35
	v_cvt_pk_bf16_f32 v35, v36, v51
	ds_write_b16 v81, v34 offset:1024
	ds_write_b16_d16_hi v82, v34 offset:1024
	ds_write_b16 v83, v35 offset:1024
	ds_write_b16_d16_hi v84, v35 offset:1024
	v_mov_b32_e32 v50, v39
	v_mov_b32_e32 v52, v55
	v_add_co_u32_e32 v68, vcc, s83, v64
	s_waitcnt vmcnt(15)
	v_mov_b64_e32 v[34:35], v[224:225]
	global_load_dwordx2 v[224:225], v[250:251], off offset:2560
	v_pk_mul_f32 v[38:39], v[38:39], v[34:35] op_sel:[0,1] op_sel_hi:[0,0]
	s_waitcnt vmcnt(15)
	v_mov_b64_e32 v[36:37], v[226:227]
	global_load_dwordx2 v[226:227], v[250:251], off offset:2816
	v_pk_mul_f32 v[50:51], v[50:51], v[36:37] op_sel:[0,1] op_sel_hi:[0,0]
	v_pk_fma_f32 v[72:73], v[54:55], v[34:35], v[38:39] neg_lo:[0,0,1] neg_hi:[0,0,1]
	v_pk_fma_f32 v[34:35], v[54:55], v[34:35], v[38:39] op_sel_hi:[0,1,1]
	v_addc_co_u32_e32 v69, vcc, 0, v65, vcc
	v_pk_fma_f32 v[38:39], v[52:53], v[36:37], v[50:51] op_sel_hi:[0,1,1] neg_lo:[0,0,1] neg_hi:[0,0,1]
	v_pk_fma_f32 v[36:37], v[52:53], v[36:37], v[50:51] op_sel_hi:[0,1,1]
	v_cvt_pk_bf16_f32 v34, v72, v35
	v_add_co_u32_e32 v70, vcc, s51, v64
	v_cvt_pk_bf16_f32 v35, v38, v37
	ds_write_b16 v48, v34 offset:1024
	ds_write_b16_d16_hi v49, v34 offset:1024
	ds_write_b16 v32, v35 offset:1024
	ds_write_b16_d16_hi v33, v35 offset:1024
	v_addc_co_u32_e32 v71, vcc, 0, v65, vcc
	v_mov_b32_e32 v38, v41
	v_mov_b32_e32 v50, v57
	s_waitcnt vmcnt(15)
	v_mov_b64_e32 v[34:35], v[228:229]
	global_load_dwordx2 v[228:229], v[252:253], off
	v_pk_mul_f32 v[40:41], v[40:41], v[34:35] op_sel:[0,1] op_sel_hi:[0,0]
	s_waitcnt vmcnt(15)
	v_mov_b64_e32 v[36:37], v[230:231]
	global_load_dwordx2 v[230:231], v[252:253], off offset:256
	v_pk_mul_f32 v[38:39], v[38:39], v[36:37] op_sel:[0,1] op_sel_hi:[0,0]
	v_pk_fma_f32 v[52:53], v[56:57], v[34:35], v[40:41] neg_lo:[0,0,1] neg_hi:[0,0,1]
	v_pk_fma_f32 v[34:35], v[56:57], v[34:35], v[40:41] op_sel_hi:[0,1,1]
	v_pk_fma_f32 v[40:41], v[50:51], v[36:37], v[38:39] op_sel_hi:[0,1,1] neg_lo:[0,0,1] neg_hi:[0,0,1]
	v_pk_fma_f32 v[36:37], v[50:51], v[36:37], v[38:39] op_sel_hi:[0,1,1]
	v_cvt_pk_bf16_f32 v34, v52, v35
	v_cvt_pk_bf16_f32 v35, v40, v37
	ds_write_b16 v81, v34 offset:2048
	ds_write_b16_d16_hi v82, v34 offset:2048
	ds_write_b16 v83, v35 offset:2048
	ds_write_b16_d16_hi v84, v35 offset:2048
	v_mov_b32_e32 v38, v43
	v_mov_b32_e32 v40, v59
	s_waitcnt vmcnt(15)
	v_mov_b64_e32 v[34:35], v[232:233]
	global_load_dwordx2 v[232:233], v[252:253], off offset:512
	v_pk_mul_f32 v[42:43], v[42:43], v[34:35] op_sel:[0,1] op_sel_hi:[0,0]
	s_waitcnt vmcnt(15)
	v_mov_b64_e32 v[36:37], v[234:235]
	global_load_dwordx2 v[234:235], v[252:253], off offset:768
	v_pk_mul_f32 v[38:39], v[38:39], v[36:37] op_sel:[0,1] op_sel_hi:[0,0]
	v_pk_fma_f32 v[50:51], v[58:59], v[34:35], v[42:43] neg_lo:[0,0,1] neg_hi:[0,0,1]
	v_pk_fma_f32 v[34:35], v[58:59], v[34:35], v[42:43] op_sel_hi:[0,1,1]
	v_pk_fma_f32 v[42:43], v[40:41], v[36:37], v[38:39] op_sel_hi:[0,1,1] neg_lo:[0,0,1] neg_hi:[0,0,1]
	v_pk_fma_f32 v[36:37], v[40:41], v[36:37], v[38:39] op_sel_hi:[0,1,1]
	v_cvt_pk_bf16_f32 v34, v50, v35
	v_cvt_pk_bf16_f32 v35, v42, v37
	ds_write_b16 v48, v34 offset:2048
	ds_write_b16_d16_hi v49, v34 offset:2048
	ds_write_b16 v32, v35 offset:2048
	ds_write_b16_d16_hi v33, v35 offset:2048
	v_mov_b32_e32 v38, v45
	v_mov_b32_e32 v40, v61
	s_waitcnt vmcnt(15)
	v_mov_b64_e32 v[34:35], v[236:237]
	global_load_dwordx2 v[236:237], v[252:253], off offset:2048
	v_pk_mul_f32 v[42:43], v[44:45], v[34:35] op_sel:[0,1] op_sel_hi:[0,0]
	s_waitcnt vmcnt(15)
	v_mov_b64_e32 v[36:37], v[238:239]
	global_load_dwordx2 v[238:239], v[252:253], off offset:2304
	v_pk_mul_f32 v[38:39], v[38:39], v[36:37] op_sel:[0,1] op_sel_hi:[0,0]
	v_pk_fma_f32 v[44:45], v[60:61], v[34:35], v[42:43] neg_lo:[0,0,1] neg_hi:[0,0,1]
	v_pk_fma_f32 v[34:35], v[60:61], v[34:35], v[42:43] op_sel_hi:[0,1,1]
	v_pk_fma_f32 v[42:43], v[40:41], v[36:37], v[38:39] op_sel_hi:[0,1,1] neg_lo:[0,0,1] neg_hi:[0,0,1]
	v_pk_fma_f32 v[36:37], v[40:41], v[36:37], v[38:39] op_sel_hi:[0,1,1]
	v_cvt_pk_bf16_f32 v34, v44, v35
	v_cvt_pk_bf16_f32 v35, v42, v37
	ds_write_b16 v81, v34 offset:3072
	ds_write_b16_d16_hi v82, v34 offset:3072
	ds_write_b16 v83, v35 offset:3072
	ds_write_b16_d16_hi v84, v35 offset:3072
	v_mov_b32_e32 v38, v47
	v_mov_b32_e32 v40, v63
	s_waitcnt vmcnt(15)
	v_mov_b64_e32 v[34:35], v[240:241]
	global_load_dwordx2 v[240:241], v[252:253], off offset:2560
	v_pk_mul_f32 v[42:43], v[46:47], v[34:35] op_sel:[0,1] op_sel_hi:[0,0]
	s_waitcnt vmcnt(15)
	v_mov_b64_e32 v[36:37], v[244:245]
	global_load_dwordx2 v[244:245], v[252:253], off offset:2816
	v_pk_mul_f32 v[38:39], v[38:39], v[36:37] op_sel:[0,1] op_sel_hi:[0,0]
	v_pk_fma_f32 v[44:45], v[62:63], v[34:35], v[42:43] neg_lo:[0,0,1] neg_hi:[0,0,1]
	v_pk_fma_f32 v[34:35], v[62:63], v[34:35], v[42:43] op_sel_hi:[0,1,1]
	v_pk_fma_f32 v[42:43], v[40:41], v[36:37], v[38:39] op_sel_hi:[0,1,1] neg_lo:[0,0,1] neg_hi:[0,0,1]
	v_pk_fma_f32 v[36:37], v[40:41], v[36:37], v[38:39] op_sel_hi:[0,1,1]
	v_cvt_pk_bf16_f32 v34, v44, v35
	v_cvt_pk_bf16_f32 v35, v42, v37
	ds_write_b16 v48, v34 offset:3072
	ds_write_b16_d16_hi v49, v34 offset:3072
	ds_write_b16 v32, v35 offset:3072
	ds_write_b16_d16_hi v33, v35 offset:3072
	s_waitcnt vmcnt(15)
	v_mov_b64_e32 v[34:35], v[212:213]
	v_pk_mul_f32 v[38:39], v[0:1], v[34:35] op_sel:[0,1] op_sel_hi:[0,0]
	s_waitcnt vmcnt(14)
	v_mov_b64_e32 v[36:37], v[214:215]
	v_pk_mul_f32 v[0:1], v[0:1], v[36:37] op_sel:[1,1] op_sel_hi:[1,0]
	v_pk_fma_f32 v[40:41], v[16:17], v[34:35], v[38:39] neg_lo:[0,0,1] neg_hi:[0,0,1]
	v_pk_fma_f32 v[34:35], v[16:17], v[34:35], v[38:39] op_sel_hi:[0,1,1]
	v_pk_fma_f32 v[38:39], v[16:17], v[36:37], v[0:1] op_sel:[1,0,0] neg_lo:[0,0,1] neg_hi:[0,0,1]
	v_pk_fma_f32 v[0:1], v[16:17], v[36:37], v[0:1] op_sel:[1,0,0]
	v_mov_b32_e32 v34, v3
	v_cvt_pk_bf16_f32 v0, v40, v35
	v_cvt_pk_bf16_f32 v1, v38, v1
	ds_write_b16 v81, v0 offset:4096
	ds_write_b16_d16_hi v82, v0 offset:4096
	ds_write_b16 v83, v1 offset:4096
	ds_write_b16_d16_hi v84, v1 offset:4096
	v_mov_b32_e32 v36, v19
	s_waitcnt vmcnt(13)
	v_mov_b64_e32 v[0:1], v[216:217]
	v_pk_mul_f32 v[2:3], v[2:3], v[0:1] op_sel:[0,1] op_sel_hi:[0,0]
	s_waitcnt vmcnt(12)
	v_mov_b64_e32 v[16:17], v[218:219]
	v_pk_mul_f32 v[34:35], v[34:35], v[16:17] op_sel:[0,1] op_sel_hi:[0,0]
	v_pk_fma_f32 v[38:39], v[18:19], v[0:1], v[2:3] neg_lo:[0,0,1] neg_hi:[0,0,1]
	v_pk_fma_f32 v[0:1], v[18:19], v[0:1], v[2:3] op_sel_hi:[0,1,1]
	v_pk_fma_f32 v[2:3], v[36:37], v[16:17], v[34:35] op_sel_hi:[0,1,1] neg_lo:[0,0,1] neg_hi:[0,0,1]
	v_pk_fma_f32 v[16:17], v[36:37], v[16:17], v[34:35] op_sel_hi:[0,1,1]
	v_cvt_pk_bf16_f32 v0, v38, v1
	v_cvt_pk_bf16_f32 v1, v2, v17
	ds_write_b16 v48, v0 offset:4096
	ds_write_b16_d16_hi v49, v0 offset:4096
	ds_write_b16 v32, v1 offset:4096
	ds_write_b16_d16_hi v33, v1 offset:4096
	v_mov_b32_e32 v16, v5
	v_mov_b32_e32 v18, v21
	s_waitcnt vmcnt(11)
	v_mov_b64_e32 v[0:1], v[220:221]
	v_pk_mul_f32 v[4:5], v[4:5], v[0:1] op_sel:[0,1] op_sel_hi:[0,0]
	s_waitcnt vmcnt(10)
	v_mov_b64_e32 v[2:3], v[222:223]
	v_pk_mul_f32 v[16:17], v[16:17], v[2:3] op_sel:[0,1] op_sel_hi:[0,0]
	v_pk_fma_f32 v[34:35], v[20:21], v[0:1], v[4:5] neg_lo:[0,0,1] neg_hi:[0,0,1]
	v_pk_fma_f32 v[0:1], v[20:21], v[0:1], v[4:5] op_sel_hi:[0,1,1]
	v_pk_fma_f32 v[4:5], v[18:19], v[2:3], v[16:17] op_sel_hi:[0,1,1] neg_lo:[0,0,1] neg_hi:[0,0,1]
	v_pk_fma_f32 v[2:3], v[18:19], v[2:3], v[16:17] op_sel_hi:[0,1,1]
	v_cvt_pk_bf16_f32 v0, v34, v1
	v_cvt_pk_bf16_f32 v1, v4, v3
	ds_write_b16 v81, v0 offset:5120
	ds_write_b16_d16_hi v82, v0 offset:5120
	ds_write_b16 v83, v1 offset:5120
	ds_write_b16_d16_hi v84, v1 offset:5120
	v_mov_b32_e32 v4, v7
	v_mov_b32_e32 v16, v23
	v_add_co_u32_e32 v18, vcc, s90, v64
	s_waitcnt vmcnt(9)
	v_mov_b64_e32 v[0:1], v[224:225]
	v_pk_mul_f32 v[6:7], v[6:7], v[0:1] op_sel:[0,1] op_sel_hi:[0,0]
	s_waitcnt vmcnt(8)
	v_mov_b64_e32 v[2:3], v[226:227]
	v_pk_mul_f32 v[4:5], v[4:5], v[2:3] op_sel:[0,1] op_sel_hi:[0,0]
	v_pk_fma_f32 v[20:21], v[22:23], v[0:1], v[6:7] neg_lo:[0,0,1] neg_hi:[0,0,1]
	v_pk_fma_f32 v[0:1], v[22:23], v[0:1], v[6:7] op_sel_hi:[0,1,1]
	v_pk_fma_f32 v[6:7], v[16:17], v[2:3], v[4:5] op_sel_hi:[0,1,1] neg_lo:[0,0,1] neg_hi:[0,0,1]
	v_pk_fma_f32 v[2:3], v[16:17], v[2:3], v[4:5] op_sel_hi:[0,1,1]
	v_cvt_pk_bf16_f32 v0, v20, v1
	v_cvt_pk_bf16_f32 v1, v6, v3
	ds_write_b16 v48, v0 offset:5120
	ds_write_b16_d16_hi v49, v0 offset:5120
	ds_write_b16 v32, v1 offset:5120
	ds_write_b16_d16_hi v33, v1 offset:5120
	v_addc_co_u32_e32 v19, vcc, 0, v65, vcc
	v_mov_b32_e32 v4, v9
	v_mov_b32_e32 v6, v25
	v_lshlrev_b64 v[22:23], 20, v[66:67]
	v_lshl_add_u64 v[22:23], s[46:47], 0, v[22:23]
	v_lshl_add_u64 v[22:23], v[22:23], 0, v[128:129]
	s_waitcnt vmcnt(7)
	v_mov_b64_e32 v[0:1], v[228:229]
	v_pk_mul_f32 v[8:9], v[8:9], v[0:1] op_sel:[0,1] op_sel_hi:[0,0]
	s_waitcnt vmcnt(6)
	v_mov_b64_e32 v[2:3], v[230:231]
	v_pk_mul_f32 v[4:5], v[4:5], v[2:3] op_sel:[0,1] op_sel_hi:[0,0]
	v_pk_fma_f32 v[16:17], v[24:25], v[0:1], v[8:9] neg_lo:[0,0,1] neg_hi:[0,0,1]
	v_pk_fma_f32 v[0:1], v[24:25], v[0:1], v[8:9] op_sel_hi:[0,1,1]
	v_pk_fma_f32 v[8:9], v[6:7], v[2:3], v[4:5] op_sel_hi:[0,1,1] neg_lo:[0,0,1] neg_hi:[0,0,1]
	v_pk_fma_f32 v[2:3], v[6:7], v[2:3], v[4:5] op_sel_hi:[0,1,1]
	v_cvt_pk_bf16_f32 v0, v16, v1
	v_cvt_pk_bf16_f32 v1, v8, v3
	ds_write_b16 v81, v0 offset:6144
	ds_write_b16_d16_hi v82, v0 offset:6144
	ds_write_b16 v83, v1 offset:6144
	ds_write_b16_d16_hi v84, v1 offset:6144
	v_mov_b32_e32 v4, v11
	v_mov_b32_e32 v6, v27
	v_lshl_add_u32 v25, v98, 7, v192
	v_mov_b32_e32 v24, v15
	v_mov_b32_e32 v16, v129
	v_mov_b32_e32 v17, v129
	s_waitcnt vmcnt(5)
	v_mov_b64_e32 v[0:1], v[232:233]
	v_pk_mul_f32 v[8:9], v[10:11], v[0:1] op_sel:[0,1] op_sel_hi:[0,0]
	s_waitcnt vmcnt(4)
	v_mov_b64_e32 v[2:3], v[234:235]
	v_pk_mul_f32 v[4:5], v[4:5], v[2:3] op_sel:[0,1] op_sel_hi:[0,0]
	v_pk_fma_f32 v[10:11], v[26:27], v[0:1], v[8:9] neg_lo:[0,0,1] neg_hi:[0,0,1]
	v_pk_fma_f32 v[0:1], v[26:27], v[0:1], v[8:9] op_sel_hi:[0,1,1]
	v_pk_fma_f32 v[8:9], v[6:7], v[2:3], v[4:5] op_sel_hi:[0,1,1] neg_lo:[0,0,1] neg_hi:[0,0,1]
	v_pk_fma_f32 v[2:3], v[6:7], v[2:3], v[4:5] op_sel_hi:[0,1,1]
	v_cvt_pk_bf16_f32 v0, v10, v1
	v_cvt_pk_bf16_f32 v1, v8, v3
	ds_write_b16 v48, v0 offset:6144
	ds_write_b16_d16_hi v49, v0 offset:6144
	ds_write_b16 v32, v1 offset:6144
	ds_write_b16_d16_hi v33, v1 offset:6144
	v_mov_b32_e32 v4, v13
	v_mov_b32_e32 v6, v29
	v_lshlrev_b32_e32 v27, 2, v98
	v_mov_b32_e32 v26, v31
	s_waitcnt vmcnt(3)
	v_mov_b64_e32 v[0:1], v[236:237]
	v_pk_mul_f32 v[8:9], v[12:13], v[0:1] op_sel:[0,1] op_sel_hi:[0,0]
	s_waitcnt vmcnt(2)
	v_mov_b64_e32 v[2:3], v[238:239]
	v_pk_mul_f32 v[4:5], v[4:5], v[2:3] op_sel:[0,1] op_sel_hi:[0,0]
	v_pk_fma_f32 v[10:11], v[28:29], v[0:1], v[8:9] neg_lo:[0,0,1] neg_hi:[0,0,1]
	v_pk_fma_f32 v[0:1], v[28:29], v[0:1], v[8:9] op_sel_hi:[0,1,1]
	v_pk_fma_f32 v[8:9], v[6:7], v[2:3], v[4:5] op_sel_hi:[0,1,1] neg_lo:[0,0,1] neg_hi:[0,0,1]
	v_pk_fma_f32 v[2:3], v[6:7], v[2:3], v[4:5] op_sel_hi:[0,1,1]
	v_cvt_pk_bf16_f32 v0, v10, v1
	v_cvt_pk_bf16_f32 v1, v8, v3
	ds_write_b16 v81, v0 offset:7168
	ds_write_b16_d16_hi v82, v0 offset:7168
	ds_write_b16 v83, v1 offset:7168
	ds_write_b16_d16_hi v84, v1 offset:7168
	v_and_b32_e32 v28, 15, v98
	v_lshlrev_b32_e32 v29, 4, v98
	v_and_or_b32 v27, v27, s78, v28
	v_and_b32_e32 v29, 0x70, v29
	v_lshlrev_b32_e32 v28, 4, v27
	v_add_u32_e32 v34, v25, v29
	v_xad_u32 v35, v29, 64, v25
	v_xad_u32 v27, v29, 16, v25
	v_xad_u32 v36, v29, s76, v25
	v_xad_u32 v37, v29, 32, v25
	v_xad_u32 v38, v29, s77, v25
	v_xad_u32 v40, v29, 48, v25
	v_xad_u32 v44, v29, s21, v25
	v_ashrrev_i32_e32 v29, 31, v28
	v_lshl_add_u64 v[50:51], v[22:23], 0, v[28:29]
	v_mov_b32_e32 v0, v129
	v_mov_b32_e32 v1, v129
	v_mov_b32_e32 v2, v129
	v_mov_b32_e32 v3, v129
	v_mov_b32_e32 v4, v129
	v_mov_b32_e32 v5, v129
	v_mov_b32_e32 v6, v129
	v_mov_b32_e32 v7, v129
	v_mov_b32_e32 v8, v129
	v_mov_b32_e32 v9, v129
	v_mov_b32_e32 v10, v129
	v_mov_b32_e32 v11, v129
	v_mov_b32_e32 v18, v129
	v_mov_b32_e32 v19, v129
	s_waitcnt vmcnt(1)
	v_mov_b64_e32 v[12:13], v[240:241]
	v_pk_mul_f32 v[14:15], v[14:15], v[12:13] op_sel:[0,1] op_sel_hi:[0,0]
	s_waitcnt vmcnt(0)
	v_mov_b64_e32 v[20:21], v[244:245]
	v_pk_mul_f32 v[22:23], v[24:25], v[20:21] op_sel:[0,1] op_sel_hi:[0,0]
	v_pk_fma_f32 v[24:25], v[30:31], v[12:13], v[14:15] neg_lo:[0,0,1] neg_hi:[0,0,1]
	v_pk_fma_f32 v[12:13], v[30:31], v[12:13], v[14:15] op_sel_hi:[0,1,1]
	v_pk_fma_f32 v[14:15], v[26:27], v[20:21], v[22:23] op_sel_hi:[0,1,1] neg_lo:[0,0,1] neg_hi:[0,0,1]
	v_pk_fma_f32 v[20:21], v[26:27], v[20:21], v[22:23] op_sel_hi:[0,1,1]
	v_cvt_pk_bf16_f32 v12, v24, v13
	v_cvt_pk_bf16_f32 v13, v14, v21
	ds_write_b16 v48, v12 offset:7168
	ds_write_b16_d16_hi v49, v12 offset:7168
	ds_write_b16 v32, v13 offset:7168
	ds_write_b16_d16_hi v33, v13 offset:7168
	ds_read_b128 v[12:15], v34
	ds_read_b128 v[20:23], v35
	ds_read_b128 v[24:27], v27
	ds_read_b128 v[28:31], v36
	ds_read_b128 v[32:35], v37
	ds_read_b128 v[36:39], v38
	ds_read_b128 v[40:43], v40
	ds_read_b128 v[44:47], v44
	s_waitcnt lgkmcnt(7)
	v_lshlrev_b32_e32 v48, 16, v12
	v_and_b32_e32 v12, 0xffff0000, v12
	v_lshlrev_b32_e32 v52, 16, v14
	v_and_b32_e32 v14, 0xffff0000, v14
	s_waitcnt lgkmcnt(6)
	v_lshlrev_b32_e32 v54, 16, v20
	v_and_b32_e32 v20, 0xffff0000, v20
	v_lshlrev_b32_e32 v56, 16, v22
	v_and_b32_e32 v22, 0xffff0000, v22
	s_waitcnt lgkmcnt(5)
	v_lshlrev_b32_e32 v58, 16, v24
	v_and_b32_e32 v24, 0xffff0000, v24
	v_lshlrev_b32_e32 v60, 16, v26
	v_and_b32_e32 v26, 0xffff0000, v26
	s_waitcnt lgkmcnt(4)
	v_lshlrev_b32_e32 v62, 16, v28
	v_and_b32_e32 v28, 0xffff0000, v28
	v_lshlrev_b32_e32 v64, 16, v30
	v_and_b32_e32 v30, 0xffff0000, v30
	v_cvt_pk_fp8_f32 v0, v48, v12
	v_cvt_pk_fp8_f32 v1, v52, v14
	v_cvt_pk_fp8_f32 v2, v54, v20
	v_cvt_pk_fp8_f32 v3, v56, v22
	s_waitcnt lgkmcnt(3)
	v_lshlrev_b32_e32 v66, 16, v32
	v_and_b32_e32 v32, 0xffff0000, v32
	v_lshlrev_b32_e32 v68, 16, v34
	v_and_b32_e32 v34, 0xffff0000, v34
	s_waitcnt lgkmcnt(2)
	v_lshlrev_b32_e32 v70, 16, v36
	v_and_b32_e32 v36, 0xffff0000, v36
	v_lshlrev_b32_e32 v72, 16, v38
	v_and_b32_e32 v38, 0xffff0000, v38
	v_cvt_pk_fp8_f32 v4, v58, v24
	v_cvt_pk_fp8_f32 v5, v60, v26
	v_cvt_pk_fp8_f32 v6, v62, v28
	v_cvt_pk_fp8_f32 v7, v64, v30
	s_waitcnt lgkmcnt(1)
	v_lshlrev_b32_e32 v74, 16, v40
	v_and_b32_e32 v40, 0xffff0000, v40
	v_lshlrev_b32_e32 v76, 16, v42
	v_and_b32_e32 v42, 0xffff0000, v42
	s_waitcnt lgkmcnt(0)
	v_lshlrev_b32_e32 v78, 16, v44
	v_and_b32_e32 v44, 0xffff0000, v44
	v_lshlrev_b32_e32 v80, 16, v46
	v_and_b32_e32 v46, 0xffff0000, v46
	v_cvt_pk_fp8_f32 v8, v66, v32
	v_cvt_pk_fp8_f32 v9, v68, v34
	v_cvt_pk_fp8_f32 v10, v70, v36
	v_cvt_pk_fp8_f32 v11, v72, v38
	v_lshlrev_b32_e32 v49, 16, v13
	v_and_b32_e32 v13, 0xffff0000, v13
	v_lshlrev_b32_e32 v53, 16, v15
	v_and_b32_e32 v15, 0xffff0000, v15
	v_lshlrev_b32_e32 v55, 16, v21
	v_and_b32_e32 v21, 0xffff0000, v21
	v_lshlrev_b32_e32 v57, 16, v23
	v_and_b32_e32 v23, 0xffff0000, v23
	v_cvt_pk_fp8_f32 v16, v74, v40
	v_cvt_pk_fp8_f32 v17, v76, v42
	v_cvt_pk_fp8_f32 v18, v78, v44
	v_cvt_pk_fp8_f32 v19, v80, v46
	v_lshlrev_b32_e32 v59, 16, v25
	v_and_b32_e32 v25, 0xffff0000, v25
	v_lshlrev_b32_e32 v61, 16, v27
	v_and_b32_e32 v27, 0xffff0000, v27
	v_lshlrev_b32_e32 v63, 16, v29
	v_and_b32_e32 v29, 0xffff0000, v29
	v_lshlrev_b32_e32 v65, 16, v31
	v_and_b32_e32 v31, 0xffff0000, v31
	v_cvt_pk_fp8_f32 v0, v49, v13 op_sel:[0,0,1]
	v_cvt_pk_fp8_f32 v1, v53, v15 op_sel:[0,0,1]
	v_cvt_pk_fp8_f32 v2, v55, v21 op_sel:[0,0,1]
	v_cvt_pk_fp8_f32 v3, v57, v23 op_sel:[0,0,1]
	v_lshlrev_b32_e32 v67, 16, v33
	v_and_b32_e32 v33, 0xffff0000, v33
	v_lshlrev_b32_e32 v69, 16, v35
	v_and_b32_e32 v35, 0xffff0000, v35
	v_lshlrev_b32_e32 v71, 16, v37
	v_and_b32_e32 v37, 0xffff0000, v37
	v_lshlrev_b32_e32 v73, 16, v39
	v_and_b32_e32 v39, 0xffff0000, v39
	v_cvt_pk_fp8_f32 v4, v59, v25 op_sel:[0,0,1]
	v_cvt_pk_fp8_f32 v5, v61, v27 op_sel:[0,0,1]
	v_cvt_pk_fp8_f32 v6, v63, v29 op_sel:[0,0,1]
	v_cvt_pk_fp8_f32 v7, v65, v31 op_sel:[0,0,1]
	v_lshlrev_b32_e32 v75, 16, v41
	v_and_b32_e32 v41, 0xffff0000, v41
	v_lshlrev_b32_e32 v77, 16, v43
	v_and_b32_e32 v43, 0xffff0000, v43
	v_lshlrev_b32_e32 v79, 16, v45
	v_and_b32_e32 v45, 0xffff0000, v45
	v_lshlrev_b32_e32 v81, 16, v47
	v_and_b32_e32 v47, 0xffff0000, v47
	v_cvt_pk_fp8_f32 v8, v67, v33 op_sel:[0,0,1]
	v_cvt_pk_fp8_f32 v9, v69, v35 op_sel:[0,0,1]
	v_cvt_pk_fp8_f32 v10, v71, v37 op_sel:[0,0,1]
	v_cvt_pk_fp8_f32 v11, v73, v39 op_sel:[0,0,1]
	v_cvt_pk_fp8_f32 v16, v75, v41 op_sel:[0,0,1]
	v_cvt_pk_fp8_f32 v17, v77, v43 op_sel:[0,0,1]
	v_cvt_pk_fp8_f32 v18, v79, v45 op_sel:[0,0,1]
	v_cvt_pk_fp8_f32 v19, v81, v47 op_sel:[0,0,1]
	global_store_dwordx4 v[50:51], v[0:3], off
	global_store_dwordx4 v[50:51], v[4:7], off offset:256
	global_store_dwordx4 v[50:51], v[8:11], off offset:512
	global_store_dwordx4 v[50:51], v[16:19], off offset:768
.LBB0_246:
	s_andn2_saveexec_b64 s[4:5], s[4:5]
	s_cbranch_execz .LBB0_159
	s_mov_b32 s101, 0
	s_mov_b32 s100, 0x1000
	v_lshl_add_u64 v[246:247], v[64:65], 0, s[100:101]
	s_mov_b32 s100, 0x2000
	v_lshl_add_u64 v[250:251], v[64:65], 0, s[100:101]
	s_mov_b32 s100, 0x3000
	v_lshl_add_u64 v[252:253], v[64:65], 0, s[100:101]
	global_load_dwordx2 v[212:213], v[64:65], off
	global_load_dwordx2 v[214:215], v[64:65], off offset:256
	global_load_dwordx2 v[216:217], v[64:65], off offset:512
	global_load_dwordx2 v[218:219], v[64:65], off offset:768
	global_load_dwordx2 v[220:221], v[64:65], off offset:2048
	global_load_dwordx2 v[222:223], v[64:65], off offset:2304
	global_load_dwordx2 v[224:225], v[64:65], off offset:2560
	global_load_dwordx2 v[226:227], v[64:65], off offset:2816
	global_load_dwordx2 v[228:229], v[246:247], off
	global_load_dwordx2 v[230:231], v[246:247], off offset:256
	global_load_dwordx2 v[232:233], v[246:247], off offset:512
	global_load_dwordx2 v[234:235], v[246:247], off offset:768
	global_load_dwordx2 v[236:237], v[246:247], off offset:2048
	global_load_dwordx2 v[238:239], v[246:247], off offset:2304
	global_load_dwordx2 v[240:241], v[246:247], off offset:2560
	global_load_dwordx2 v[244:245], v[246:247], off offset:2816
	v_ashrrev_i32_e32 v66, 3, v98
	v_lshrrev_b32_e32 v73, 3, v98
	v_lshlrev_b32_e32 v67, 1, v98
	v_and_b32_e32 v81, -4, v66
	v_bfe_u32 v80, v98, 3, 2
	v_bfi_b32 v70, 3, v73, v66
	v_and_b32_e32 v82, 14, v67
	v_lshlrev_b32_e32 v67, 7, v81
	v_or_b32_e32 v71, 1, v81
	v_bitop3_b32 v72, v81, v80, 1 bitop3:0x36
	v_lshl_add_u32 v67, v70, 4, v67
	v_lshlrev_b32_e32 v70, 7, v71
	v_lshl_add_u32 v71, v72, 4, v70
	v_or_b32_e32 v70, v67, v82
	v_add_u32_e32 v67, v192, v70
	v_or_b32_e32 v72, v71, v82
	v_xad_u32 v70, v70, 64, v192
	v_add_u32_e32 v71, v192, v72
	v_xad_u32 v72, v72, 64, v192
	v_ashrrev_i32_e32 v141, 31, v140
	v_ashrrev_i32_e32 v143, 31, v142
	s_waitcnt vmcnt(14)
	v_mov_b64_e32 v[68:69], v[212:213]
	v_mov_b64_e32 v[74:75], v[214:215]
	global_load_dwordx2 v[212:213], v[250:251], off
	global_load_dwordx2 v[214:215], v[250:251], off offset:256
	v_pk_mul_f32 v[76:77], v[32:33], v[68:69] op_sel:[0,1] op_sel_hi:[0,0]
	v_pk_mul_f32 v[32:33], v[32:33], v[74:75] op_sel:[1,1] op_sel_hi:[1,0]
	v_pk_fma_f32 v[78:79], v[48:49], v[68:69], v[76:77] neg_lo:[0,0,1] neg_hi:[0,0,1]
	v_pk_fma_f32 v[68:69], v[48:49], v[68:69], v[76:77] op_sel_hi:[0,1,1]
	v_pk_fma_f32 v[76:77], v[48:49], v[74:75], v[32:33] op_sel:[1,0,0] neg_lo:[0,0,1] neg_hi:[0,0,1]
	v_pk_fma_f32 v[32:33], v[48:49], v[74:75], v[32:33] op_sel:[1,0,0]
	v_mov_b32_e32 v79, v69
	v_mov_b32_e32 v77, v33
	v_pk_mul_f32 v[32:33], v[78:79], s[20:21] op_sel_hi:[1,0]
	v_pk_mul_f32 v[48:49], v[76:77], s[20:21] op_sel_hi:[1,0]
	v_cvt_pk_bf16_f32 v32, v32, v33
	v_cvt_pk_bf16_f32 v33, v48, v49
	ds_write_b16 v67, v32
	ds_write_b16_d16_hi v70, v32
	ds_write_b16 v71, v33
	ds_write_b16_d16_hi v72, v33
	v_mov_b32_e32 v76, v35
	v_or_b32_e32 v48, 3, v66
	v_or_b32_e32 v68, 2, v81
	v_mov_b32_e32 v78, v51
	v_bitop3_b32 v49, v73, v66, 3 bitop3:0x4e
	v_bitop3_b32 v69, v81, v80, 2 bitop3:0x36
	v_lshlrev_b32_e32 v48, 7, v48
	v_lshlrev_b32_e32 v68, 7, v68
	v_lshl_add_u32 v48, v49, 4, v48
	v_lshl_add_u32 v49, v69, 4, v68
	v_or_b32_e32 v68, v48, v82
	v_or_b32_e32 v69, v49, v82
	v_add_u32_e32 v48, v192, v68
	v_xad_u32 v49, v68, 64, v192
	v_add_u32_e32 v68, v192, v69
	v_xad_u32 v69, v69, 64, v192
	s_waitcnt vmcnt(15)
	v_mov_b64_e32 v[32:33], v[216:217]
	global_load_dwordx2 v[216:217], v[250:251], off offset:512
	v_pk_mul_f32 v[34:35], v[34:35], v[32:33] op_sel:[0,1] op_sel_hi:[0,0]
	s_waitcnt vmcnt(15)
	v_mov_b64_e32 v[74:75], v[218:219]
	global_load_dwordx2 v[218:219], v[250:251], off offset:768
	v_pk_mul_f32 v[76:77], v[76:77], v[74:75] op_sel:[0,1] op_sel_hi:[0,0]
	v_pk_fma_f32 v[80:81], v[50:51], v[32:33], v[34:35] neg_lo:[0,0,1] neg_hi:[0,0,1]
	v_pk_fma_f32 v[32:33], v[50:51], v[32:33], v[34:35] op_sel_hi:[0,1,1]
	v_pk_fma_f32 v[34:35], v[78:79], v[74:75], v[76:77] op_sel_hi:[0,1,1] neg_lo:[0,0,1] neg_hi:[0,0,1]
	v_pk_fma_f32 v[50:51], v[78:79], v[74:75], v[76:77] op_sel_hi:[0,1,1]
	v_mov_b32_e32 v81, v33
	v_mov_b32_e32 v35, v51
	v_pk_mul_f32 v[32:33], v[80:81], s[20:21] op_sel_hi:[1,0]
	v_pk_mul_f32 v[34:35], v[34:35], s[20:21] op_sel_hi:[1,0]
	v_cvt_pk_bf16_f32 v32, v32, v33
	v_cvt_pk_bf16_f32 v33, v34, v35
	ds_write_b16 v68, v32
	ds_write_b16_d16_hi v69, v32
	ds_write_b16 v48, v33
	ds_write_b16_d16_hi v49, v33
	v_mov_b32_e32 v50, v37
	v_mov_b32_e32 v74, v53
	s_waitcnt vmcnt(15)
	v_mov_b64_e32 v[32:33], v[220:221]
	global_load_dwordx2 v[220:221], v[250:251], off offset:2048
	v_pk_mul_f32 v[36:37], v[36:37], v[32:33] op_sel:[0,1] op_sel_hi:[0,0]
	s_waitcnt vmcnt(15)
	v_mov_b64_e32 v[34:35], v[222:223]
	global_load_dwordx2 v[222:223], v[250:251], off offset:2304
	v_pk_mul_f32 v[50:51], v[50:51], v[34:35] op_sel:[0,1] op_sel_hi:[0,0]
	v_pk_fma_f32 v[76:77], v[52:53], v[32:33], v[36:37] neg_lo:[0,0,1] neg_hi:[0,0,1]
	v_pk_fma_f32 v[32:33], v[52:53], v[32:33], v[36:37] op_sel_hi:[0,1,1]
	v_pk_fma_f32 v[36:37], v[74:75], v[34:35], v[50:51] op_sel_hi:[0,1,1] neg_lo:[0,0,1] neg_hi:[0,0,1]
	v_pk_fma_f32 v[34:35], v[74:75], v[34:35], v[50:51] op_sel_hi:[0,1,1]
	v_mov_b32_e32 v77, v33
	v_mov_b32_e32 v37, v35
	v_pk_mul_f32 v[32:33], v[76:77], s[20:21] op_sel_hi:[1,0]
	v_pk_mul_f32 v[34:35], v[36:37], s[20:21] op_sel_hi:[1,0]
	v_cvt_pk_bf16_f32 v32, v32, v33
	v_cvt_pk_bf16_f32 v33, v34, v35
	ds_write_b16 v67, v32 offset:1024
	ds_write_b16_d16_hi v70, v32 offset:1024
	ds_write_b16 v71, v33 offset:1024
	ds_write_b16_d16_hi v72, v33 offset:1024
	v_mov_b32_e32 v50, v39
	v_mov_b32_e32 v52, v55
	v_add_co_u32_e32 v74, vcc, s83, v64
	s_waitcnt vmcnt(15)
	v_mov_b64_e32 v[34:35], v[224:225]
	global_load_dwordx2 v[224:225], v[250:251], off offset:2560
	v_pk_mul_f32 v[38:39], v[38:39], v[34:35] op_sel:[0,1] op_sel_hi:[0,0]
	s_waitcnt vmcnt(15)
	v_mov_b64_e32 v[36:37], v[226:227]
	global_load_dwordx2 v[226:227], v[250:251], off offset:2816
	v_pk_mul_f32 v[50:51], v[50:51], v[36:37] op_sel:[0,1] op_sel_hi:[0,0]
	v_pk_fma_f32 v[76:77], v[54:55], v[34:35], v[38:39] neg_lo:[0,0,1] neg_hi:[0,0,1]
	v_pk_fma_f32 v[34:35], v[54:55], v[34:35], v[38:39] op_sel_hi:[0,1,1]
	v_pk_fma_f32 v[38:39], v[52:53], v[36:37], v[50:51] op_sel_hi:[0,1,1] neg_lo:[0,0,1] neg_hi:[0,0,1]
	v_pk_fma_f32 v[36:37], v[52:53], v[36:37], v[50:51] op_sel_hi:[0,1,1]
	v_mov_b32_e32 v77, v35
	v_mov_b32_e32 v39, v37
	v_pk_mul_f32 v[34:35], v[76:77], s[20:21] op_sel_hi:[1,0]
	v_addc_co_u32_e32 v75, vcc, 0, v65, vcc
	v_pk_mul_f32 v[36:37], v[38:39], s[20:21] op_sel_hi:[1,0]
	v_cvt_pk_bf16_f32 v34, v34, v35
	v_add_co_u32_e32 v32, vcc, s51, v64
	v_cvt_pk_bf16_f32 v35, v36, v37
	ds_write_b16 v68, v34 offset:1024
	ds_write_b16_d16_hi v69, v34 offset:1024
	ds_write_b16 v48, v35 offset:1024
	ds_write_b16_d16_hi v49, v35 offset:1024
	v_addc_co_u32_e32 v33, vcc, 0, v65, vcc
	v_mov_b32_e32 v38, v41
	v_mov_b32_e32 v50, v57
	s_waitcnt vmcnt(15)
	v_mov_b64_e32 v[34:35], v[228:229]
	global_load_dwordx2 v[228:229], v[252:253], off
	v_pk_mul_f32 v[40:41], v[40:41], v[34:35] op_sel:[0,1] op_sel_hi:[0,0]
	s_waitcnt vmcnt(15)
	v_mov_b64_e32 v[36:37], v[230:231]
	global_load_dwordx2 v[230:231], v[252:253], off offset:256
	v_pk_mul_f32 v[38:39], v[38:39], v[36:37] op_sel:[0,1] op_sel_hi:[0,0]
	v_pk_fma_f32 v[52:53], v[56:57], v[34:35], v[40:41] neg_lo:[0,0,1] neg_hi:[0,0,1]
	v_pk_fma_f32 v[34:35], v[56:57], v[34:35], v[40:41] op_sel_hi:[0,1,1]
	v_pk_fma_f32 v[40:41], v[50:51], v[36:37], v[38:39] op_sel_hi:[0,1,1] neg_lo:[0,0,1] neg_hi:[0,0,1]
	v_pk_fma_f32 v[36:37], v[50:51], v[36:37], v[38:39] op_sel_hi:[0,1,1]
	v_mov_b32_e32 v53, v35
	v_mov_b32_e32 v41, v37
	v_pk_mul_f32 v[34:35], v[52:53], s[20:21] op_sel_hi:[1,0]
	v_pk_mul_f32 v[36:37], v[40:41], s[20:21] op_sel_hi:[1,0]
	v_cvt_pk_bf16_f32 v34, v34, v35
	v_cvt_pk_bf16_f32 v35, v36, v37
	ds_write_b16 v67, v34 offset:2048
	ds_write_b16_d16_hi v70, v34 offset:2048
	ds_write_b16 v71, v35 offset:2048
	ds_write_b16_d16_hi v72, v35 offset:2048
	v_mov_b32_e32 v38, v43
	v_mov_b32_e32 v40, v59
	s_waitcnt vmcnt(15)
	v_mov_b64_e32 v[34:35], v[232:233]
	global_load_dwordx2 v[232:233], v[252:253], off offset:512
	v_pk_mul_f32 v[42:43], v[42:43], v[34:35] op_sel:[0,1] op_sel_hi:[0,0]
	s_waitcnt vmcnt(15)
	v_mov_b64_e32 v[36:37], v[234:235]
	global_load_dwordx2 v[234:235], v[252:253], off offset:768
	v_pk_mul_f32 v[38:39], v[38:39], v[36:37] op_sel:[0,1] op_sel_hi:[0,0]
	v_pk_fma_f32 v[50:51], v[58:59], v[34:35], v[42:43] neg_lo:[0,0,1] neg_hi:[0,0,1]
	v_pk_fma_f32 v[34:35], v[58:59], v[34:35], v[42:43] op_sel_hi:[0,1,1]
	v_pk_fma_f32 v[42:43], v[40:41], v[36:37], v[38:39] op_sel_hi:[0,1,1] neg_lo:[0,0,1] neg_hi:[0,0,1]
	v_pk_fma_f32 v[36:37], v[40:41], v[36:37], v[38:39] op_sel_hi:[0,1,1]
	v_mov_b32_e32 v51, v35
	v_mov_b32_e32 v43, v37
	v_pk_mul_f32 v[34:35], v[50:51], s[20:21] op_sel_hi:[1,0]
	v_pk_mul_f32 v[36:37], v[42:43], s[20:21] op_sel_hi:[1,0]
	v_cvt_pk_bf16_f32 v34, v34, v35
	v_cvt_pk_bf16_f32 v35, v36, v37
	ds_write_b16 v68, v34 offset:2048
	ds_write_b16_d16_hi v69, v34 offset:2048
	ds_write_b16 v48, v35 offset:2048
	ds_write_b16_d16_hi v49, v35 offset:2048
	v_mov_b32_e32 v38, v45
	v_mov_b32_e32 v40, v61
	s_waitcnt vmcnt(15)
	v_mov_b64_e32 v[34:35], v[236:237]
	global_load_dwordx2 v[236:237], v[252:253], off offset:2048
	v_pk_mul_f32 v[42:43], v[44:45], v[34:35] op_sel:[0,1] op_sel_hi:[0,0]
	s_waitcnt vmcnt(15)
	v_mov_b64_e32 v[36:37], v[238:239]
	global_load_dwordx2 v[238:239], v[252:253], off offset:2304
	v_pk_mul_f32 v[38:39], v[38:39], v[36:37] op_sel:[0,1] op_sel_hi:[0,0]
	v_pk_fma_f32 v[44:45], v[60:61], v[34:35], v[42:43] neg_lo:[0,0,1] neg_hi:[0,0,1]
	v_pk_fma_f32 v[34:35], v[60:61], v[34:35], v[42:43] op_sel_hi:[0,1,1]
	v_pk_fma_f32 v[42:43], v[40:41], v[36:37], v[38:39] op_sel_hi:[0,1,1] neg_lo:[0,0,1] neg_hi:[0,0,1]
	v_pk_fma_f32 v[36:37], v[40:41], v[36:37], v[38:39] op_sel_hi:[0,1,1]
	v_mov_b32_e32 v45, v35
	v_mov_b32_e32 v43, v37
	v_pk_mul_f32 v[34:35], v[44:45], s[20:21] op_sel_hi:[1,0]
	v_pk_mul_f32 v[36:37], v[42:43], s[20:21] op_sel_hi:[1,0]
	v_cvt_pk_bf16_f32 v34, v34, v35
	v_cvt_pk_bf16_f32 v35, v36, v37
	ds_write_b16 v67, v34 offset:3072
	ds_write_b16_d16_hi v70, v34 offset:3072
	ds_write_b16 v71, v35 offset:3072
	ds_write_b16_d16_hi v72, v35 offset:3072
	v_mov_b32_e32 v38, v47
	v_mov_b32_e32 v40, v63
	s_waitcnt vmcnt(15)
	v_mov_b64_e32 v[34:35], v[240:241]
	global_load_dwordx2 v[240:241], v[252:253], off offset:2560
	v_pk_mul_f32 v[42:43], v[46:47], v[34:35] op_sel:[0,1] op_sel_hi:[0,0]
	s_waitcnt vmcnt(15)
	v_mov_b64_e32 v[36:37], v[244:245]
	global_load_dwordx2 v[244:245], v[252:253], off offset:2816
	v_pk_mul_f32 v[38:39], v[38:39], v[36:37] op_sel:[0,1] op_sel_hi:[0,0]
	v_pk_fma_f32 v[44:45], v[62:63], v[34:35], v[42:43] neg_lo:[0,0,1] neg_hi:[0,0,1]
	v_pk_fma_f32 v[34:35], v[62:63], v[34:35], v[42:43] op_sel_hi:[0,1,1]
	v_pk_fma_f32 v[42:43], v[40:41], v[36:37], v[38:39] op_sel_hi:[0,1,1] neg_lo:[0,0,1] neg_hi:[0,0,1]
	v_pk_fma_f32 v[36:37], v[40:41], v[36:37], v[38:39] op_sel_hi:[0,1,1]
	v_mov_b32_e32 v45, v35
	v_mov_b32_e32 v43, v37
	v_pk_mul_f32 v[34:35], v[44:45], s[20:21] op_sel_hi:[1,0]
	v_pk_mul_f32 v[36:37], v[42:43], s[20:21] op_sel_hi:[1,0]
	v_cvt_pk_bf16_f32 v34, v34, v35
	v_cvt_pk_bf16_f32 v35, v36, v37
	ds_write_b16 v68, v34 offset:3072
	ds_write_b16_d16_hi v69, v34 offset:3072
	ds_write_b16 v48, v35 offset:3072
	ds_write_b16_d16_hi v49, v35 offset:3072
	s_waitcnt vmcnt(15)
	v_mov_b64_e32 v[34:35], v[212:213]
	v_pk_mul_f32 v[38:39], v[0:1], v[34:35] op_sel:[0,1] op_sel_hi:[0,0]
	s_waitcnt vmcnt(14)
	v_mov_b64_e32 v[36:37], v[214:215]
	v_pk_mul_f32 v[0:1], v[0:1], v[36:37] op_sel:[1,1] op_sel_hi:[1,0]
	v_pk_fma_f32 v[40:41], v[16:17], v[34:35], v[38:39] neg_lo:[0,0,1] neg_hi:[0,0,1]
	v_pk_fma_f32 v[34:35], v[16:17], v[34:35], v[38:39] op_sel_hi:[0,1,1]
	v_pk_fma_f32 v[38:39], v[16:17], v[36:37], v[0:1] op_sel:[1,0,0] neg_lo:[0,0,1] neg_hi:[0,0,1]
	v_pk_fma_f32 v[0:1], v[16:17], v[36:37], v[0:1] op_sel:[1,0,0]
	v_mov_b32_e32 v41, v35
	v_mov_b32_e32 v39, v1
	v_pk_mul_f32 v[0:1], v[40:41], s[20:21] op_sel_hi:[1,0]
	v_pk_mul_f32 v[16:17], v[38:39], s[20:21] op_sel_hi:[1,0]
	v_cvt_pk_bf16_f32 v0, v0, v1
	v_cvt_pk_bf16_f32 v1, v16, v17
	ds_write_b16 v67, v0 offset:4096
	ds_write_b16_d16_hi v70, v0 offset:4096
	ds_write_b16 v71, v1 offset:4096
	ds_write_b16_d16_hi v72, v1 offset:4096
	v_mov_b32_e32 v34, v3
	v_mov_b32_e32 v36, v19
	s_waitcnt vmcnt(13)
	v_mov_b64_e32 v[0:1], v[216:217]
	v_pk_mul_f32 v[2:3], v[2:3], v[0:1] op_sel:[0,1] op_sel_hi:[0,0]
	s_waitcnt vmcnt(12)
	v_mov_b64_e32 v[16:17], v[218:219]
	v_pk_mul_f32 v[34:35], v[34:35], v[16:17] op_sel:[0,1] op_sel_hi:[0,0]
	v_pk_fma_f32 v[38:39], v[18:19], v[0:1], v[2:3] neg_lo:[0,0,1] neg_hi:[0,0,1]
	v_pk_fma_f32 v[0:1], v[18:19], v[0:1], v[2:3] op_sel_hi:[0,1,1]
	v_pk_fma_f32 v[2:3], v[36:37], v[16:17], v[34:35] op_sel_hi:[0,1,1] neg_lo:[0,0,1] neg_hi:[0,0,1]
	v_pk_fma_f32 v[16:17], v[36:37], v[16:17], v[34:35] op_sel_hi:[0,1,1]
	v_mov_b32_e32 v39, v1
	v_mov_b32_e32 v3, v17
	v_pk_mul_f32 v[0:1], v[38:39], s[20:21] op_sel_hi:[1,0]
	v_pk_mul_f32 v[2:3], v[2:3], s[20:21] op_sel_hi:[1,0]
	v_cvt_pk_bf16_f32 v0, v0, v1
	v_cvt_pk_bf16_f32 v1, v2, v3
	ds_write_b16 v68, v0 offset:4096
	ds_write_b16_d16_hi v69, v0 offset:4096
	ds_write_b16 v48, v1 offset:4096
	ds_write_b16_d16_hi v49, v1 offset:4096
	v_mov_b32_e32 v16, v5
	v_mov_b32_e32 v18, v21
	s_waitcnt vmcnt(11)
	v_mov_b64_e32 v[0:1], v[220:221]
	v_pk_mul_f32 v[4:5], v[4:5], v[0:1] op_sel:[0,1] op_sel_hi:[0,0]
	s_waitcnt vmcnt(10)
	v_mov_b64_e32 v[2:3], v[222:223]
	v_pk_mul_f32 v[16:17], v[16:17], v[2:3] op_sel:[0,1] op_sel_hi:[0,0]
	v_pk_fma_f32 v[34:35], v[20:21], v[0:1], v[4:5] neg_lo:[0,0,1] neg_hi:[0,0,1]
	v_pk_fma_f32 v[0:1], v[20:21], v[0:1], v[4:5] op_sel_hi:[0,1,1]
	v_pk_fma_f32 v[4:5], v[18:19], v[2:3], v[16:17] op_sel_hi:[0,1,1] neg_lo:[0,0,1] neg_hi:[0,0,1]
	v_pk_fma_f32 v[2:3], v[18:19], v[2:3], v[16:17] op_sel_hi:[0,1,1]
	v_mov_b32_e32 v35, v1
	v_mov_b32_e32 v5, v3
	v_pk_mul_f32 v[0:1], v[34:35], s[20:21] op_sel_hi:[1,0]
	v_pk_mul_f32 v[2:3], v[4:5], s[20:21] op_sel_hi:[1,0]
	v_cvt_pk_bf16_f32 v0, v0, v1
	v_cvt_pk_bf16_f32 v1, v2, v3
	ds_write_b16 v67, v0 offset:5120
	ds_write_b16_d16_hi v70, v0 offset:5120
	ds_write_b16 v71, v1 offset:5120
	ds_write_b16_d16_hi v72, v1 offset:5120
	v_mov_b32_e32 v4, v7
	v_mov_b32_e32 v16, v23
	v_add_co_u32_e32 v18, vcc, s90, v64
	s_waitcnt vmcnt(9)
	v_mov_b64_e32 v[0:1], v[224:225]
	v_pk_mul_f32 v[6:7], v[6:7], v[0:1] op_sel:[0,1] op_sel_hi:[0,0]
	s_waitcnt vmcnt(8)
	v_mov_b64_e32 v[2:3], v[226:227]
	v_pk_mul_f32 v[4:5], v[4:5], v[2:3] op_sel:[0,1] op_sel_hi:[0,0]
	v_pk_fma_f32 v[20:21], v[22:23], v[0:1], v[6:7] neg_lo:[0,0,1] neg_hi:[0,0,1]
	v_pk_fma_f32 v[0:1], v[22:23], v[0:1], v[6:7] op_sel_hi:[0,1,1]
	v_pk_fma_f32 v[6:7], v[16:17], v[2:3], v[4:5] op_sel_hi:[0,1,1] neg_lo:[0,0,1] neg_hi:[0,0,1]
	v_pk_fma_f32 v[2:3], v[16:17], v[2:3], v[4:5] op_sel_hi:[0,1,1]
	v_mov_b32_e32 v21, v1
	v_mov_b32_e32 v7, v3
	v_pk_mul_f32 v[0:1], v[20:21], s[20:21] op_sel_hi:[1,0]
	v_pk_mul_f32 v[2:3], v[6:7], s[20:21] op_sel_hi:[1,0]
	v_cvt_pk_bf16_f32 v0, v0, v1
	v_cvt_pk_bf16_f32 v1, v2, v3
	ds_write_b16 v68, v0 offset:5120
	ds_write_b16_d16_hi v69, v0 offset:5120
	ds_write_b16 v48, v1 offset:5120
	ds_write_b16_d16_hi v49, v1 offset:5120
	v_addc_co_u32_e32 v19, vcc, 0, v65, vcc
	v_mov_b32_e32 v4, v9
	v_mov_b32_e32 v6, v25
	v_add_u32_e32 v20, 40, v66
	v_add_u32_e32 v22, 48, v66
	v_ashrrev_i32_e32 v21, 31, v20
	v_ashrrev_i32_e32 v23, 31, v22
	v_lshlrev_b64 v[38:39], 11, v[20:21]
	v_lshlrev_b64 v[40:41], 11, v[22:23]
	s_waitcnt vmcnt(7)
	v_mov_b64_e32 v[0:1], v[228:229]
	v_pk_mul_f32 v[8:9], v[8:9], v[0:1] op_sel:[0,1] op_sel_hi:[0,0]
	s_waitcnt vmcnt(6)
	v_mov_b64_e32 v[2:3], v[230:231]
	v_pk_mul_f32 v[4:5], v[4:5], v[2:3] op_sel:[0,1] op_sel_hi:[0,0]
	v_pk_fma_f32 v[16:17], v[24:25], v[0:1], v[8:9] neg_lo:[0,0,1] neg_hi:[0,0,1]
	v_pk_fma_f32 v[0:1], v[24:25], v[0:1], v[8:9] op_sel_hi:[0,1,1]
	v_pk_fma_f32 v[8:9], v[6:7], v[2:3], v[4:5] op_sel_hi:[0,1,1] neg_lo:[0,0,1] neg_hi:[0,0,1]
	v_pk_fma_f32 v[2:3], v[6:7], v[2:3], v[4:5] op_sel_hi:[0,1,1]
	v_mov_b32_e32 v17, v1
	v_mov_b32_e32 v9, v3
	v_pk_mul_f32 v[0:1], v[16:17], s[20:21] op_sel_hi:[1,0]
	v_pk_mul_f32 v[2:3], v[8:9], s[20:21] op_sel_hi:[1,0]
	v_cvt_pk_bf16_f32 v0, v0, v1
	v_cvt_pk_bf16_f32 v1, v2, v3
	ds_write_b16 v67, v0 offset:6144
	ds_write_b16_d16_hi v70, v0 offset:6144
	ds_write_b16 v71, v1 offset:6144
	ds_write_b16_d16_hi v72, v1 offset:6144
	v_mov_b32_e32 v4, v11
	v_mov_b32_e32 v6, v27
	v_add_u32_e32 v16, 24, v66
	v_add_u32_e32 v24, 56, v66
	v_ashrrev_i32_e32 v17, 31, v16
	v_ashrrev_i32_e32 v25, 31, v24
	v_lshlrev_b64 v[34:35], 11, v[16:17]
	v_lshlrev_b64 v[42:43], 11, v[24:25]
	s_waitcnt vmcnt(5)
	v_mov_b64_e32 v[0:1], v[232:233]
	v_pk_mul_f32 v[8:9], v[10:11], v[0:1] op_sel:[0,1] op_sel_hi:[0,0]
	s_waitcnt vmcnt(4)
	v_mov_b64_e32 v[2:3], v[234:235]
	v_pk_mul_f32 v[4:5], v[4:5], v[2:3] op_sel:[0,1] op_sel_hi:[0,0]
	v_pk_fma_f32 v[10:11], v[26:27], v[0:1], v[8:9] neg_lo:[0,0,1] neg_hi:[0,0,1]
	v_pk_fma_f32 v[0:1], v[26:27], v[0:1], v[8:9] op_sel_hi:[0,1,1]
	v_pk_fma_f32 v[8:9], v[6:7], v[2:3], v[4:5] op_sel_hi:[0,1,1] neg_lo:[0,0,1] neg_hi:[0,0,1]
	v_pk_fma_f32 v[2:3], v[6:7], v[2:3], v[4:5] op_sel_hi:[0,1,1]
	v_mov_b32_e32 v11, v1
	v_mov_b32_e32 v9, v3
	v_pk_mul_f32 v[0:1], v[10:11], s[20:21] op_sel_hi:[1,0]
	v_pk_mul_f32 v[2:3], v[8:9], s[20:21] op_sel_hi:[1,0]
	v_cvt_pk_bf16_f32 v0, v0, v1
	v_cvt_pk_bf16_f32 v1, v2, v3
	ds_write_b16 v68, v0 offset:6144
	ds_write_b16_d16_hi v69, v0 offset:6144
	ds_write_b16 v48, v1 offset:6144
	ds_write_b16_d16_hi v49, v1 offset:6144
	v_mov_b32_e32 v4, v13
	v_mov_b32_e32 v6, v29
	s_waitcnt vmcnt(3)
	v_mov_b64_e32 v[0:1], v[236:237]
	v_pk_mul_f32 v[8:9], v[12:13], v[0:1] op_sel:[0,1] op_sel_hi:[0,0]
	s_waitcnt vmcnt(2)
	v_mov_b64_e32 v[2:3], v[238:239]
	v_pk_mul_f32 v[4:5], v[4:5], v[2:3] op_sel:[0,1] op_sel_hi:[0,0]
	v_pk_fma_f32 v[10:11], v[28:29], v[0:1], v[8:9] neg_lo:[0,0,1] neg_hi:[0,0,1]
	v_pk_fma_f32 v[0:1], v[28:29], v[0:1], v[8:9] op_sel_hi:[0,1,1]
	v_pk_fma_f32 v[8:9], v[6:7], v[2:3], v[4:5] op_sel_hi:[0,1,1] neg_lo:[0,0,1] neg_hi:[0,0,1]
	v_pk_fma_f32 v[2:3], v[6:7], v[2:3], v[4:5] op_sel_hi:[0,1,1]
	v_mov_b32_e32 v11, v1
	v_mov_b32_e32 v9, v3
	v_pk_mul_f32 v[0:1], v[10:11], s[20:21] op_sel_hi:[1,0]
	v_pk_mul_f32 v[2:3], v[8:9], s[20:21] op_sel_hi:[1,0]
	v_cvt_pk_bf16_f32 v0, v0, v1
	v_cvt_pk_bf16_f32 v1, v2, v3
	ds_write_b16 v67, v0 offset:7168
	ds_write_b16_d16_hi v70, v0 offset:7168
	ds_write_b16 v71, v1 offset:7168
	ds_write_b16_d16_hi v72, v1 offset:7168
	v_lshlrev_b64 v[8:9], 11, v[140:141]
	v_lshl_add_u64 v[8:9], s[10:11], 0, v[8:9]
	v_lshlrev_b32_e32 v5, 4, v98
	v_lshl_add_u64 v[8:9], v[142:143], 1, v[8:9]
	v_xor_b32_e32 v7, v66, v98
	v_and_b32_e32 v128, 0x70, v5
	v_ashrrev_i32_e32 v67, 31, v66
	v_add_u32_e32 v10, 8, v66
	v_add_u32_e32 v12, 16, v66
	v_add_u32_e32 v18, 32, v66
	v_lshlrev_b32_e32 v5, 4, v7
	v_lshl_add_u64 v[8:9], v[8:9], 0, v[128:129]
	v_lshlrev_b64 v[26:27], 11, v[66:67]
	v_ashrrev_i32_e32 v11, 31, v10
	v_ashrrev_i32_e32 v13, 31, v12
	v_ashrrev_i32_e32 v19, 31, v18
	v_and_b32_e32 v5, 0x70, v5
	v_lshl_add_u64 v[32:33], v[8:9], 0, v[26:27]
	v_lshlrev_b64 v[26:27], 11, v[10:11]
	v_lshlrev_b64 v[28:29], 11, v[12:13]
	v_lshlrev_b64 v[36:37], 11, v[18:19]
	v_mov_b32_e32 v4, v15
	v_add_u32_e32 v5, v192, v5
	v_lshl_add_u64 v[44:45], v[8:9], 0, v[26:27]
	v_lshl_add_u64 v[46:47], v[8:9], 0, v[28:29]
	v_lshl_add_u64 v[34:35], v[8:9], 0, v[34:35]
	v_lshl_add_u64 v[36:37], v[8:9], 0, v[36:37]
	v_lshl_add_u64 v[38:39], v[8:9], 0, v[38:39]
	v_lshl_add_u64 v[40:41], v[8:9], 0, v[40:41]
	v_lshl_add_u64 v[42:43], v[8:9], 0, v[42:43]
	v_mov_b32_e32 v6, v31
	v_lshl_add_u32 v7, v66, 7, v5
	v_lshl_add_u32 v13, v10, 7, v5
	v_lshl_add_u32 v12, v12, 7, v5
	v_lshl_add_u32 v16, v16, 7, v5
	v_lshl_add_u32 v17, v18, 7, v5
	v_lshl_add_u32 v20, v20, 7, v5
	v_lshl_add_u32 v25, v22, 7, v5
	v_lshl_add_u32 v28, v24, 7, v5
	s_waitcnt vmcnt(1)
	v_mov_b64_e32 v[0:1], v[240:241]
	v_pk_mul_f32 v[8:9], v[14:15], v[0:1] op_sel:[0,1] op_sel_hi:[0,0]
	s_waitcnt vmcnt(0)
	v_mov_b64_e32 v[2:3], v[244:245]
	v_pk_mul_f32 v[4:5], v[4:5], v[2:3] op_sel:[0,1] op_sel_hi:[0,0]
	v_pk_fma_f32 v[10:11], v[30:31], v[0:1], v[8:9] neg_lo:[0,0,1] neg_hi:[0,0,1]
	v_pk_fma_f32 v[0:1], v[30:31], v[0:1], v[8:9] op_sel_hi:[0,1,1]
	v_pk_fma_f32 v[8:9], v[6:7], v[2:3], v[4:5] op_sel_hi:[0,1,1] neg_lo:[0,0,1] neg_hi:[0,0,1]
	v_pk_fma_f32 v[2:3], v[6:7], v[2:3], v[4:5] op_sel_hi:[0,1,1]
	v_mov_b32_e32 v11, v1
	v_mov_b32_e32 v9, v3
	v_pk_mul_f32 v[0:1], v[10:11], s[20:21] op_sel_hi:[1,0]
	v_pk_mul_f32 v[2:3], v[8:9], s[20:21] op_sel_hi:[1,0]
	v_cvt_pk_bf16_f32 v0, v0, v1
	v_cvt_pk_bf16_f32 v1, v2, v3
	ds_write_b16 v68, v0 offset:7168
	ds_write_b16_d16_hi v69, v0 offset:7168
	ds_write_b16 v48, v1 offset:7168
	ds_write_b16_d16_hi v49, v1 offset:7168
	ds_read_b128 v[0:3], v7
	ds_read_b128 v[4:7], v13
	ds_read_b128 v[8:11], v12
	ds_read_b128 v[12:15], v16
	ds_read_b128 v[16:19], v17
	ds_read_b128 v[20:23], v20
	ds_read_b128 v[24:27], v25
	ds_read_b128 v[28:31], v28
	s_waitcnt lgkmcnt(7)
	global_store_dwordx4 v[32:33], v[0:3], off offset:128
	s_waitcnt lgkmcnt(6)
	global_store_dwordx4 v[44:45], v[4:7], off offset:128
	s_waitcnt lgkmcnt(5)
	global_store_dwordx4 v[46:47], v[8:11], off offset:128
	s_waitcnt lgkmcnt(4)
	global_store_dwordx4 v[34:35], v[12:15], off offset:128
	s_waitcnt lgkmcnt(3)
	global_store_dwordx4 v[36:37], v[16:19], off offset:128
	s_waitcnt lgkmcnt(2)
	global_store_dwordx4 v[38:39], v[20:23], off offset:128
	s_waitcnt lgkmcnt(1)
	global_store_dwordx4 v[40:41], v[24:27], off offset:128
	s_waitcnt lgkmcnt(0)
	global_store_dwordx4 v[42:43], v[28:31], off offset:128
	s_branch .LBB0_159
